# lead-group early raise: priority 2 from the K-loop exit (before the hoisted epilogue loads) on P3/P4/P5/P7, trailing group back to 1 on its align skip path
# speedup vs baseline: 1.0016x; 1.0016x over previous
; #define PG8_STAGE(bufoff, gbase, voff) do { _Pragma("unroll") for (int _i = 0; _i < 2; ++_i) \
;         __builtin_amdgcn_global_load_lds((const __attribute__((address_space(1))) unsigned*)((const char*)(gbase) + (voff)[_i]), (LAS unsigned*)(lds + (bufoff) + ldsw + _i * 8192), 16, 0, 0); } while (0)
; #define PG8_LDA(dst, b, h) do { _Pragma("unroll") for (int m = 0; m < 4; ++m) _Pragma("unroll") for (int k = 0; k < 2; ++k) dst[m][k] = *(const LAS bf16x8*)(lds + PG8_SA(b, h) + aoff + m * 2048 + k * 1024); } while (0)
; #define PG8_LDB(dst, b, h) do { _Pragma("unroll") for (int n = 0; n < 2; ++n) _Pragma("unroll") for (int k = 0; k < 2; ++k) dst[n][k] = *(const LAS bf16x8*)(lds + PG8_SB(b, h) + boff + n * 2048 + k * 1024); } while (0)
; #define PG8_MMA(ai, bj, At, Bt) do { __builtin_amdgcn_s_setprio(1); _Pragma("unroll") for (int m = 0; m < 4; ++m) _Pragma("unroll") for (int n = 0; n < 2; ++n) _Pragma("unroll") for (int k = 0; k < 2; ++k) \
;         acc[ai][bj][m][n] = __builtin_amdgcn_mfma_f32_16x16x32_bf16(Bt[n][k], At[m][k], acc[ai][bj][m][n], 0, 0, 0); __builtin_amdgcn_s_setprio(0); } while (0)
; #define PG8_WAIT_V(n) asm volatile("s_waitcnt vmcnt(" #n ")" ::: "memory")
; #define PG8_WAIT_L(n) asm volatile("s_waitcnt lgkmcnt(" #n ")" ::: "memory")
; #define PG8_BAR __builtin_amdgcn_s_barrier()
; template <class Epi, class SchedT, bool ALIGN_EPI, bool SP2>
; __device__ __forceinline__ void gemm_phase(LAS unsigned char* lds, const int ldk, const int nt, const SchedT& S, const Epi& E) {
;     ...
;             const bool last = (t == nt - 2);
;             const char* a1 = cA + (size_t)(t + 1) * kstep;
;             const char* a2 = last ? nA : cA + (size_t)(t + 2) * kstep; const char* b2 = last ? nB : cB + (size_t)(t + 2) * kstep;
;             const char* a3 = a2 + kstep; const char* b3 = b2 + kstep;
;             if constexpr (SP2) {
;             PG8_LDB(B0, 0, 0); PG8_LDB(B1, 0, 1); PG8_SCHED; PG8_LDA(At, 0, 0); PG8_STAGE(PG8_SA(1, 1), a1 + hstep, voffA);
;             PG8_WAIT_V(8); PG8_WAIT_L(0); PG8_BAR; PG8_MMA(0, 0, At, B0); PG8_MMA(0, 1, At, B1); PG8_BAR; PG8_SCHED;
;             PG8_LDA(At, 0, 1); PG8_STAGE(PG8_SB(0, 0), b2, voffB); PG8_STAGE(PG8_SB(0, 1), b2 + hstepB, voffB); PG8_STAGE(PG8_SA(0, 0), a2, voffA);
;             PG8_WAIT_V(8); PG8_WAIT_L(0); PG8_BAR; PG8_MMA(1, 0, At, B0); PG8_MMA(1, 1, At, B1); PG8_BAR; PG8_SCHED;
.LBB0_534:
	s_add_u32 s36, s34, 0xfff80080
	s_addc_u32 s37, s35, -1
	s_add_i32 s49, 0, 0x10000
	s_cmp_eq_u32 s47, 12
	s_cselect_b32 s41, s1, s37
	s_cselect_b32 s40, s0, s36
	v_add_u32_e32 v0, s49, v159
	s_cselect_b32 s37, s53, s20
	s_cselect_b32 s36, s52, s17
	s_add_i32 s51, 0, 0x14000
	ds_read_b128 v[144:147], v0
	ds_read_b128 v[148:151], v0 offset:1024
	ds_read_b128 v[152:155], v0 offset:2048
	ds_read_b128 v[174:177], v0 offset:3072
	v_add_u32_e32 v0, s51, v159
	ds_read_b128 v[178:181], v0
	ds_read_b128 v[182:185], v0 offset:1024
	ds_read_b128 v[186:189], v0 offset:2048
	ds_read_b128 v[190:193], v0 offset:3072
	v_lshl_add_u64 v[2:3], s[34:35], 0, v[140:141]
	s_add_i32 m0, s57, 0xc000
	ds_read_b128 v[194:197], v161
	ds_read_b128 v[198:201], v161 offset:1024
	ds_read_b128 v[202:205], v161 offset:2048
	ds_read_b128 v[206:209], v161 offset:3072
	ds_read_b128 v[210:213], v161 offset:4096
	ds_read_b128 v[214:217], v161 offset:5120
	ds_read_b128 v[218:221], v161 offset:6144
	ds_read_b128 v[222:225], v161 offset:7168
	global_load_lds_dwordx4 v[2:3], off
	v_lshl_add_u64 v[2:3], s[34:35], 0, v[142:143]
	s_add_i32 m0, s57, 0xe000
	s_nop 0
	global_load_lds_dwordx4 v[2:3], off
	s_waitcnt vmcnt(8)
	s_waitcnt lgkmcnt(0)
	s_barrier
	s_waitcnt lgkmcnt(0)
	v_mfma_f32_16x16x32_bf16 v[128:131], v[144:147], v[194:197], v[128:131]
	v_mfma_f32_16x16x32_bf16 v[124:127], v[152:155], v[194:197], v[124:127]
	v_mfma_f32_16x16x32_bf16 v[120:123], v[144:147], v[202:205], v[120:123]
	v_mfma_f32_16x16x32_bf16 v[116:119], v[152:155], v[202:205], v[116:119]
	v_mfma_f32_16x16x32_bf16 v[112:115], v[144:147], v[210:213], v[112:115]
	v_mfma_f32_16x16x32_bf16 v[108:111], v[152:155], v[210:213], v[108:111]
	v_mfma_f32_16x16x32_bf16 v[104:107], v[144:147], v[218:221], v[104:107]
	v_mfma_f32_16x16x32_bf16 v[100:103], v[152:155], v[218:221], v[100:103]
	v_mfma_f32_16x16x32_bf16 v[128:131], v[148:151], v[198:201], v[128:131]
	v_mfma_f32_16x16x32_bf16 v[124:127], v[174:177], v[198:201], v[124:127]
	v_mfma_f32_16x16x32_bf16 v[120:123], v[148:151], v[206:209], v[120:123]
	v_mfma_f32_16x16x32_bf16 v[116:119], v[174:177], v[206:209], v[116:119]
	v_mfma_f32_16x16x32_bf16 v[112:115], v[148:151], v[214:217], v[112:115]
	v_mfma_f32_16x16x32_bf16 v[108:111], v[174:177], v[214:217], v[108:111]
	v_mfma_f32_16x16x32_bf16 v[104:107], v[148:151], v[222:225], v[104:107]
	v_mfma_f32_16x16x32_bf16 v[100:103], v[174:177], v[222:225], v[100:103]
	v_mfma_f32_16x16x32_bf16 v[96:99], v[178:181], v[194:197], v[96:99]
	v_mfma_f32_16x16x32_bf16 v[92:95], v[186:189], v[194:197], v[92:95]
	v_mfma_f32_16x16x32_bf16 v[88:91], v[178:181], v[202:205], v[88:91]
	v_mfma_f32_16x16x32_bf16 v[84:87], v[186:189], v[202:205], v[84:87]
	v_mfma_f32_16x16x32_bf16 v[80:83], v[178:181], v[210:213], v[80:83]
	v_mfma_f32_16x16x32_bf16 v[76:79], v[186:189], v[210:213], v[76:79]
	v_mfma_f32_16x16x32_bf16 v[72:75], v[178:181], v[218:221], v[72:75]
	v_mfma_f32_16x16x32_bf16 v[68:71], v[186:189], v[218:221], v[68:71]
	v_mfma_f32_16x16x32_bf16 v[96:99], v[182:185], v[198:201], v[96:99]
	v_mfma_f32_16x16x32_bf16 v[92:95], v[190:193], v[198:201], v[92:95]
	v_mfma_f32_16x16x32_bf16 v[88:91], v[182:185], v[206:209], v[88:91]
	v_mfma_f32_16x16x32_bf16 v[84:87], v[190:193], v[206:209], v[84:87]
	v_mfma_f32_16x16x32_bf16 v[80:83], v[182:185], v[214:217], v[80:83]
	v_mfma_f32_16x16x32_bf16 v[76:79], v[190:193], v[214:217], v[76:79]
	v_mfma_f32_16x16x32_bf16 v[72:75], v[182:185], v[222:225], v[72:75]
	v_mfma_f32_16x16x32_bf16 v[68:71], v[190:193], v[222:225], v[68:71]
	s_barrier
	s_add_i32 s49, s49, s56
	v_lshl_add_u64 v[156:157], s[36:37], 0, v[134:135]
	s_mov_b32 m0, s49
	ds_read_b128 v[194:197], v161 offset:16384
	ds_read_b128 v[198:201], v161 offset:17408
	ds_read_b128 v[202:205], v161 offset:18432
	ds_read_b128 v[206:209], v161 offset:19456
	ds_read_b128 v[210:213], v161 offset:20480
	ds_read_b128 v[214:217], v161 offset:21504
	ds_read_b128 v[218:221], v161 offset:22528
	ds_read_b128 v[222:225], v161 offset:23552
	global_load_lds_dwordx4 v[156:157], off
	s_add_i32 m0, s49, 0x2000
	s_add_u32 s82, s36, 0x20000
	v_lshl_add_u64 v[226:227], s[36:37], 0, v[138:139]
	s_addc_u32 s83, s37, 0
	s_add_i32 s49, s51, s56
	global_load_lds_dwordx4 v[226:227], off
	v_lshl_add_u64 v[2:3], s[82:83], 0, v[134:135]
	s_mov_b32 m0, s49
	v_lshl_add_u64 v[228:229], s[40:41], 0, v[132:133]
	global_load_lds_dwordx4 v[2:3], off
	v_lshl_add_u64 v[2:3], s[82:83], 0, v[138:139]
	s_add_i32 m0, s49, 0x2000
	v_lshl_add_u64 v[230:231], s[40:41], 0, v[136:137]
	global_load_lds_dwordx4 v[2:3], off
	s_mov_b32 m0, s57
	s_nop 0
	global_load_lds_dwordx4 v[228:229], off
	s_mov_b32 m0, s58
	s_nop 0
	global_load_lds_dwordx4 v[230:231], off
	s_waitcnt vmcnt(8)
	s_waitcnt lgkmcnt(0)
	s_barrier
; #define PG8_STAGE(bufoff, gbase, voff) do { _Pragma("unroll") for (int _i = 0; _i < 2; ++_i) \
;         __builtin_amdgcn_global_load_lds((const __attribute__((address_space(1))) unsigned*)((const char*)(gbase) + (voff)[_i]), (LAS unsigned*)(lds + (bufoff) + ldsw + _i * 8192), 16, 0, 0); } while (0)
; #define PG8_LDA(dst, b, h) do { _Pragma("unroll") for (int m = 0; m < 4; ++m) _Pragma("unroll") for (int k = 0; k < 2; ++k) dst[m][k] = *(const LAS bf16x8*)(lds + PG8_SA(b, h) + aoff + m * 2048 + k * 1024); } while (0)
; #define PG8_LDB(dst, b, h) do { _Pragma("unroll") for (int n = 0; n < 2; ++n) _Pragma("unroll") for (int k = 0; k < 2; ++k) dst[n][k] = *(const LAS bf16x8*)(lds + PG8_SB(b, h) + boff + n * 2048 + k * 1024); } while (0)
; #define PG8_MMA(ai, bj, At, Bt) do { __builtin_amdgcn_s_setprio(1); _Pragma("unroll") for (int m = 0; m < 4; ++m) _Pragma("unroll") for (int n = 0; n < 2; ++n) _Pragma("unroll") for (int k = 0; k < 2; ++k) \
;         acc[ai][bj][m][n] = __builtin_amdgcn_mfma_f32_16x16x32_bf16(Bt[n][k], At[m][k], acc[ai][bj][m][n], 0, 0, 0); __builtin_amdgcn_s_setprio(0); } while (0)
; #define PG8_WAIT_V(n) asm volatile("s_waitcnt vmcnt(" #n ")" ::: "memory")
; #define PG8_WAIT_L(n) asm volatile("s_waitcnt lgkmcnt(" #n ")" ::: "memory")
; #define PG8_BAR __builtin_amdgcn_s_barrier()
; #define PG8_SCHED __builtin_amdgcn_sched_barrier(0)
; template <class Epi, class SchedT, bool ALIGN_EPI, bool SP2>
; __device__ __forceinline__ void gemm_phase(LAS unsigned char* lds, const int ldk, const int nt, const SchedT& S, const Epi& E) {
;     ...
;             PG8_WAIT_V(8); PG8_WAIT_L(0); PG8_BAR; PG8_MMA(1, 0, At, B0); PG8_MMA(1, 1, At, B1); PG8_BAR; PG8_SCHED;
;             PG8_LDB(B0, 1, 0); PG8_LDB(B1, 1, 1); PG8_SCHED; PG8_LDA(At, 1, 0); PG8_STAGE(PG8_SA(0, 1), a2 + hstep, voffA);
;             PG8_WAIT_V(8); PG8_WAIT_L(0); PG8_BAR; PG8_MMA(0, 0, At, B0); PG8_MMA(0, 1, At, B1); PG8_BAR; PG8_SCHED;
	s_waitcnt lgkmcnt(0)
	v_mfma_f32_16x16x32_bf16 v[64:67], v[144:147], v[194:197], v[64:67]
	v_mfma_f32_16x16x32_bf16 v[60:63], v[152:155], v[194:197], v[60:63]
	v_mfma_f32_16x16x32_bf16 v[56:59], v[144:147], v[202:205], v[56:59]
	v_mfma_f32_16x16x32_bf16 v[52:55], v[152:155], v[202:205], v[52:55]
	v_mfma_f32_16x16x32_bf16 v[48:51], v[144:147], v[210:213], v[48:51]
	v_mfma_f32_16x16x32_bf16 v[44:47], v[152:155], v[210:213], v[44:47]
	v_mfma_f32_16x16x32_bf16 v[40:43], v[144:147], v[218:221], v[40:43]
	v_mfma_f32_16x16x32_bf16 v[36:39], v[152:155], v[218:221], v[36:39]
	v_mfma_f32_16x16x32_bf16 v[64:67], v[148:151], v[198:201], v[64:67]
	v_mfma_f32_16x16x32_bf16 v[60:63], v[174:177], v[198:201], v[60:63]
	v_mfma_f32_16x16x32_bf16 v[56:59], v[148:151], v[206:209], v[56:59]
	v_mfma_f32_16x16x32_bf16 v[52:55], v[174:177], v[206:209], v[52:55]
	v_mfma_f32_16x16x32_bf16 v[48:51], v[148:151], v[214:217], v[48:51]
	v_mfma_f32_16x16x32_bf16 v[44:47], v[174:177], v[214:217], v[44:47]
	v_mfma_f32_16x16x32_bf16 v[40:43], v[148:151], v[222:225], v[40:43]
	v_mfma_f32_16x16x32_bf16 v[36:39], v[174:177], v[222:225], v[36:39]
	v_mfma_f32_16x16x32_bf16 v[32:35], v[178:181], v[194:197], v[32:35]
	v_mfma_f32_16x16x32_bf16 v[28:31], v[186:189], v[194:197], v[28:31]
	v_mfma_f32_16x16x32_bf16 v[24:27], v[178:181], v[202:205], v[24:27]
	v_mfma_f32_16x16x32_bf16 v[20:23], v[186:189], v[202:205], v[20:23]
	v_mfma_f32_16x16x32_bf16 v[16:19], v[178:181], v[210:213], v[16:19]
	v_mfma_f32_16x16x32_bf16 v[12:15], v[186:189], v[210:213], v[12:15]
	v_mfma_f32_16x16x32_bf16 v[8:11], v[178:181], v[218:221], v[8:11]
	v_mfma_f32_16x16x32_bf16 v[2:5], v[186:189], v[218:221], v[4:7]
	v_mfma_f32_16x16x32_bf16 v[32:35], v[182:185], v[198:201], v[32:35]
	v_mfma_f32_16x16x32_bf16 v[28:31], v[190:193], v[198:201], v[28:31]
	v_mfma_f32_16x16x32_bf16 v[24:27], v[182:185], v[206:209], v[24:27]
	v_mfma_f32_16x16x32_bf16 v[20:23], v[190:193], v[206:209], v[20:23]
	v_mfma_f32_16x16x32_bf16 v[16:19], v[182:185], v[214:217], v[16:19]
	v_mfma_f32_16x16x32_bf16 v[12:15], v[190:193], v[214:217], v[12:15]
	v_mfma_f32_16x16x32_bf16 v[8:11], v[182:185], v[222:225], v[8:11]
	v_mfma_f32_16x16x32_bf16 v[2:5], v[190:193], v[222:225], v[2:5]
	s_barrier
	s_add_i32 s49, 0, 0x18000
	v_add_u32_e32 v0, s49, v159
	s_add_i32 s51, 0, 0x1c000
	ds_read_b128 v[144:147], v0
	ds_read_b128 v[148:151], v0 offset:1024
	ds_read_b128 v[152:155], v0 offset:2048
	ds_read_b128 v[174:177], v0 offset:3072
	v_add_u32_e32 v0, s51, v159
	ds_read_b128 v[178:181], v0
	ds_read_b128 v[182:185], v0 offset:1024
	ds_read_b128 v[186:189], v0 offset:2048
	ds_read_b128 v[190:193], v0 offset:3072
	s_add_u32 s40, s40, 0x80000
	s_addc_u32 s41, s41, 0
	s_mov_b32 m0, s59
	v_lshl_add_u64 v[6:7], s[40:41], 0, v[132:133]
	ds_read_b128 v[194:197], v161 offset:32768
	ds_read_b128 v[198:201], v161 offset:33792
	ds_read_b128 v[202:205], v161 offset:34816
	ds_read_b128 v[206:209], v161 offset:35840
	ds_read_b128 v[210:213], v161 offset:36864
	ds_read_b128 v[214:217], v161 offset:37888
	ds_read_b128 v[218:221], v161 offset:38912
	ds_read_b128 v[222:225], v161 offset:39936
	global_load_lds_dwordx4 v[6:7], off
	v_lshl_add_u64 v[6:7], s[40:41], 0, v[136:137]
	s_mov_b32 m0, s60
	s_nop 0
	global_load_lds_dwordx4 v[6:7], off
	s_waitcnt vmcnt(8)
	s_waitcnt lgkmcnt(0)
	s_barrier
	s_waitcnt lgkmcnt(0)
	v_mfma_f32_16x16x32_bf16 v[128:131], v[144:147], v[194:197], v[128:131]
	v_mfma_f32_16x16x32_bf16 v[124:127], v[152:155], v[194:197], v[124:127]
	v_mfma_f32_16x16x32_bf16 v[120:123], v[144:147], v[202:205], v[120:123]
	v_mfma_f32_16x16x32_bf16 v[116:119], v[152:155], v[202:205], v[116:119]
	v_mfma_f32_16x16x32_bf16 v[112:115], v[144:147], v[210:213], v[112:115]
	v_mfma_f32_16x16x32_bf16 v[108:111], v[152:155], v[210:213], v[108:111]
	v_mfma_f32_16x16x32_bf16 v[104:107], v[144:147], v[218:221], v[104:107]
	v_mfma_f32_16x16x32_bf16 v[100:103], v[152:155], v[218:221], v[100:103]
	v_mfma_f32_16x16x32_bf16 v[128:131], v[148:151], v[198:201], v[128:131]
	v_mfma_f32_16x16x32_bf16 v[124:127], v[174:177], v[198:201], v[124:127]
	v_mfma_f32_16x16x32_bf16 v[120:123], v[148:151], v[206:209], v[120:123]
	v_mfma_f32_16x16x32_bf16 v[116:119], v[174:177], v[206:209], v[116:119]
	v_mfma_f32_16x16x32_bf16 v[112:115], v[148:151], v[214:217], v[112:115]
	v_mfma_f32_16x16x32_bf16 v[108:111], v[174:177], v[214:217], v[108:111]
	v_mfma_f32_16x16x32_bf16 v[104:107], v[148:151], v[222:225], v[104:107]
	v_mfma_f32_16x16x32_bf16 v[100:103], v[174:177], v[222:225], v[100:103]
	v_mfma_f32_16x16x32_bf16 v[96:99], v[178:181], v[194:197], v[96:99]
	v_mfma_f32_16x16x32_bf16 v[92:95], v[186:189], v[194:197], v[92:95]
	v_mfma_f32_16x16x32_bf16 v[88:91], v[178:181], v[202:205], v[88:91]
	v_mfma_f32_16x16x32_bf16 v[84:87], v[186:189], v[202:205], v[84:87]
	v_mfma_f32_16x16x32_bf16 v[80:83], v[178:181], v[210:213], v[80:83]
	v_mfma_f32_16x16x32_bf16 v[76:79], v[186:189], v[210:213], v[76:79]
	v_mfma_f32_16x16x32_bf16 v[72:75], v[178:181], v[218:221], v[72:75]
	v_mfma_f32_16x16x32_bf16 v[68:71], v[186:189], v[218:221], v[68:71]
	v_mfma_f32_16x16x32_bf16 v[96:99], v[182:185], v[198:201], v[96:99]
	v_mfma_f32_16x16x32_bf16 v[92:95], v[190:193], v[198:201], v[92:95]
	v_mfma_f32_16x16x32_bf16 v[88:91], v[182:185], v[206:209], v[88:91]
	v_mfma_f32_16x16x32_bf16 v[84:87], v[190:193], v[206:209], v[84:87]
	v_mfma_f32_16x16x32_bf16 v[80:83], v[182:185], v[214:217], v[80:83]
	v_mfma_f32_16x16x32_bf16 v[76:79], v[190:193], v[214:217], v[76:79]
	v_mfma_f32_16x16x32_bf16 v[72:75], v[182:185], v[222:225], v[72:75]
	v_mfma_f32_16x16x32_bf16 v[68:71], v[190:193], v[222:225], v[68:71]
	s_barrier
; #define PG8_STAGE(bufoff, gbase, voff) do { _Pragma("unroll") for (int _i = 0; _i < 2; ++_i) \
;         __builtin_amdgcn_global_load_lds((const __attribute__((address_space(1))) unsigned*)((const char*)(gbase) + (voff)[_i]), (LAS unsigned*)(lds + (bufoff) + ldsw + _i * 8192), 16, 0, 0); } while (0)
; #define PG8_LDA(dst, b, h) do { _Pragma("unroll") for (int m = 0; m < 4; ++m) _Pragma("unroll") for (int k = 0; k < 2; ++k) dst[m][k] = *(const LAS bf16x8*)(lds + PG8_SA(b, h) + aoff + m * 2048 + k * 1024); } while (0)
; #define PG8_MMA(ai, bj, At, Bt) do { __builtin_amdgcn_s_setprio(1); _Pragma("unroll") for (int m = 0; m < 4; ++m) _Pragma("unroll") for (int n = 0; n < 2; ++n) _Pragma("unroll") for (int k = 0; k < 2; ++k) \
;         acc[ai][bj][m][n] = __builtin_amdgcn_mfma_f32_16x16x32_bf16(Bt[n][k], At[m][k], acc[ai][bj][m][n], 0, 0, 0); __builtin_amdgcn_s_setprio(0); } while (0)
; #define PG8_BAR __builtin_amdgcn_s_barrier()
; template <class Epi, class SchedT, bool ALIGN_EPI, bool SP2>
; __device__ __forceinline__ void gemm_phase(LAS unsigned char* lds, const int ldk, const int nt, const SchedT& S, const Epi& E) {
;     ...
;             PG8_WAIT_V(8); PG8_WAIT_L(0); PG8_BAR; PG8_MMA(0, 0, At, B0); PG8_MMA(0, 1, At, B1); PG8_BAR; PG8_SCHED;
;             PG8_LDA(At, 1, 1); PG8_STAGE(PG8_SB(1, 0), b3, voffB); PG8_STAGE(PG8_SB(1, 1), b3 + hstepB, voffB); PG8_STAGE(PG8_SA(1, 0), a3, voffA);
;             PG8_WAIT_V(8); PG8_WAIT_L(0); PG8_BAR; PG8_MMA(1, 0, At, B0); PG8_MMA(1, 1, At, B1); PG8_BAR; PG8_SCHED;
;     __device__ __forceinline__ void operator()(f32x4 (&acc)[2][2][4][2], const Unit& u, int wr, int wc, int fr, int fq) const {
;         const int row0 = u.pm * BM + wr * 64 + fr, col0 = u.pn * BM + wc * 64 + 8 * fq;
; #pragma unroll
;         for (int ai = 0; ai < 2; ++ai)
; #pragma unroll
;             for (int m = 0; m < 4; ++m) {
;                 const int row = row0 + ai * HALF + m * 16;
; #pragma unroll
;                 for (int bj = 0; bj < 2; ++bj) {
;                     const int col = col0 + bj * 32;
;                     const unsigned char* grow = (const unsigned char*)Gt + (size_t)row * 4096 + col;
;                     const u32x2 gw = *(const u32x2*)(grow + 2048);
;                     f32x4 g0 = gate_d4(gw.x), g1 = gate_d4(gw.y);
;                     if (u.kind == 0) {
;                         const u32x2 aw = *(const u32x2*)grow;
	s_add_i32 s40, s49, s56
	v_lshl_add_u64 v[6:7], v[156:157], 0, s[24:25]
	s_mov_b32 m0, s40
	ds_read_b128 v[194:197], v161 offset:49152
	ds_read_b128 v[198:201], v161 offset:50176
	ds_read_b128 v[202:205], v161 offset:51200
	ds_read_b128 v[206:209], v161 offset:52224
	ds_read_b128 v[210:213], v161 offset:53248
	ds_read_b128 v[214:217], v161 offset:54272
	ds_read_b128 v[218:221], v161 offset:55296
	ds_read_b128 v[222:225], v161 offset:56320
	global_load_lds_dwordx4 v[6:7], off
	s_add_i32 m0, s40, 0x2000
	s_add_u32 s36, s36, 0x20080
	v_lshl_add_u64 v[6:7], v[226:227], 0, s[24:25]
	s_addc_u32 s37, s37, 0
	s_add_i32 s40, s51, s56
	global_load_lds_dwordx4 v[6:7], off
	v_lshl_add_u64 v[6:7], s[36:37], 0, v[134:135]
	s_mov_b32 m0, s40
	s_nop 0
	global_load_lds_dwordx4 v[6:7], off
	v_lshl_add_u64 v[6:7], s[36:37], 0, v[138:139]
	s_add_i32 m0, s40, 0x2000
	s_nop 0
	global_load_lds_dwordx4 v[6:7], off
	v_lshl_add_u64 v[6:7], v[228:229], 0, s[24:25]
	s_mov_b32 m0, s61
	s_nop 0
	global_load_lds_dwordx4 v[6:7], off
	v_lshl_add_u64 v[6:7], v[230:231], 0, s[24:25]
	s_mov_b32 m0, s62
	s_nop 0
	global_load_lds_dwordx4 v[6:7], off
	s_waitcnt vmcnt(8)
	s_waitcnt lgkmcnt(0)
	s_barrier
	s_waitcnt lgkmcnt(0)
	v_mfma_f32_16x16x32_bf16 v[64:67], v[144:147], v[194:197], v[64:67]
	v_mfma_f32_16x16x32_bf16 v[60:63], v[152:155], v[194:197], v[60:63]
	v_mfma_f32_16x16x32_bf16 v[56:59], v[144:147], v[202:205], v[56:59]
	v_mfma_f32_16x16x32_bf16 v[52:55], v[152:155], v[202:205], v[52:55]
	v_mfma_f32_16x16x32_bf16 v[48:51], v[144:147], v[210:213], v[48:51]
	v_mfma_f32_16x16x32_bf16 v[44:47], v[152:155], v[210:213], v[44:47]
	v_mfma_f32_16x16x32_bf16 v[40:43], v[144:147], v[218:221], v[40:43]
	v_mfma_f32_16x16x32_bf16 v[36:39], v[152:155], v[218:221], v[36:39]
	v_mfma_f32_16x16x32_bf16 v[64:67], v[148:151], v[198:201], v[64:67]
	v_mfma_f32_16x16x32_bf16 v[60:63], v[174:177], v[198:201], v[60:63]
	v_mfma_f32_16x16x32_bf16 v[56:59], v[148:151], v[206:209], v[56:59]
	v_mfma_f32_16x16x32_bf16 v[52:55], v[174:177], v[206:209], v[52:55]
	v_mfma_f32_16x16x32_bf16 v[48:51], v[148:151], v[214:217], v[48:51]
	v_mfma_f32_16x16x32_bf16 v[44:47], v[174:177], v[214:217], v[44:47]
	v_mfma_f32_16x16x32_bf16 v[40:43], v[148:151], v[222:225], v[40:43]
	v_mfma_f32_16x16x32_bf16 v[36:39], v[174:177], v[222:225], v[36:39]
	v_mfma_f32_16x16x32_bf16 v[32:35], v[178:181], v[194:197], v[32:35]
	v_mfma_f32_16x16x32_bf16 v[28:31], v[186:189], v[194:197], v[28:31]
	v_mfma_f32_16x16x32_bf16 v[24:27], v[178:181], v[202:205], v[24:27]
	v_mfma_f32_16x16x32_bf16 v[20:23], v[186:189], v[202:205], v[20:23]
	v_mfma_f32_16x16x32_bf16 v[16:19], v[178:181], v[210:213], v[16:19]
	v_mfma_f32_16x16x32_bf16 v[12:15], v[186:189], v[210:213], v[12:15]
	v_mfma_f32_16x16x32_bf16 v[6:9], v[178:181], v[218:221], v[8:11]
	v_mfma_f32_16x16x32_bf16 v[2:5], v[186:189], v[218:221], v[2:5]
	v_mfma_f32_16x16x32_bf16 v[32:35], v[182:185], v[198:201], v[32:35]
	v_mfma_f32_16x16x32_bf16 v[28:31], v[190:193], v[198:201], v[28:31]
	v_mfma_f32_16x16x32_bf16 v[24:27], v[182:185], v[206:209], v[24:27]
	v_mfma_f32_16x16x32_bf16 v[20:23], v[190:193], v[206:209], v[20:23]
	v_mfma_f32_16x16x32_bf16 v[16:19], v[182:185], v[214:217], v[16:19]
	v_mfma_f32_16x16x32_bf16 v[12:15], v[190:193], v[214:217], v[12:15]
	v_mfma_f32_16x16x32_bf16 v[8:11], v[182:185], v[222:225], v[6:9]
	v_mfma_f32_16x16x32_bf16 v[4:7], v[190:193], v[222:225], v[2:5]
	s_barrier
	s_add_i32 s47, s47, 2
	s_add_u32 s34, s34, 0x100
	s_addc_u32 s35, s35, 0
	s_add_u32 s17, s17, 0x100
	s_addc_u32 s20, s20, 0
	s_cmp_gt_u32 s47, 13
	s_cbranch_scc0 .LBB0_534
	s_setprio 2
	v_lshl_add_u32 v144, s16, 8, v158
	v_lshl_or_b32 v145, s12, 8, v160
	v_lshl_add_u32 v146, v144, 12, v145
	v_add_u32_e32 v147, 0x10000, v146
	v_add_u32_e32 v148, 0x20000, v146
	v_add_u32_e32 v149, 0x30000, v146
	v_add_u32_e32 v150, 0x80000, v146
	v_add_u32_e32 v151, 0x90000, v146
	v_add_u32_e32 v152, 0xa0000, v146
	v_add_u32_e32 v153, 0xb0000, v146
	s_cmp_lg_u32 s13, 0
	s_cbranch_scc1 .Lp3e_k1_loads
	global_load_dwordx2 v[174:175], v146, s[30:31] offset:2048
	global_load_dwordx2 v[176:177], v146, s[30:31] offset:0
	global_load_dwordx2 v[178:179], v146, s[30:31] offset:2080
	global_load_dwordx2 v[180:181], v146, s[30:31] offset:32
	global_load_dwordx2 v[182:183], v147, s[30:31] offset:2048
	global_load_dwordx2 v[184:185], v147, s[30:31] offset:0
	global_load_dwordx2 v[186:187], v147, s[30:31] offset:2080
	global_load_dwordx2 v[188:189], v147, s[30:31] offset:32
	global_load_dwordx2 v[190:191], v148, s[30:31] offset:2048
	global_load_dwordx2 v[192:193], v148, s[30:31] offset:0
	global_load_dwordx2 v[194:195], v148, s[30:31] offset:2080
	global_load_dwordx2 v[196:197], v148, s[30:31] offset:32
	global_load_dwordx2 v[198:199], v149, s[30:31] offset:2048
	global_load_dwordx2 v[200:201], v149, s[30:31] offset:0
	global_load_dwordx2 v[202:203], v149, s[30:31] offset:2080
	global_load_dwordx2 v[204:205], v149, s[30:31] offset:32
	global_load_dwordx2 v[206:207], v150, s[30:31] offset:2048
	global_load_dwordx2 v[208:209], v150, s[30:31] offset:0
	global_load_dwordx2 v[210:211], v150, s[30:31] offset:2080
	global_load_dwordx2 v[212:213], v150, s[30:31] offset:32
	global_load_dwordx2 v[214:215], v151, s[30:31] offset:2048
	global_load_dwordx2 v[216:217], v151, s[30:31] offset:0
	global_load_dwordx2 v[218:219], v151, s[30:31] offset:2080
	global_load_dwordx2 v[220:221], v151, s[30:31] offset:32
	global_load_dwordx2 v[222:223], v152, s[30:31] offset:2048
	global_load_dwordx2 v[224:225], v152, s[30:31] offset:0
	global_load_dwordx2 v[226:227], v152, s[30:31] offset:2080
	global_load_dwordx2 v[228:229], v152, s[30:31] offset:32
	global_load_dwordx2 v[230:231], v153, s[30:31] offset:2048
	global_load_dwordx2 v[232:233], v153, s[30:31] offset:0
	global_load_dwordx2 v[234:235], v153, s[30:31] offset:2080
	global_load_dwordx2 v[236:237], v153, s[30:31] offset:32
	s_branch .Lp3e_align

; __device__ __forceinline__ float fast_rcp(float x) { return __builtin_amdgcn_rcpf(x); }
; #define PG8_BAR __builtin_amdgcn_s_barrier()
; template <class Epi, class SchedT, bool ALIGN_EPI, bool SP2>
; __device__ __forceinline__ void gemm_phase(LAS unsigned char* lds, const int ldk, const int nt, const SchedT& S, const Epi& E) {
;     ...
;         if constexpr (ALIGN_EPI) { if (wr == 0) PG8_BAR; }
;     __device__ __forceinline__ void operator()(f32x4 (&acc)[2][2][4][2], const Unit& u, int wr, int wc, int fr, int fq) const {
;     ...
;                     const unsigned char* grow = (const unsigned char*)Gt + (size_t)row * 4096 + col;
;                     const u32x2 gw = *(const u32x2*)(grow + 2048);
;                     f32x4 g0 = gate_d4(gw.x), g1 = gate_d4(gw.y);
;                     if (u.kind == 0) {
;                         const u32x2 aw = *(const u32x2*)grow;
;                         const f32x4 a0 = gate_d4(aw.x), a1 = gate_d4(aw.y);
; #pragma unroll
;                         for (int j = 0; j < 4; ++j) { g0[j] = a0[j] * fast_rcp(g0[j]); g1[j] = a1[j] * fast_rcp(g1[j]); }
;                         acc[ai][bj][m][0] *= g0; acc[ai][bj][m][1] *= g1;
.Lp3e_align:
	s_and_b64 vcc, exec, s[44:45]
	s_cbranch_vccnz .Lg0bar_p3
	s_setprio 1
	s_branch .LBB0_537
.Lg0bar_p3:
	s_barrier
.LBB0_537:
	s_cmp_lg_u32 s13, 0
	s_cbranch_scc1 .Lp3e_k1
	s_waitcnt vmcnt(30)
	v_cvt_f32_ubyte0_e32 v246, v174
	v_cvt_f32_ubyte1_e32 v247, v174
	v_cvt_f32_ubyte2_e32 v248, v174
	v_cvt_f32_ubyte3_e32 v249, v174
	v_cvt_f32_ubyte0_e32 v250, v175
	v_cvt_f32_ubyte1_e32 v251, v175
	v_cvt_f32_ubyte2_e32 v252, v175
	v_cvt_f32_ubyte3_e32 v253, v175
	v_max_f32_e32 v246, 0.5, v246
	v_max_f32_e32 v247, 0.5, v247
	v_max_f32_e32 v248, 0.5, v248
	v_max_f32_e32 v249, 0.5, v249
	v_max_f32_e32 v250, 0.5, v250
	v_max_f32_e32 v251, 0.5, v251
	v_max_f32_e32 v252, 0.5, v252
	v_max_f32_e32 v253, 0.5, v253
	v_rcp_f32_e32 v246, v246
	v_rcp_f32_e32 v247, v247
	v_rcp_f32_e32 v248, v248
	v_rcp_f32_e32 v249, v249
	v_rcp_f32_e32 v250, v250
	v_rcp_f32_e32 v251, v251
	v_rcp_f32_e32 v252, v252
	v_rcp_f32_e32 v253, v253
	v_cvt_f32_ubyte0_e32 v238, v176
	v_cvt_f32_ubyte1_e32 v239, v176
	v_cvt_f32_ubyte2_e32 v154, v176
	v_cvt_f32_ubyte3_e32 v155, v176
	v_cvt_f32_ubyte0_e32 v156, v177
	v_cvt_f32_ubyte1_e32 v157, v177
	v_cvt_f32_ubyte2_e32 v2, v177
	v_cvt_f32_ubyte3_e32 v3, v177
	v_max_f32_e32 v238, 0.5, v238
	v_max_f32_e32 v239, 0.5, v239
	v_max_f32_e32 v154, 0.5, v154
	v_max_f32_e32 v155, 0.5, v155
	v_max_f32_e32 v156, 0.5, v156
	v_max_f32_e32 v157, 0.5, v157
	v_max_f32_e32 v2, 0.5, v2
	v_max_f32_e32 v3, 0.5, v3
	v_pk_mul_f32 v[246:247], v[238:239], v[246:247]
	v_pk_mul_f32 v[248:249], v[154:155], v[248:249]
	v_pk_mul_f32 v[250:251], v[156:157], v[250:251]
	v_pk_mul_f32 v[252:253], v[2:3], v[252:253]
	v_pk_mul_f32 v[128:129], v[128:129], v[246:247]
	v_pk_mul_f32 v[130:131], v[130:131], v[248:249]
	v_pk_mul_f32 v[124:125], v[124:125], v[250:251]
	v_pk_mul_f32 v[126:127], v[126:127], v[252:253]
	s_waitcnt vmcnt(28)
	v_cvt_f32_ubyte0_e32 v246, v178
	v_cvt_f32_ubyte1_e32 v247, v178
	v_cvt_f32_ubyte2_e32 v248, v178
	v_cvt_f32_ubyte3_e32 v249, v178
	v_cvt_f32_ubyte0_e32 v250, v179
	v_cvt_f32_ubyte1_e32 v251, v179
	v_cvt_f32_ubyte2_e32 v252, v179
	v_cvt_f32_ubyte3_e32 v253, v179
	v_max_f32_e32 v246, 0.5, v246
	v_max_f32_e32 v247, 0.5, v247
	v_max_f32_e32 v248, 0.5, v248
	v_max_f32_e32 v249, 0.5, v249
	v_max_f32_e32 v250, 0.5, v250
	v_max_f32_e32 v251, 0.5, v251
	v_max_f32_e32 v252, 0.5, v252
	v_max_f32_e32 v253, 0.5, v253
	v_rcp_f32_e32 v246, v246
	v_rcp_f32_e32 v247, v247
	v_rcp_f32_e32 v248, v248
	v_rcp_f32_e32 v249, v249
	v_rcp_f32_e32 v250, v250
	v_rcp_f32_e32 v251, v251
	v_rcp_f32_e32 v252, v252
	v_rcp_f32_e32 v253, v253
	v_cvt_f32_ubyte0_e32 v238, v180
	v_cvt_f32_ubyte1_e32 v239, v180
	v_cvt_f32_ubyte2_e32 v154, v180
	v_cvt_f32_ubyte3_e32 v155, v180
	v_cvt_f32_ubyte0_e32 v156, v181
	v_cvt_f32_ubyte1_e32 v157, v181
	v_cvt_f32_ubyte2_e32 v2, v181
	v_cvt_f32_ubyte3_e32 v3, v181
	v_max_f32_e32 v238, 0.5, v238
	v_max_f32_e32 v239, 0.5, v239
	v_max_f32_e32 v154, 0.5, v154
	v_max_f32_e32 v155, 0.5, v155
	v_max_f32_e32 v156, 0.5, v156
	v_max_f32_e32 v157, 0.5, v157
	v_max_f32_e32 v2, 0.5, v2
	v_max_f32_e32 v3, 0.5, v3
	v_pk_mul_f32 v[246:247], v[238:239], v[246:247]
	v_pk_mul_f32 v[248:249], v[154:155], v[248:249]
	v_pk_mul_f32 v[250:251], v[156:157], v[250:251]
	v_pk_mul_f32 v[252:253], v[2:3], v[252:253]
	v_pk_mul_f32 v[96:97], v[96:97], v[246:247]
	v_pk_mul_f32 v[98:99], v[98:99], v[248:249]
	v_pk_mul_f32 v[92:93], v[92:93], v[250:251]
	v_pk_mul_f32 v[94:95], v[94:95], v[252:253]
	s_waitcnt vmcnt(26)
	v_cvt_f32_ubyte0_e32 v246, v182
	v_cvt_f32_ubyte1_e32 v247, v182
	v_cvt_f32_ubyte2_e32 v248, v182
	v_cvt_f32_ubyte3_e32 v249, v182
	v_cvt_f32_ubyte0_e32 v250, v183
	v_cvt_f32_ubyte1_e32 v251, v183
	v_cvt_f32_ubyte2_e32 v252, v183
	v_cvt_f32_ubyte3_e32 v253, v183
	v_max_f32_e32 v246, 0.5, v246
	v_max_f32_e32 v247, 0.5, v247
	v_max_f32_e32 v248, 0.5, v248
	v_max_f32_e32 v249, 0.5, v249
	v_max_f32_e32 v250, 0.5, v250
	v_max_f32_e32 v251, 0.5, v251
	v_max_f32_e32 v252, 0.5, v252
	v_max_f32_e32 v253, 0.5, v253
	v_rcp_f32_e32 v246, v246
	v_rcp_f32_e32 v247, v247
	v_rcp_f32_e32 v248, v248
	v_rcp_f32_e32 v249, v249
	v_rcp_f32_e32 v250, v250
	v_rcp_f32_e32 v251, v251
	v_rcp_f32_e32 v252, v252
	v_rcp_f32_e32 v253, v253
	v_cvt_f32_ubyte0_e32 v238, v184
	v_cvt_f32_ubyte1_e32 v239, v184
	v_cvt_f32_ubyte2_e32 v154, v184
	v_cvt_f32_ubyte3_e32 v155, v184
	v_cvt_f32_ubyte0_e32 v156, v185
	v_cvt_f32_ubyte1_e32 v157, v185
	v_cvt_f32_ubyte2_e32 v2, v185
	v_cvt_f32_ubyte3_e32 v3, v185
	v_max_f32_e32 v238, 0.5, v238
	v_max_f32_e32 v239, 0.5, v239
	v_max_f32_e32 v154, 0.5, v154
	v_max_f32_e32 v155, 0.5, v155
	v_max_f32_e32 v156, 0.5, v156
	v_max_f32_e32 v157, 0.5, v157
	v_max_f32_e32 v2, 0.5, v2
	v_max_f32_e32 v3, 0.5, v3
	v_pk_mul_f32 v[246:247], v[238:239], v[246:247]
	v_pk_mul_f32 v[248:249], v[154:155], v[248:249]
	v_pk_mul_f32 v[250:251], v[156:157], v[250:251]
	v_pk_mul_f32 v[252:253], v[2:3], v[252:253]
	v_pk_mul_f32 v[120:121], v[120:121], v[246:247]
	v_pk_mul_f32 v[122:123], v[122:123], v[248:249]
	v_pk_mul_f32 v[116:117], v[116:117], v[250:251]
	v_pk_mul_f32 v[118:119], v[118:119], v[252:253]
	s_waitcnt vmcnt(24)
; __device__ __forceinline__ float fast_rcp(float x) { return __builtin_amdgcn_rcpf(x); }
;     __device__ __forceinline__ void operator()(f32x4 (&acc)[2][2][4][2], const Unit& u, int wr, int wc, int fr, int fq) const {
;     ...
;                     const u32x2 gw = *(const u32x2*)(grow + 2048);
;                     f32x4 g0 = gate_d4(gw.x), g1 = gate_d4(gw.y);
;                     if (u.kind == 0) {
;                         const u32x2 aw = *(const u32x2*)grow;
;                         const f32x4 a0 = gate_d4(aw.x), a1 = gate_d4(aw.y);
; #pragma unroll
;                         for (int j = 0; j < 4; ++j) { g0[j] = a0[j] * fast_rcp(g0[j]); g1[j] = a1[j] * fast_rcp(g1[j]); }
;                         acc[ai][bj][m][0] *= g0; acc[ai][bj][m][1] *= g1;
	v_cvt_f32_ubyte0_e32 v246, v186
	v_cvt_f32_ubyte1_e32 v247, v186
	v_cvt_f32_ubyte2_e32 v248, v186
	v_cvt_f32_ubyte3_e32 v249, v186
	v_cvt_f32_ubyte0_e32 v250, v187
	v_cvt_f32_ubyte1_e32 v251, v187
	v_cvt_f32_ubyte2_e32 v252, v187
	v_cvt_f32_ubyte3_e32 v253, v187
	v_max_f32_e32 v246, 0.5, v246
	v_max_f32_e32 v247, 0.5, v247
	v_max_f32_e32 v248, 0.5, v248
	v_max_f32_e32 v249, 0.5, v249
	v_max_f32_e32 v250, 0.5, v250
	v_max_f32_e32 v251, 0.5, v251
	v_max_f32_e32 v252, 0.5, v252
	v_max_f32_e32 v253, 0.5, v253
	v_rcp_f32_e32 v246, v246
	v_rcp_f32_e32 v247, v247
	v_rcp_f32_e32 v248, v248
	v_rcp_f32_e32 v249, v249
	v_rcp_f32_e32 v250, v250
	v_rcp_f32_e32 v251, v251
	v_rcp_f32_e32 v252, v252
	v_rcp_f32_e32 v253, v253
	v_cvt_f32_ubyte0_e32 v238, v188
	v_cvt_f32_ubyte1_e32 v239, v188
	v_cvt_f32_ubyte2_e32 v154, v188
	v_cvt_f32_ubyte3_e32 v155, v188
	v_cvt_f32_ubyte0_e32 v156, v189
	v_cvt_f32_ubyte1_e32 v157, v189
	v_cvt_f32_ubyte2_e32 v2, v189
	v_cvt_f32_ubyte3_e32 v3, v189
	v_max_f32_e32 v238, 0.5, v238
	v_max_f32_e32 v239, 0.5, v239
	v_max_f32_e32 v154, 0.5, v154
	v_max_f32_e32 v155, 0.5, v155
	v_max_f32_e32 v156, 0.5, v156
	v_max_f32_e32 v157, 0.5, v157
	v_max_f32_e32 v2, 0.5, v2
	v_max_f32_e32 v3, 0.5, v3
	v_pk_mul_f32 v[246:247], v[238:239], v[246:247]
	v_pk_mul_f32 v[248:249], v[154:155], v[248:249]
	v_pk_mul_f32 v[250:251], v[156:157], v[250:251]
	v_pk_mul_f32 v[252:253], v[2:3], v[252:253]
	v_pk_mul_f32 v[88:89], v[88:89], v[246:247]
	v_pk_mul_f32 v[90:91], v[90:91], v[248:249]
	v_pk_mul_f32 v[84:85], v[84:85], v[250:251]
	v_pk_mul_f32 v[86:87], v[86:87], v[252:253]
	s_waitcnt vmcnt(22)
	v_cvt_f32_ubyte0_e32 v246, v190
	v_cvt_f32_ubyte1_e32 v247, v190
	v_cvt_f32_ubyte2_e32 v248, v190
	v_cvt_f32_ubyte3_e32 v249, v190
	v_cvt_f32_ubyte0_e32 v250, v191
	v_cvt_f32_ubyte1_e32 v251, v191
	v_cvt_f32_ubyte2_e32 v252, v191
	v_cvt_f32_ubyte3_e32 v253, v191
	v_max_f32_e32 v246, 0.5, v246
	v_max_f32_e32 v247, 0.5, v247
	v_max_f32_e32 v248, 0.5, v248
	v_max_f32_e32 v249, 0.5, v249
	v_max_f32_e32 v250, 0.5, v250
	v_max_f32_e32 v251, 0.5, v251
	v_max_f32_e32 v252, 0.5, v252
	v_max_f32_e32 v253, 0.5, v253
	v_rcp_f32_e32 v246, v246
	v_rcp_f32_e32 v247, v247
	v_rcp_f32_e32 v248, v248
	v_rcp_f32_e32 v249, v249
	v_rcp_f32_e32 v250, v250
	v_rcp_f32_e32 v251, v251
	v_rcp_f32_e32 v252, v252
	v_rcp_f32_e32 v253, v253
	v_cvt_f32_ubyte0_e32 v238, v192
	v_cvt_f32_ubyte1_e32 v239, v192
	v_cvt_f32_ubyte2_e32 v154, v192
	v_cvt_f32_ubyte3_e32 v155, v192
	v_cvt_f32_ubyte0_e32 v156, v193
	v_cvt_f32_ubyte1_e32 v157, v193
	v_cvt_f32_ubyte2_e32 v2, v193
	v_cvt_f32_ubyte3_e32 v3, v193
	v_max_f32_e32 v238, 0.5, v238
	v_max_f32_e32 v239, 0.5, v239
	v_max_f32_e32 v154, 0.5, v154
	v_max_f32_e32 v155, 0.5, v155
	v_max_f32_e32 v156, 0.5, v156
	v_max_f32_e32 v157, 0.5, v157
	v_max_f32_e32 v2, 0.5, v2
	v_max_f32_e32 v3, 0.5, v3
	v_pk_mul_f32 v[246:247], v[238:239], v[246:247]
	v_pk_mul_f32 v[248:249], v[154:155], v[248:249]
	v_pk_mul_f32 v[250:251], v[156:157], v[250:251]
	v_pk_mul_f32 v[252:253], v[2:3], v[252:253]
	v_pk_mul_f32 v[112:113], v[112:113], v[246:247]
	v_pk_mul_f32 v[114:115], v[114:115], v[248:249]
	v_pk_mul_f32 v[108:109], v[108:109], v[250:251]
	v_pk_mul_f32 v[110:111], v[110:111], v[252:253]
	s_waitcnt vmcnt(20)
	v_cvt_f32_ubyte0_e32 v246, v194
	v_cvt_f32_ubyte1_e32 v247, v194
	v_cvt_f32_ubyte2_e32 v248, v194
	v_cvt_f32_ubyte3_e32 v249, v194
	v_cvt_f32_ubyte0_e32 v250, v195
	v_cvt_f32_ubyte1_e32 v251, v195
	v_cvt_f32_ubyte2_e32 v252, v195
	v_cvt_f32_ubyte3_e32 v253, v195
	v_max_f32_e32 v246, 0.5, v246
	v_max_f32_e32 v247, 0.5, v247
	v_max_f32_e32 v248, 0.5, v248
	v_max_f32_e32 v249, 0.5, v249
	v_max_f32_e32 v250, 0.5, v250
	v_max_f32_e32 v251, 0.5, v251
	v_max_f32_e32 v252, 0.5, v252
	v_max_f32_e32 v253, 0.5, v253
	v_rcp_f32_e32 v246, v246
	v_rcp_f32_e32 v247, v247
	v_rcp_f32_e32 v248, v248
	v_rcp_f32_e32 v249, v249
	v_rcp_f32_e32 v250, v250
	v_rcp_f32_e32 v251, v251
	v_rcp_f32_e32 v252, v252
	v_rcp_f32_e32 v253, v253
	v_cvt_f32_ubyte0_e32 v238, v196
	v_cvt_f32_ubyte1_e32 v239, v196
	v_cvt_f32_ubyte2_e32 v154, v196
	v_cvt_f32_ubyte3_e32 v155, v196
	v_cvt_f32_ubyte0_e32 v156, v197
	v_cvt_f32_ubyte1_e32 v157, v197
	v_cvt_f32_ubyte2_e32 v2, v197
	v_cvt_f32_ubyte3_e32 v3, v197
	v_max_f32_e32 v238, 0.5, v238
	v_max_f32_e32 v239, 0.5, v239
	v_max_f32_e32 v154, 0.5, v154
	v_max_f32_e32 v155, 0.5, v155
	v_max_f32_e32 v156, 0.5, v156
	v_max_f32_e32 v157, 0.5, v157
	v_max_f32_e32 v2, 0.5, v2
	v_max_f32_e32 v3, 0.5, v3
	v_pk_mul_f32 v[246:247], v[238:239], v[246:247]
	v_pk_mul_f32 v[248:249], v[154:155], v[248:249]
	v_pk_mul_f32 v[250:251], v[156:157], v[250:251]
	v_pk_mul_f32 v[252:253], v[2:3], v[252:253]
	v_pk_mul_f32 v[80:81], v[80:81], v[246:247]
	v_pk_mul_f32 v[82:83], v[82:83], v[248:249]
	v_pk_mul_f32 v[76:77], v[76:77], v[250:251]
	v_pk_mul_f32 v[78:79], v[78:79], v[252:253]
	s_waitcnt vmcnt(18)
; __device__ __forceinline__ float fast_rcp(float x) { return __builtin_amdgcn_rcpf(x); }
;     __device__ __forceinline__ void operator()(f32x4 (&acc)[2][2][4][2], const Unit& u, int wr, int wc, int fr, int fq) const {
;     ...
;                     const u32x2 gw = *(const u32x2*)(grow + 2048);
;                     f32x4 g0 = gate_d4(gw.x), g1 = gate_d4(gw.y);
;                     if (u.kind == 0) {
;                         const u32x2 aw = *(const u32x2*)grow;
;                         const f32x4 a0 = gate_d4(aw.x), a1 = gate_d4(aw.y);
; #pragma unroll
;                         for (int j = 0; j < 4; ++j) { g0[j] = a0[j] * fast_rcp(g0[j]); g1[j] = a1[j] * fast_rcp(g1[j]); }
;                         acc[ai][bj][m][0] *= g0; acc[ai][bj][m][1] *= g1;
	v_cvt_f32_ubyte0_e32 v246, v198
	v_cvt_f32_ubyte1_e32 v247, v198
	v_cvt_f32_ubyte2_e32 v248, v198
	v_cvt_f32_ubyte3_e32 v249, v198
	v_cvt_f32_ubyte0_e32 v250, v199
	v_cvt_f32_ubyte1_e32 v251, v199
	v_cvt_f32_ubyte2_e32 v252, v199
	v_cvt_f32_ubyte3_e32 v253, v199
	v_max_f32_e32 v246, 0.5, v246
	v_max_f32_e32 v247, 0.5, v247
	v_max_f32_e32 v248, 0.5, v248
	v_max_f32_e32 v249, 0.5, v249
	v_max_f32_e32 v250, 0.5, v250
	v_max_f32_e32 v251, 0.5, v251
	v_max_f32_e32 v252, 0.5, v252
	v_max_f32_e32 v253, 0.5, v253
	v_rcp_f32_e32 v246, v246
	v_rcp_f32_e32 v247, v247
	v_rcp_f32_e32 v248, v248
	v_rcp_f32_e32 v249, v249
	v_rcp_f32_e32 v250, v250
	v_rcp_f32_e32 v251, v251
	v_rcp_f32_e32 v252, v252
	v_rcp_f32_e32 v253, v253
	v_cvt_f32_ubyte0_e32 v238, v200
	v_cvt_f32_ubyte1_e32 v239, v200
	v_cvt_f32_ubyte2_e32 v154, v200
	v_cvt_f32_ubyte3_e32 v155, v200
	v_cvt_f32_ubyte0_e32 v156, v201
	v_cvt_f32_ubyte1_e32 v157, v201
	v_cvt_f32_ubyte2_e32 v2, v201
	v_cvt_f32_ubyte3_e32 v3, v201
	v_max_f32_e32 v238, 0.5, v238
	v_max_f32_e32 v239, 0.5, v239
	v_max_f32_e32 v154, 0.5, v154
	v_max_f32_e32 v155, 0.5, v155
	v_max_f32_e32 v156, 0.5, v156
	v_max_f32_e32 v157, 0.5, v157
	v_max_f32_e32 v2, 0.5, v2
	v_max_f32_e32 v3, 0.5, v3
	v_pk_mul_f32 v[246:247], v[238:239], v[246:247]
	v_pk_mul_f32 v[248:249], v[154:155], v[248:249]
	v_pk_mul_f32 v[250:251], v[156:157], v[250:251]
	v_pk_mul_f32 v[252:253], v[2:3], v[252:253]
	v_pk_mul_f32 v[104:105], v[104:105], v[246:247]
	v_pk_mul_f32 v[106:107], v[106:107], v[248:249]
	v_pk_mul_f32 v[100:101], v[100:101], v[250:251]
	v_pk_mul_f32 v[102:103], v[102:103], v[252:253]
	s_waitcnt vmcnt(16)
	v_cvt_f32_ubyte0_e32 v246, v202
	v_cvt_f32_ubyte1_e32 v247, v202
	v_cvt_f32_ubyte2_e32 v248, v202
	v_cvt_f32_ubyte3_e32 v249, v202
	v_cvt_f32_ubyte0_e32 v250, v203
	v_cvt_f32_ubyte1_e32 v251, v203
	v_cvt_f32_ubyte2_e32 v252, v203
	v_cvt_f32_ubyte3_e32 v253, v203
	v_max_f32_e32 v246, 0.5, v246
	v_max_f32_e32 v247, 0.5, v247
	v_max_f32_e32 v248, 0.5, v248
	v_max_f32_e32 v249, 0.5, v249
	v_max_f32_e32 v250, 0.5, v250
	v_max_f32_e32 v251, 0.5, v251
	v_max_f32_e32 v252, 0.5, v252
	v_max_f32_e32 v253, 0.5, v253
	v_rcp_f32_e32 v246, v246
	v_rcp_f32_e32 v247, v247
	v_rcp_f32_e32 v248, v248
	v_rcp_f32_e32 v249, v249
	v_rcp_f32_e32 v250, v250
	v_rcp_f32_e32 v251, v251
	v_rcp_f32_e32 v252, v252
	v_rcp_f32_e32 v253, v253
	v_cvt_f32_ubyte0_e32 v238, v204
	v_cvt_f32_ubyte1_e32 v239, v204
	v_cvt_f32_ubyte2_e32 v154, v204
	v_cvt_f32_ubyte3_e32 v155, v204
	v_cvt_f32_ubyte0_e32 v156, v205
	v_cvt_f32_ubyte1_e32 v157, v205
	v_cvt_f32_ubyte2_e32 v2, v205
	v_cvt_f32_ubyte3_e32 v3, v205
	v_max_f32_e32 v238, 0.5, v238
	v_max_f32_e32 v239, 0.5, v239
	v_max_f32_e32 v154, 0.5, v154
	v_max_f32_e32 v155, 0.5, v155
	v_max_f32_e32 v156, 0.5, v156
	v_max_f32_e32 v157, 0.5, v157
	v_max_f32_e32 v2, 0.5, v2
	v_max_f32_e32 v3, 0.5, v3
	v_pk_mul_f32 v[246:247], v[238:239], v[246:247]
	v_pk_mul_f32 v[248:249], v[154:155], v[248:249]
	v_pk_mul_f32 v[250:251], v[156:157], v[250:251]
	v_pk_mul_f32 v[252:253], v[2:3], v[252:253]
	v_pk_mul_f32 v[72:73], v[72:73], v[246:247]
	v_pk_mul_f32 v[74:75], v[74:75], v[248:249]
	v_pk_mul_f32 v[68:69], v[68:69], v[250:251]
	v_pk_mul_f32 v[70:71], v[70:71], v[252:253]
	s_waitcnt vmcnt(14)
	v_cvt_f32_ubyte0_e32 v246, v206
	v_cvt_f32_ubyte1_e32 v247, v206
	v_cvt_f32_ubyte2_e32 v248, v206
	v_cvt_f32_ubyte3_e32 v249, v206
	v_cvt_f32_ubyte0_e32 v250, v207
	v_cvt_f32_ubyte1_e32 v251, v207
	v_cvt_f32_ubyte2_e32 v252, v207
	v_cvt_f32_ubyte3_e32 v253, v207
	v_max_f32_e32 v246, 0.5, v246
	v_max_f32_e32 v247, 0.5, v247
	v_max_f32_e32 v248, 0.5, v248
	v_max_f32_e32 v249, 0.5, v249
	v_max_f32_e32 v250, 0.5, v250
	v_max_f32_e32 v251, 0.5, v251
	v_max_f32_e32 v252, 0.5, v252
	v_max_f32_e32 v253, 0.5, v253
	v_rcp_f32_e32 v246, v246
	v_rcp_f32_e32 v247, v247
	v_rcp_f32_e32 v248, v248
	v_rcp_f32_e32 v249, v249
	v_rcp_f32_e32 v250, v250
	v_rcp_f32_e32 v251, v251
	v_rcp_f32_e32 v252, v252
	v_rcp_f32_e32 v253, v253
	v_cvt_f32_ubyte0_e32 v238, v208
	v_cvt_f32_ubyte1_e32 v239, v208
	v_cvt_f32_ubyte2_e32 v154, v208
	v_cvt_f32_ubyte3_e32 v155, v208
	v_cvt_f32_ubyte0_e32 v156, v209
	v_cvt_f32_ubyte1_e32 v157, v209
	v_cvt_f32_ubyte2_e32 v2, v209
	v_cvt_f32_ubyte3_e32 v3, v209
	v_max_f32_e32 v238, 0.5, v238
	v_max_f32_e32 v239, 0.5, v239
	v_max_f32_e32 v154, 0.5, v154
	v_max_f32_e32 v155, 0.5, v155
	v_max_f32_e32 v156, 0.5, v156
	v_max_f32_e32 v157, 0.5, v157
	v_max_f32_e32 v2, 0.5, v2
	v_max_f32_e32 v3, 0.5, v3
	v_pk_mul_f32 v[246:247], v[238:239], v[246:247]
	v_pk_mul_f32 v[248:249], v[154:155], v[248:249]
	v_pk_mul_f32 v[250:251], v[156:157], v[250:251]
	v_pk_mul_f32 v[252:253], v[2:3], v[252:253]
	v_pk_mul_f32 v[64:65], v[64:65], v[246:247]
	v_pk_mul_f32 v[66:67], v[66:67], v[248:249]
	v_pk_mul_f32 v[60:61], v[60:61], v[250:251]
	v_pk_mul_f32 v[62:63], v[62:63], v[252:253]
	s_waitcnt vmcnt(12)
; __device__ __forceinline__ float fast_rcp(float x) { return __builtin_amdgcn_rcpf(x); }
;     __device__ __forceinline__ void operator()(f32x4 (&acc)[2][2][4][2], const Unit& u, int wr, int wc, int fr, int fq) const {
;     ...
;                     const u32x2 gw = *(const u32x2*)(grow + 2048);
;                     f32x4 g0 = gate_d4(gw.x), g1 = gate_d4(gw.y);
;                     if (u.kind == 0) {
;                         const u32x2 aw = *(const u32x2*)grow;
;                         const f32x4 a0 = gate_d4(aw.x), a1 = gate_d4(aw.y);
; #pragma unroll
;                         for (int j = 0; j < 4; ++j) { g0[j] = a0[j] * fast_rcp(g0[j]); g1[j] = a1[j] * fast_rcp(g1[j]); }
;                         acc[ai][bj][m][0] *= g0; acc[ai][bj][m][1] *= g1;
	v_cvt_f32_ubyte0_e32 v246, v210
	v_cvt_f32_ubyte1_e32 v247, v210
	v_cvt_f32_ubyte2_e32 v248, v210
	v_cvt_f32_ubyte3_e32 v249, v210
	v_cvt_f32_ubyte0_e32 v250, v211
	v_cvt_f32_ubyte1_e32 v251, v211
	v_cvt_f32_ubyte2_e32 v252, v211
	v_cvt_f32_ubyte3_e32 v253, v211
	v_max_f32_e32 v246, 0.5, v246
	v_max_f32_e32 v247, 0.5, v247
	v_max_f32_e32 v248, 0.5, v248
	v_max_f32_e32 v249, 0.5, v249
	v_max_f32_e32 v250, 0.5, v250
	v_max_f32_e32 v251, 0.5, v251
	v_max_f32_e32 v252, 0.5, v252
	v_max_f32_e32 v253, 0.5, v253
	v_rcp_f32_e32 v246, v246
	v_rcp_f32_e32 v247, v247
	v_rcp_f32_e32 v248, v248
	v_rcp_f32_e32 v249, v249
	v_rcp_f32_e32 v250, v250
	v_rcp_f32_e32 v251, v251
	v_rcp_f32_e32 v252, v252
	v_rcp_f32_e32 v253, v253
	v_cvt_f32_ubyte0_e32 v238, v212
	v_cvt_f32_ubyte1_e32 v239, v212
	v_cvt_f32_ubyte2_e32 v154, v212
	v_cvt_f32_ubyte3_e32 v155, v212
	v_cvt_f32_ubyte0_e32 v156, v213
	v_cvt_f32_ubyte1_e32 v157, v213
	v_cvt_f32_ubyte2_e32 v2, v213
	v_cvt_f32_ubyte3_e32 v3, v213
	v_max_f32_e32 v238, 0.5, v238
	v_max_f32_e32 v239, 0.5, v239
	v_max_f32_e32 v154, 0.5, v154
	v_max_f32_e32 v155, 0.5, v155
	v_max_f32_e32 v156, 0.5, v156
	v_max_f32_e32 v157, 0.5, v157
	v_max_f32_e32 v2, 0.5, v2
	v_max_f32_e32 v3, 0.5, v3
	v_pk_mul_f32 v[246:247], v[238:239], v[246:247]
	v_pk_mul_f32 v[248:249], v[154:155], v[248:249]
	v_pk_mul_f32 v[250:251], v[156:157], v[250:251]
	v_pk_mul_f32 v[252:253], v[2:3], v[252:253]
	v_pk_mul_f32 v[32:33], v[32:33], v[246:247]
	v_pk_mul_f32 v[34:35], v[34:35], v[248:249]
	v_pk_mul_f32 v[28:29], v[28:29], v[250:251]
	v_pk_mul_f32 v[30:31], v[30:31], v[252:253]
	s_waitcnt vmcnt(10)
	v_cvt_f32_ubyte0_e32 v246, v214
	v_cvt_f32_ubyte1_e32 v247, v214
	v_cvt_f32_ubyte2_e32 v248, v214
	v_cvt_f32_ubyte3_e32 v249, v214
	v_cvt_f32_ubyte0_e32 v250, v215
	v_cvt_f32_ubyte1_e32 v251, v215
	v_cvt_f32_ubyte2_e32 v252, v215
	v_cvt_f32_ubyte3_e32 v253, v215
	v_max_f32_e32 v246, 0.5, v246
	v_max_f32_e32 v247, 0.5, v247
	v_max_f32_e32 v248, 0.5, v248
	v_max_f32_e32 v249, 0.5, v249
	v_max_f32_e32 v250, 0.5, v250
	v_max_f32_e32 v251, 0.5, v251
	v_max_f32_e32 v252, 0.5, v252
	v_max_f32_e32 v253, 0.5, v253
	v_rcp_f32_e32 v246, v246
	v_rcp_f32_e32 v247, v247
	v_rcp_f32_e32 v248, v248
	v_rcp_f32_e32 v249, v249
	v_rcp_f32_e32 v250, v250
	v_rcp_f32_e32 v251, v251
	v_rcp_f32_e32 v252, v252
	v_rcp_f32_e32 v253, v253
	v_cvt_f32_ubyte0_e32 v238, v216
	v_cvt_f32_ubyte1_e32 v239, v216
	v_cvt_f32_ubyte2_e32 v154, v216
	v_cvt_f32_ubyte3_e32 v155, v216
	v_cvt_f32_ubyte0_e32 v156, v217
	v_cvt_f32_ubyte1_e32 v157, v217
	v_cvt_f32_ubyte2_e32 v2, v217
	v_cvt_f32_ubyte3_e32 v3, v217
	v_max_f32_e32 v238, 0.5, v238
	v_max_f32_e32 v239, 0.5, v239
	v_max_f32_e32 v154, 0.5, v154
	v_max_f32_e32 v155, 0.5, v155
	v_max_f32_e32 v156, 0.5, v156
	v_max_f32_e32 v157, 0.5, v157
	v_max_f32_e32 v2, 0.5, v2
	v_max_f32_e32 v3, 0.5, v3
	v_pk_mul_f32 v[246:247], v[238:239], v[246:247]
	v_pk_mul_f32 v[248:249], v[154:155], v[248:249]
	v_pk_mul_f32 v[250:251], v[156:157], v[250:251]
	v_pk_mul_f32 v[252:253], v[2:3], v[252:253]
	v_pk_mul_f32 v[56:57], v[56:57], v[246:247]
	v_pk_mul_f32 v[58:59], v[58:59], v[248:249]
	v_pk_mul_f32 v[52:53], v[52:53], v[250:251]
	v_pk_mul_f32 v[54:55], v[54:55], v[252:253]
	s_waitcnt vmcnt(8)
	v_cvt_f32_ubyte0_e32 v246, v218
	v_cvt_f32_ubyte1_e32 v247, v218
	v_cvt_f32_ubyte2_e32 v248, v218
	v_cvt_f32_ubyte3_e32 v249, v218
	v_cvt_f32_ubyte0_e32 v250, v219
	v_cvt_f32_ubyte1_e32 v251, v219
	v_cvt_f32_ubyte2_e32 v252, v219
	v_cvt_f32_ubyte3_e32 v253, v219
	v_max_f32_e32 v246, 0.5, v246
	v_max_f32_e32 v247, 0.5, v247
	v_max_f32_e32 v248, 0.5, v248
	v_max_f32_e32 v249, 0.5, v249
	v_max_f32_e32 v250, 0.5, v250
	v_max_f32_e32 v251, 0.5, v251
	v_max_f32_e32 v252, 0.5, v252
	v_max_f32_e32 v253, 0.5, v253
	v_rcp_f32_e32 v246, v246
	v_rcp_f32_e32 v247, v247
	v_rcp_f32_e32 v248, v248
	v_rcp_f32_e32 v249, v249
	v_rcp_f32_e32 v250, v250
	v_rcp_f32_e32 v251, v251
	v_rcp_f32_e32 v252, v252
	v_rcp_f32_e32 v253, v253
	v_cvt_f32_ubyte0_e32 v238, v220
	v_cvt_f32_ubyte1_e32 v239, v220
	v_cvt_f32_ubyte2_e32 v154, v220
	v_cvt_f32_ubyte3_e32 v155, v220
	v_cvt_f32_ubyte0_e32 v156, v221
	v_cvt_f32_ubyte1_e32 v157, v221
	v_cvt_f32_ubyte2_e32 v2, v221
	v_cvt_f32_ubyte3_e32 v3, v221
	v_max_f32_e32 v238, 0.5, v238
	v_max_f32_e32 v239, 0.5, v239
	v_max_f32_e32 v154, 0.5, v154
	v_max_f32_e32 v155, 0.5, v155
	v_max_f32_e32 v156, 0.5, v156
	v_max_f32_e32 v157, 0.5, v157
	v_max_f32_e32 v2, 0.5, v2
	v_max_f32_e32 v3, 0.5, v3
	v_pk_mul_f32 v[246:247], v[238:239], v[246:247]
	v_pk_mul_f32 v[248:249], v[154:155], v[248:249]
	v_pk_mul_f32 v[250:251], v[156:157], v[250:251]
	v_pk_mul_f32 v[252:253], v[2:3], v[252:253]
	v_pk_mul_f32 v[24:25], v[24:25], v[246:247]
	v_pk_mul_f32 v[26:27], v[26:27], v[248:249]
	v_pk_mul_f32 v[20:21], v[20:21], v[250:251]
	v_pk_mul_f32 v[22:23], v[22:23], v[252:253]
	s_waitcnt vmcnt(6)
; __device__ __forceinline__ float fast_rcp(float x) { return __builtin_amdgcn_rcpf(x); }
;     __device__ __forceinline__ void operator()(f32x4 (&acc)[2][2][4][2], const Unit& u, int wr, int wc, int fr, int fq) const {
;     ...
;                     const u32x2 gw = *(const u32x2*)(grow + 2048);
;                     f32x4 g0 = gate_d4(gw.x), g1 = gate_d4(gw.y);
;                     if (u.kind == 0) {
;                         const u32x2 aw = *(const u32x2*)grow;
;                         const f32x4 a0 = gate_d4(aw.x), a1 = gate_d4(aw.y);
; #pragma unroll
;                         for (int j = 0; j < 4; ++j) { g0[j] = a0[j] * fast_rcp(g0[j]); g1[j] = a1[j] * fast_rcp(g1[j]); }
;                         acc[ai][bj][m][0] *= g0; acc[ai][bj][m][1] *= g1;
	v_cvt_f32_ubyte0_e32 v246, v222
	v_cvt_f32_ubyte1_e32 v247, v222
	v_cvt_f32_ubyte2_e32 v248, v222
	v_cvt_f32_ubyte3_e32 v249, v222
	v_cvt_f32_ubyte0_e32 v250, v223
	v_cvt_f32_ubyte1_e32 v251, v223
	v_cvt_f32_ubyte2_e32 v252, v223
	v_cvt_f32_ubyte3_e32 v253, v223
	v_max_f32_e32 v246, 0.5, v246
	v_max_f32_e32 v247, 0.5, v247
	v_max_f32_e32 v248, 0.5, v248
	v_max_f32_e32 v249, 0.5, v249
	v_max_f32_e32 v250, 0.5, v250
	v_max_f32_e32 v251, 0.5, v251
	v_max_f32_e32 v252, 0.5, v252
	v_max_f32_e32 v253, 0.5, v253
	v_rcp_f32_e32 v246, v246
	v_rcp_f32_e32 v247, v247
	v_rcp_f32_e32 v248, v248
	v_rcp_f32_e32 v249, v249
	v_rcp_f32_e32 v250, v250
	v_rcp_f32_e32 v251, v251
	v_rcp_f32_e32 v252, v252
	v_rcp_f32_e32 v253, v253
	v_cvt_f32_ubyte0_e32 v238, v224
	v_cvt_f32_ubyte1_e32 v239, v224
	v_cvt_f32_ubyte2_e32 v154, v224
	v_cvt_f32_ubyte3_e32 v155, v224
	v_cvt_f32_ubyte0_e32 v156, v225
	v_cvt_f32_ubyte1_e32 v157, v225
	v_cvt_f32_ubyte2_e32 v2, v225
	v_cvt_f32_ubyte3_e32 v3, v225
	v_max_f32_e32 v238, 0.5, v238
	v_max_f32_e32 v239, 0.5, v239
	v_max_f32_e32 v154, 0.5, v154
	v_max_f32_e32 v155, 0.5, v155
	v_max_f32_e32 v156, 0.5, v156
	v_max_f32_e32 v157, 0.5, v157
	v_max_f32_e32 v2, 0.5, v2
	v_max_f32_e32 v3, 0.5, v3
	v_pk_mul_f32 v[246:247], v[238:239], v[246:247]
	v_pk_mul_f32 v[248:249], v[154:155], v[248:249]
	v_pk_mul_f32 v[250:251], v[156:157], v[250:251]
	v_pk_mul_f32 v[252:253], v[2:3], v[252:253]
	v_pk_mul_f32 v[48:49], v[48:49], v[246:247]
	v_pk_mul_f32 v[50:51], v[50:51], v[248:249]
	v_pk_mul_f32 v[44:45], v[44:45], v[250:251]
	v_pk_mul_f32 v[46:47], v[46:47], v[252:253]
	s_waitcnt vmcnt(4)
	v_cvt_f32_ubyte0_e32 v246, v226
	v_cvt_f32_ubyte1_e32 v247, v226
	v_cvt_f32_ubyte2_e32 v248, v226
	v_cvt_f32_ubyte3_e32 v249, v226
	v_cvt_f32_ubyte0_e32 v250, v227
	v_cvt_f32_ubyte1_e32 v251, v227
	v_cvt_f32_ubyte2_e32 v252, v227
	v_cvt_f32_ubyte3_e32 v253, v227
	v_max_f32_e32 v246, 0.5, v246
	v_max_f32_e32 v247, 0.5, v247
	v_max_f32_e32 v248, 0.5, v248
	v_max_f32_e32 v249, 0.5, v249
	v_max_f32_e32 v250, 0.5, v250
	v_max_f32_e32 v251, 0.5, v251
	v_max_f32_e32 v252, 0.5, v252
	v_max_f32_e32 v253, 0.5, v253
	v_rcp_f32_e32 v246, v246
	v_rcp_f32_e32 v247, v247
	v_rcp_f32_e32 v248, v248
	v_rcp_f32_e32 v249, v249
	v_rcp_f32_e32 v250, v250
	v_rcp_f32_e32 v251, v251
	v_rcp_f32_e32 v252, v252
	v_rcp_f32_e32 v253, v253
	v_cvt_f32_ubyte0_e32 v238, v228
	v_cvt_f32_ubyte1_e32 v239, v228
	v_cvt_f32_ubyte2_e32 v154, v228
	v_cvt_f32_ubyte3_e32 v155, v228
	v_cvt_f32_ubyte0_e32 v156, v229
	v_cvt_f32_ubyte1_e32 v157, v229
	v_cvt_f32_ubyte2_e32 v2, v229
	v_cvt_f32_ubyte3_e32 v3, v229
	v_max_f32_e32 v238, 0.5, v238
	v_max_f32_e32 v239, 0.5, v239
	v_max_f32_e32 v154, 0.5, v154
	v_max_f32_e32 v155, 0.5, v155
	v_max_f32_e32 v156, 0.5, v156
	v_max_f32_e32 v157, 0.5, v157
	v_max_f32_e32 v2, 0.5, v2
	v_max_f32_e32 v3, 0.5, v3
	v_pk_mul_f32 v[246:247], v[238:239], v[246:247]
	v_pk_mul_f32 v[248:249], v[154:155], v[248:249]
	v_pk_mul_f32 v[250:251], v[156:157], v[250:251]
	v_pk_mul_f32 v[252:253], v[2:3], v[252:253]
	v_pk_mul_f32 v[16:17], v[16:17], v[246:247]
	v_pk_mul_f32 v[18:19], v[18:19], v[248:249]
	v_pk_mul_f32 v[12:13], v[12:13], v[250:251]
	v_pk_mul_f32 v[14:15], v[14:15], v[252:253]
	s_waitcnt vmcnt(2)
	v_cvt_f32_ubyte0_e32 v246, v230
	v_cvt_f32_ubyte1_e32 v247, v230
	v_cvt_f32_ubyte2_e32 v248, v230
	v_cvt_f32_ubyte3_e32 v249, v230
	v_cvt_f32_ubyte0_e32 v250, v231
	v_cvt_f32_ubyte1_e32 v251, v231
	v_cvt_f32_ubyte2_e32 v252, v231
	v_cvt_f32_ubyte3_e32 v253, v231
	v_max_f32_e32 v246, 0.5, v246
	v_max_f32_e32 v247, 0.5, v247
	v_max_f32_e32 v248, 0.5, v248
	v_max_f32_e32 v249, 0.5, v249
	v_max_f32_e32 v250, 0.5, v250
	v_max_f32_e32 v251, 0.5, v251
	v_max_f32_e32 v252, 0.5, v252
	v_max_f32_e32 v253, 0.5, v253
	v_rcp_f32_e32 v246, v246
	v_rcp_f32_e32 v247, v247
	v_rcp_f32_e32 v248, v248
	v_rcp_f32_e32 v249, v249
	v_rcp_f32_e32 v250, v250
	v_rcp_f32_e32 v251, v251
	v_rcp_f32_e32 v252, v252
	v_rcp_f32_e32 v253, v253
	v_cvt_f32_ubyte0_e32 v238, v232
	v_cvt_f32_ubyte1_e32 v239, v232
	v_cvt_f32_ubyte2_e32 v154, v232
	v_cvt_f32_ubyte3_e32 v155, v232
	v_cvt_f32_ubyte0_e32 v156, v233
	v_cvt_f32_ubyte1_e32 v157, v233
	v_cvt_f32_ubyte2_e32 v2, v233
	v_cvt_f32_ubyte3_e32 v3, v233
	v_max_f32_e32 v238, 0.5, v238
	v_max_f32_e32 v239, 0.5, v239
	v_max_f32_e32 v154, 0.5, v154
	v_max_f32_e32 v155, 0.5, v155
	v_max_f32_e32 v156, 0.5, v156
	v_max_f32_e32 v157, 0.5, v157
	v_max_f32_e32 v2, 0.5, v2
	v_max_f32_e32 v3, 0.5, v3
	v_pk_mul_f32 v[246:247], v[238:239], v[246:247]
	v_pk_mul_f32 v[248:249], v[154:155], v[248:249]
	v_pk_mul_f32 v[250:251], v[156:157], v[250:251]
	v_pk_mul_f32 v[252:253], v[2:3], v[252:253]
	v_pk_mul_f32 v[40:41], v[40:41], v[246:247]
	v_pk_mul_f32 v[42:43], v[42:43], v[248:249]
	v_pk_mul_f32 v[36:37], v[36:37], v[250:251]
	v_pk_mul_f32 v[38:39], v[38:39], v[252:253]
	s_waitcnt vmcnt(0)
	v_cvt_f32_ubyte0_e32 v246, v234
	v_cvt_f32_ubyte1_e32 v247, v234
	v_cvt_f32_ubyte2_e32 v248, v234
	v_cvt_f32_ubyte3_e32 v249, v234
	v_cvt_f32_ubyte0_e32 v250, v235
	v_cvt_f32_ubyte1_e32 v251, v235
	v_cvt_f32_ubyte2_e32 v252, v235
	v_cvt_f32_ubyte3_e32 v253, v235
	v_max_f32_e32 v246, 0.5, v246
	v_max_f32_e32 v247, 0.5, v247
	v_max_f32_e32 v248, 0.5, v248
	v_max_f32_e32 v249, 0.5, v249
	v_max_f32_e32 v250, 0.5, v250
	v_max_f32_e32 v251, 0.5, v251
	v_max_f32_e32 v252, 0.5, v252
	v_max_f32_e32 v253, 0.5, v253
	v_rcp_f32_e32 v246, v246
	v_rcp_f32_e32 v247, v247
	v_rcp_f32_e32 v248, v248
	v_rcp_f32_e32 v249, v249
	v_rcp_f32_e32 v250, v250
	v_rcp_f32_e32 v251, v251
	v_rcp_f32_e32 v252, v252
	v_rcp_f32_e32 v253, v253
	v_cvt_f32_ubyte0_e32 v238, v236
	v_cvt_f32_ubyte1_e32 v239, v236
	v_cvt_f32_ubyte2_e32 v154, v236
	v_cvt_f32_ubyte3_e32 v155, v236
	v_cvt_f32_ubyte0_e32 v156, v237
	v_cvt_f32_ubyte1_e32 v157, v237
	v_cvt_f32_ubyte2_e32 v2, v237
	v_cvt_f32_ubyte3_e32 v3, v237
	v_max_f32_e32 v238, 0.5, v238
	v_max_f32_e32 v239, 0.5, v239
	v_max_f32_e32 v154, 0.5, v154
	v_max_f32_e32 v155, 0.5, v155
	v_max_f32_e32 v156, 0.5, v156
	v_max_f32_e32 v157, 0.5, v157
	v_max_f32_e32 v2, 0.5, v2
	v_max_f32_e32 v3, 0.5, v3
	v_pk_mul_f32 v[246:247], v[238:239], v[246:247]
	v_pk_mul_f32 v[248:249], v[154:155], v[248:249]
	v_pk_mul_f32 v[250:251], v[156:157], v[250:251]
	v_pk_mul_f32 v[252:253], v[2:3], v[252:253]
	v_pk_mul_f32 v[8:9], v[8:9], v[246:247]
	v_pk_mul_f32 v[10:11], v[10:11], v[248:249]
	v_pk_mul_f32 v[4:5], v[4:5], v[250:251]
	v_pk_mul_f32 v[6:7], v[6:7], v[252:253]
	s_mov_b64 s[40:41], -1
	s_branch .Lp3e_done

; #define PG8_STAGE(bufoff, gbase, voff) do { _Pragma("unroll") for (int _i = 0; _i < 2; ++_i) \
;         __builtin_amdgcn_global_load_lds((const __attribute__((address_space(1))) unsigned*)((const char*)(gbase) + (voff)[_i]), (LAS unsigned*)(lds + (bufoff) + ldsw + _i * 8192), 16, 0, 0); } while (0)
; #define PG8_LDA(dst, b, h) do { _Pragma("unroll") for (int m = 0; m < 4; ++m) _Pragma("unroll") for (int k = 0; k < 2; ++k) dst[m][k] = *(const LAS bf16x8*)(lds + PG8_SA(b, h) + aoff + m * 2048 + k * 1024); } while (0)
; #define PG8_LDB(dst, b, h) do { _Pragma("unroll") for (int n = 0; n < 2; ++n) _Pragma("unroll") for (int k = 0; k < 2; ++k) dst[n][k] = *(const LAS bf16x8*)(lds + PG8_SB(b, h) + boff + n * 2048 + k * 1024); } while (0)
; #define PG8_MMA(ai, bj, At, Bt) do { __builtin_amdgcn_s_setprio(1); _Pragma("unroll") for (int m = 0; m < 4; ++m) _Pragma("unroll") for (int n = 0; n < 2; ++n) _Pragma("unroll") for (int k = 0; k < 2; ++k) \
;         acc[ai][bj][m][n] = __builtin_amdgcn_mfma_f32_16x16x32_bf16(Bt[n][k], At[m][k], acc[ai][bj][m][n], 0, 0, 0); __builtin_amdgcn_s_setprio(0); } while (0)
; #define PG8_WAIT_V(n) asm volatile("s_waitcnt vmcnt(" #n ")" ::: "memory")
; #define PG8_WAIT_L(n) asm volatile("s_waitcnt lgkmcnt(" #n ")" ::: "memory")
; #define PG8_BAR __builtin_amdgcn_s_barrier()
; template <class Epi, class SchedT, bool ALIGN_EPI, bool SP2>
; __device__ __forceinline__ void gemm_phase(LAS unsigned char* lds, const int ldk, const int nt, const SchedT& S, const Epi& E) {
;     ...
;             const bool last = (t == nt - 2);
;             const char* a1 = cA + (size_t)(t + 1) * kstep;
;             const char* a2 = last ? nA : cA + (size_t)(t + 2) * kstep; const char* b2 = last ? nB : cB + (size_t)(t + 2) * kstep;
;             const char* a3 = a2 + kstep; const char* b3 = b2 + kstep;
;             if constexpr (SP2) {
;             PG8_LDB(B0, 0, 0); PG8_LDB(B1, 0, 1); PG8_SCHED; PG8_LDA(At, 0, 0); PG8_STAGE(PG8_SA(1, 1), a1 + hstep, voffA);
;             PG8_WAIT_V(8); PG8_WAIT_L(0); PG8_BAR; PG8_MMA(0, 0, At, B0); PG8_MMA(0, 1, At, B1); PG8_BAR; PG8_SCHED;
;             PG8_LDA(At, 0, 1); PG8_STAGE(PG8_SB(0, 0), b2, voffB); PG8_STAGE(PG8_SB(0, 1), b2 + hstepB, voffB); PG8_STAGE(PG8_SA(0, 0), a2, voffA);
;             PG8_WAIT_V(8); PG8_WAIT_L(0); PG8_BAR; PG8_MMA(1, 0, At, B0); PG8_MMA(1, 1, At, B1); PG8_BAR; PG8_SCHED;
.LBB0_668:
	s_add_u32 s36, s34, 0xfff80080
	s_addc_u32 s37, s35, -1
	s_add_i32 s51, 0, 0x10000
	s_cmp_eq_u32 s22, 28
	s_cselect_b32 s57, s1, s37
	s_cselect_b32 s56, s0, s36
	v_add_u32_e32 v144, s51, v147
	s_cselect_b32 s37, s55, s20
	s_cselect_b32 s36, s54, s13
	s_add_i32 s53, 0, 0x14000
	ds_read_b128 v[140:143], v144
	ds_read_b128 v[150:153], v144 offset:1024
	ds_read_b128 v[154:157], v144 offset:2048
	ds_read_b128 v[158:161], v144 offset:3072
	v_add_u32_e32 v144, s53, v147
	ds_read_b128 v[174:177], v144
	ds_read_b128 v[178:181], v144 offset:1024
	ds_read_b128 v[182:185], v144 offset:2048
	ds_read_b128 v[186:189], v144 offset:3072
	v_lshl_add_u64 v[144:145], s[34:35], 0, v[136:137]
	s_add_i32 m0, s17, 0xc000
	ds_read_b128 v[190:193], v149
	ds_read_b128 v[194:197], v149 offset:1024
	ds_read_b128 v[198:201], v149 offset:2048
	ds_read_b128 v[202:205], v149 offset:3072
	ds_read_b128 v[206:209], v149 offset:4096
	ds_read_b128 v[210:213], v149 offset:5120
	ds_read_b128 v[214:217], v149 offset:6144
	ds_read_b128 v[218:221], v149 offset:7168
	global_load_lds_dwordx4 v[144:145], off
	v_lshl_add_u64 v[144:145], s[34:35], 0, v[138:139]
	s_add_i32 m0, s17, 0xe000
	s_nop 0
	global_load_lds_dwordx4 v[144:145], off
	s_waitcnt vmcnt(8)
	s_waitcnt lgkmcnt(0)
	s_barrier
	s_waitcnt lgkmcnt(0)
	v_mfma_f32_16x16x32_bf16 v[126:129], v[140:143], v[190:193], v[126:129]
	v_mfma_f32_16x16x32_bf16 v[122:125], v[154:157], v[190:193], v[122:125]
	v_mfma_f32_16x16x32_bf16 v[110:113], v[140:143], v[198:201], v[110:113]
	v_mfma_f32_16x16x32_bf16 v[106:109], v[154:157], v[198:201], v[106:109]
	v_mfma_f32_16x16x32_bf16 v[94:97], v[140:143], v[206:209], v[94:97]
	v_mfma_f32_16x16x32_bf16 v[90:93], v[154:157], v[206:209], v[90:93]
	v_mfma_f32_16x16x32_bf16 v[78:81], v[140:143], v[214:217], v[78:81]
	v_mfma_f32_16x16x32_bf16 v[74:77], v[154:157], v[214:217], v[74:77]
	v_mfma_f32_16x16x32_bf16 v[126:129], v[150:153], v[194:197], v[126:129]
	v_mfma_f32_16x16x32_bf16 v[122:125], v[158:161], v[194:197], v[122:125]
	v_mfma_f32_16x16x32_bf16 v[110:113], v[150:153], v[202:205], v[110:113]
	v_mfma_f32_16x16x32_bf16 v[106:109], v[158:161], v[202:205], v[106:109]
	v_mfma_f32_16x16x32_bf16 v[94:97], v[150:153], v[210:213], v[94:97]
	v_mfma_f32_16x16x32_bf16 v[90:93], v[158:161], v[210:213], v[90:93]
	v_mfma_f32_16x16x32_bf16 v[78:81], v[150:153], v[218:221], v[78:81]
	v_mfma_f32_16x16x32_bf16 v[74:77], v[158:161], v[218:221], v[74:77]
	v_mfma_f32_16x16x32_bf16 v[118:121], v[174:177], v[190:193], v[118:121]
	v_mfma_f32_16x16x32_bf16 v[114:117], v[182:185], v[190:193], v[114:117]
	v_mfma_f32_16x16x32_bf16 v[102:105], v[174:177], v[198:201], v[102:105]
	v_mfma_f32_16x16x32_bf16 v[98:101], v[182:185], v[198:201], v[98:101]
	v_mfma_f32_16x16x32_bf16 v[86:89], v[174:177], v[206:209], v[86:89]
	v_mfma_f32_16x16x32_bf16 v[82:85], v[182:185], v[206:209], v[82:85]
	v_mfma_f32_16x16x32_bf16 v[70:73], v[174:177], v[214:217], v[70:73]
	v_mfma_f32_16x16x32_bf16 v[66:69], v[182:185], v[214:217], v[66:69]
	v_mfma_f32_16x16x32_bf16 v[118:121], v[178:181], v[194:197], v[118:121]
	v_mfma_f32_16x16x32_bf16 v[114:117], v[186:189], v[194:197], v[114:117]
	v_mfma_f32_16x16x32_bf16 v[102:105], v[178:181], v[202:205], v[102:105]
	v_mfma_f32_16x16x32_bf16 v[98:101], v[186:189], v[202:205], v[98:101]
	v_mfma_f32_16x16x32_bf16 v[86:89], v[178:181], v[210:213], v[86:89]
	v_mfma_f32_16x16x32_bf16 v[82:85], v[186:189], v[210:213], v[82:85]
	v_mfma_f32_16x16x32_bf16 v[70:73], v[178:181], v[218:221], v[70:73]
	v_mfma_f32_16x16x32_bf16 v[66:69], v[186:189], v[218:221], v[66:69]
	s_barrier
	s_add_i32 s51, s51, s61
	v_lshl_add_u64 v[144:145], s[36:37], 0, v[0:1]
	s_mov_b32 m0, s51
	ds_read_b128 v[190:193], v149 offset:16384
	ds_read_b128 v[194:197], v149 offset:17408
	ds_read_b128 v[198:201], v149 offset:18432
	ds_read_b128 v[202:205], v149 offset:19456
	ds_read_b128 v[206:209], v149 offset:20480
	ds_read_b128 v[210:213], v149 offset:21504
	ds_read_b128 v[214:217], v149 offset:22528
	ds_read_b128 v[218:221], v149 offset:23552
	global_load_lds_dwordx4 v[144:145], off
	s_add_i32 m0, s51, 0x2000
	s_add_u32 s86, s36, 0x20000
	v_lshl_add_u64 v[222:223], s[36:37], 0, v[134:135]
	s_addc_u32 s87, s37, 0
	s_add_i32 s51, s53, s61
	global_load_lds_dwordx4 v[222:223], off
	v_lshl_add_u64 v[224:225], s[86:87], 0, v[0:1]
	s_mov_b32 m0, s51
	v_lshl_add_u64 v[226:227], s[56:57], 0, v[132:133]
	global_load_lds_dwordx4 v[224:225], off
	v_lshl_add_u64 v[224:225], s[86:87], 0, v[134:135]
	s_add_i32 m0, s51, 0x2000
	s_nop 0
	global_load_lds_dwordx4 v[224:225], off
	v_lshl_add_u64 v[224:225], s[56:57], 0, v[130:131]
	s_mov_b32 m0, s17
	s_nop 0
	global_load_lds_dwordx4 v[224:225], off
	s_mov_b32 m0, s62
	s_nop 0
	global_load_lds_dwordx4 v[226:227], off
	s_waitcnt vmcnt(8)
	s_waitcnt lgkmcnt(0)
	s_barrier
; #define PG8_STAGE(bufoff, gbase, voff) do { _Pragma("unroll") for (int _i = 0; _i < 2; ++_i) \
;         __builtin_amdgcn_global_load_lds((const __attribute__((address_space(1))) unsigned*)((const char*)(gbase) + (voff)[_i]), (LAS unsigned*)(lds + (bufoff) + ldsw + _i * 8192), 16, 0, 0); } while (0)
; #define PG8_LDA(dst, b, h) do { _Pragma("unroll") for (int m = 0; m < 4; ++m) _Pragma("unroll") for (int k = 0; k < 2; ++k) dst[m][k] = *(const LAS bf16x8*)(lds + PG8_SA(b, h) + aoff + m * 2048 + k * 1024); } while (0)
; #define PG8_LDB(dst, b, h) do { _Pragma("unroll") for (int n = 0; n < 2; ++n) _Pragma("unroll") for (int k = 0; k < 2; ++k) dst[n][k] = *(const LAS bf16x8*)(lds + PG8_SB(b, h) + boff + n * 2048 + k * 1024); } while (0)
; #define PG8_MMA(ai, bj, At, Bt) do { __builtin_amdgcn_s_setprio(1); _Pragma("unroll") for (int m = 0; m < 4; ++m) _Pragma("unroll") for (int n = 0; n < 2; ++n) _Pragma("unroll") for (int k = 0; k < 2; ++k) \
;         acc[ai][bj][m][n] = __builtin_amdgcn_mfma_f32_16x16x32_bf16(Bt[n][k], At[m][k], acc[ai][bj][m][n], 0, 0, 0); __builtin_amdgcn_s_setprio(0); } while (0)
; #define PG8_WAIT_V(n) asm volatile("s_waitcnt vmcnt(" #n ")" ::: "memory")
; #define PG8_WAIT_L(n) asm volatile("s_waitcnt lgkmcnt(" #n ")" ::: "memory")
; #define PG8_BAR __builtin_amdgcn_s_barrier()
; #define PG8_SCHED __builtin_amdgcn_sched_barrier(0)
; template <class Epi, class SchedT, bool ALIGN_EPI, bool SP2>
; __device__ __forceinline__ void gemm_phase(LAS unsigned char* lds, const int ldk, const int nt, const SchedT& S, const Epi& E) {
;     ...
;             PG8_WAIT_V(8); PG8_WAIT_L(0); PG8_BAR; PG8_MMA(1, 0, At, B0); PG8_MMA(1, 1, At, B1); PG8_BAR; PG8_SCHED;
;             PG8_LDB(B0, 1, 0); PG8_LDB(B1, 1, 1); PG8_SCHED; PG8_LDA(At, 1, 0); PG8_STAGE(PG8_SA(0, 1), a2 + hstep, voffA);
;             PG8_WAIT_V(8); PG8_WAIT_L(0); PG8_BAR; PG8_MMA(0, 0, At, B0); PG8_MMA(0, 1, At, B1); PG8_BAR; PG8_SCHED;
	s_waitcnt lgkmcnt(0)
	v_mfma_f32_16x16x32_bf16 v[62:65], v[140:143], v[190:193], v[62:65]
	v_mfma_f32_16x16x32_bf16 v[58:61], v[154:157], v[190:193], v[58:61]
	v_mfma_f32_16x16x32_bf16 v[46:49], v[140:143], v[198:201], v[46:49]
	v_mfma_f32_16x16x32_bf16 v[42:45], v[154:157], v[198:201], v[42:45]
	v_mfma_f32_16x16x32_bf16 v[30:33], v[140:143], v[206:209], v[30:33]
	v_mfma_f32_16x16x32_bf16 v[26:29], v[154:157], v[206:209], v[26:29]
	v_mfma_f32_16x16x32_bf16 v[14:17], v[140:143], v[214:217], v[14:17]
	v_mfma_f32_16x16x32_bf16 v[10:13], v[154:157], v[214:217], v[10:13]
	v_mfma_f32_16x16x32_bf16 v[62:65], v[150:153], v[194:197], v[62:65]
	v_mfma_f32_16x16x32_bf16 v[58:61], v[158:161], v[194:197], v[58:61]
	v_mfma_f32_16x16x32_bf16 v[46:49], v[150:153], v[202:205], v[46:49]
	v_mfma_f32_16x16x32_bf16 v[42:45], v[158:161], v[202:205], v[42:45]
	v_mfma_f32_16x16x32_bf16 v[30:33], v[150:153], v[210:213], v[30:33]
	v_mfma_f32_16x16x32_bf16 v[26:29], v[158:161], v[210:213], v[26:29]
	v_mfma_f32_16x16x32_bf16 v[14:17], v[150:153], v[218:221], v[14:17]
	v_mfma_f32_16x16x32_bf16 v[10:13], v[158:161], v[218:221], v[10:13]
	v_mfma_f32_16x16x32_bf16 v[54:57], v[174:177], v[190:193], v[54:57]
	v_mfma_f32_16x16x32_bf16 v[50:53], v[182:185], v[190:193], v[50:53]
	v_mfma_f32_16x16x32_bf16 v[38:41], v[174:177], v[198:201], v[38:41]
	v_mfma_f32_16x16x32_bf16 v[34:37], v[182:185], v[198:201], v[34:37]
	v_mfma_f32_16x16x32_bf16 v[22:25], v[174:177], v[206:209], v[22:25]
	v_mfma_f32_16x16x32_bf16 v[18:21], v[182:185], v[206:209], v[18:21]
	v_mfma_f32_16x16x32_bf16 v[6:9], v[174:177], v[214:217], v[6:9]
	v_mfma_f32_16x16x32_bf16 v[2:5], v[182:185], v[214:217], v[2:5]
	v_mfma_f32_16x16x32_bf16 v[54:57], v[178:181], v[194:197], v[54:57]
	v_mfma_f32_16x16x32_bf16 v[50:53], v[186:189], v[194:197], v[50:53]
	v_mfma_f32_16x16x32_bf16 v[38:41], v[178:181], v[202:205], v[38:41]
	v_mfma_f32_16x16x32_bf16 v[34:37], v[186:189], v[202:205], v[34:37]
	v_mfma_f32_16x16x32_bf16 v[22:25], v[178:181], v[210:213], v[22:25]
	v_mfma_f32_16x16x32_bf16 v[18:21], v[186:189], v[210:213], v[18:21]
	v_mfma_f32_16x16x32_bf16 v[6:9], v[178:181], v[218:221], v[6:9]
	v_mfma_f32_16x16x32_bf16 v[2:5], v[186:189], v[218:221], v[2:5]
	s_barrier
	s_add_i32 s51, 0, 0x18000
	s_add_i32 s53, 0, 0x1c000
	v_add_u32_e32 v158, s51, v147
	v_add_u32_e32 v186, s53, v147
	ds_read_b128 v[140:143], v158
	ds_read_b128 v[150:153], v158 offset:1024
	ds_read_b128 v[154:157], v158 offset:2048
	ds_read_b128 v[158:161], v158 offset:3072
	ds_read_b128 v[174:177], v186
	ds_read_b128 v[178:181], v186 offset:1024
	ds_read_b128 v[182:185], v186 offset:2048
	ds_read_b128 v[186:189], v186 offset:3072
	s_add_u32 s56, s56, 0x80000
	s_addc_u32 s57, s57, 0
	s_mov_b32 m0, s63
	v_lshl_add_u64 v[228:229], s[56:57], 0, v[130:131]
	ds_read_b128 v[190:193], v149 offset:32768
	ds_read_b128 v[194:197], v149 offset:33792
	ds_read_b128 v[198:201], v149 offset:34816
	ds_read_b128 v[202:205], v149 offset:35840
	ds_read_b128 v[206:209], v149 offset:36864
	ds_read_b128 v[210:213], v149 offset:37888
	ds_read_b128 v[214:217], v149 offset:38912
	ds_read_b128 v[218:221], v149 offset:39936
	global_load_lds_dwordx4 v[228:229], off
	v_lshl_add_u64 v[228:229], s[56:57], 0, v[132:133]
	s_mov_b32 m0, s81
	s_nop 0
	global_load_lds_dwordx4 v[228:229], off
	s_waitcnt vmcnt(8)
	s_waitcnt lgkmcnt(0)
	s_barrier
	s_waitcnt lgkmcnt(0)
	v_mfma_f32_16x16x32_bf16 v[126:129], v[140:143], v[190:193], v[126:129]
	v_mfma_f32_16x16x32_bf16 v[122:125], v[154:157], v[190:193], v[122:125]
	v_mfma_f32_16x16x32_bf16 v[110:113], v[140:143], v[198:201], v[110:113]
	v_mfma_f32_16x16x32_bf16 v[106:109], v[154:157], v[198:201], v[106:109]
	v_mfma_f32_16x16x32_bf16 v[94:97], v[140:143], v[206:209], v[94:97]
	v_mfma_f32_16x16x32_bf16 v[90:93], v[154:157], v[206:209], v[90:93]
	v_mfma_f32_16x16x32_bf16 v[78:81], v[140:143], v[214:217], v[78:81]
	v_mfma_f32_16x16x32_bf16 v[74:77], v[154:157], v[214:217], v[74:77]
	v_mfma_f32_16x16x32_bf16 v[126:129], v[150:153], v[194:197], v[126:129]
	v_mfma_f32_16x16x32_bf16 v[122:125], v[158:161], v[194:197], v[122:125]
	v_mfma_f32_16x16x32_bf16 v[110:113], v[150:153], v[202:205], v[110:113]
	v_mfma_f32_16x16x32_bf16 v[106:109], v[158:161], v[202:205], v[106:109]
	v_mfma_f32_16x16x32_bf16 v[94:97], v[150:153], v[210:213], v[94:97]
	v_mfma_f32_16x16x32_bf16 v[90:93], v[158:161], v[210:213], v[90:93]
	v_mfma_f32_16x16x32_bf16 v[78:81], v[150:153], v[218:221], v[78:81]
	v_mfma_f32_16x16x32_bf16 v[74:77], v[158:161], v[218:221], v[74:77]
	v_mfma_f32_16x16x32_bf16 v[118:121], v[174:177], v[190:193], v[118:121]
	v_mfma_f32_16x16x32_bf16 v[114:117], v[182:185], v[190:193], v[114:117]
	v_mfma_f32_16x16x32_bf16 v[102:105], v[174:177], v[198:201], v[102:105]
	v_mfma_f32_16x16x32_bf16 v[98:101], v[182:185], v[198:201], v[98:101]
	v_mfma_f32_16x16x32_bf16 v[86:89], v[174:177], v[206:209], v[86:89]
	v_mfma_f32_16x16x32_bf16 v[82:85], v[182:185], v[206:209], v[82:85]
	v_mfma_f32_16x16x32_bf16 v[70:73], v[174:177], v[214:217], v[70:73]
	v_mfma_f32_16x16x32_bf16 v[66:69], v[182:185], v[214:217], v[66:69]
	v_mfma_f32_16x16x32_bf16 v[118:121], v[178:181], v[194:197], v[118:121]
	v_mfma_f32_16x16x32_bf16 v[114:117], v[186:189], v[194:197], v[114:117]
	v_mfma_f32_16x16x32_bf16 v[102:105], v[178:181], v[202:205], v[102:105]
	v_mfma_f32_16x16x32_bf16 v[98:101], v[186:189], v[202:205], v[98:101]
	v_mfma_f32_16x16x32_bf16 v[86:89], v[178:181], v[210:213], v[86:89]
	v_mfma_f32_16x16x32_bf16 v[82:85], v[186:189], v[210:213], v[82:85]
	v_mfma_f32_16x16x32_bf16 v[70:73], v[178:181], v[218:221], v[70:73]
	v_mfma_f32_16x16x32_bf16 v[66:69], v[186:189], v[218:221], v[66:69]
	s_barrier
; #define PG8_STAGE(bufoff, gbase, voff) do { _Pragma("unroll") for (int _i = 0; _i < 2; ++_i) \
;         __builtin_amdgcn_global_load_lds((const __attribute__((address_space(1))) unsigned*)((const char*)(gbase) + (voff)[_i]), (LAS unsigned*)(lds + (bufoff) + ldsw + _i * 8192), 16, 0, 0); } while (0)
; #define PG8_LDA(dst, b, h) do { _Pragma("unroll") for (int m = 0; m < 4; ++m) _Pragma("unroll") for (int k = 0; k < 2; ++k) dst[m][k] = *(const LAS bf16x8*)(lds + PG8_SA(b, h) + aoff + m * 2048 + k * 1024); } while (0)
; #define PG8_MMA(ai, bj, At, Bt) do { __builtin_amdgcn_s_setprio(1); _Pragma("unroll") for (int m = 0; m < 4; ++m) _Pragma("unroll") for (int n = 0; n < 2; ++n) _Pragma("unroll") for (int k = 0; k < 2; ++k) \
;         acc[ai][bj][m][n] = __builtin_amdgcn_mfma_f32_16x16x32_bf16(Bt[n][k], At[m][k], acc[ai][bj][m][n], 0, 0, 0); __builtin_amdgcn_s_setprio(0); } while (0)
; #define PG8_WAIT_V(n) asm volatile("s_waitcnt vmcnt(" #n ")" ::: "memory")
; #define PG8_WAIT_L(n) asm volatile("s_waitcnt lgkmcnt(" #n ")" ::: "memory")
; #define PG8_BAR __builtin_amdgcn_s_barrier()
; #define PG8_SCHED __builtin_amdgcn_sched_barrier(0)
; template <class Epi, class SchedT, bool ALIGN_EPI, bool SP2>
; __device__ __forceinline__ void gemm_phase(LAS unsigned char* lds, const int ldk, const int nt, const SchedT& S, const Epi& E) {
;     ...
;             PG8_WAIT_V(8); PG8_WAIT_L(0); PG8_BAR; PG8_MMA(0, 0, At, B0); PG8_MMA(0, 1, At, B1); PG8_BAR; PG8_SCHED;
;             PG8_LDA(At, 1, 1); PG8_STAGE(PG8_SB(1, 0), b3, voffB); PG8_STAGE(PG8_SB(1, 1), b3 + hstepB, voffB); PG8_STAGE(PG8_SA(1, 0), a3, voffA);
;             PG8_WAIT_V(8); PG8_WAIT_L(0); PG8_BAR; PG8_MMA(1, 0, At, B0); PG8_MMA(1, 1, At, B1); PG8_BAR; PG8_SCHED;
;     __device__ __forceinline__ void operator()(f32x4 (&acc)[2][2][4][2], const Unit& u, int wr, int wc, int fr, int fq) const {
;         const int row0 = u.pm * BM + wr * 64 + fr, col0 = u.pn * BM + wc * 64 + 8 * fq;
; #pragma unroll
;         for (int ai = 0; ai < 2; ++ai)
; #pragma unroll
;             for (int m = 0; m < 4; ++m) {
;                 const int row = row0 + ai * HALF + m * 16; float sq = 0.f;
; #pragma unroll
;                 for (int bj = 0; bj < 2; ++bj) {
;                     const size_t off = (size_t)row * D + col0 + bj * 32;
;                     const u32x4 xw = *(const u32x4*)(xin + off);
	s_add_i32 s51, s51, s61
	v_lshl_add_u64 v[144:145], v[144:145], 0, s[24:25]
	s_mov_b32 m0, s51
	ds_read_b128 v[190:193], v149 offset:49152
	ds_read_b128 v[194:197], v149 offset:50176
	ds_read_b128 v[198:201], v149 offset:51200
	ds_read_b128 v[202:205], v149 offset:52224
	ds_read_b128 v[206:209], v149 offset:53248
	ds_read_b128 v[210:213], v149 offset:54272
	ds_read_b128 v[214:217], v149 offset:55296
	ds_read_b128 v[218:221], v149 offset:56320
	global_load_lds_dwordx4 v[144:145], off
	s_add_i32 m0, s51, 0x2000
	s_add_u32 s36, s36, 0x20080
	v_lshl_add_u64 v[144:145], v[222:223], 0, s[24:25]
	s_addc_u32 s37, s37, 0
	s_add_i32 s51, s53, s61
	global_load_lds_dwordx4 v[144:145], off
	v_lshl_add_u64 v[144:145], s[36:37], 0, v[0:1]
	s_mov_b32 m0, s51
	s_nop 0
	global_load_lds_dwordx4 v[144:145], off
	v_lshl_add_u64 v[144:145], s[36:37], 0, v[134:135]
	s_add_i32 m0, s51, 0x2000
	s_nop 0
	global_load_lds_dwordx4 v[144:145], off
	v_lshl_add_u64 v[144:145], v[224:225], 0, s[24:25]
	s_mov_b32 m0, s83
	s_nop 0
	global_load_lds_dwordx4 v[144:145], off
	v_lshl_add_u64 v[144:145], v[226:227], 0, s[24:25]
	s_mov_b32 m0, s84
	s_nop 0
	global_load_lds_dwordx4 v[144:145], off
	s_waitcnt vmcnt(8)
	s_waitcnt lgkmcnt(0)
	s_barrier
	s_waitcnt lgkmcnt(0)
	v_mfma_f32_16x16x32_bf16 v[62:65], v[140:143], v[190:193], v[62:65]
	v_mfma_f32_16x16x32_bf16 v[58:61], v[154:157], v[190:193], v[58:61]
	v_mfma_f32_16x16x32_bf16 v[46:49], v[140:143], v[198:201], v[46:49]
	v_mfma_f32_16x16x32_bf16 v[42:45], v[154:157], v[198:201], v[42:45]
	v_mfma_f32_16x16x32_bf16 v[30:33], v[140:143], v[206:209], v[30:33]
	v_mfma_f32_16x16x32_bf16 v[26:29], v[154:157], v[206:209], v[26:29]
	v_mfma_f32_16x16x32_bf16 v[14:17], v[140:143], v[214:217], v[14:17]
	v_mfma_f32_16x16x32_bf16 v[10:13], v[154:157], v[214:217], v[10:13]
	v_mfma_f32_16x16x32_bf16 v[62:65], v[150:153], v[194:197], v[62:65]
	v_mfma_f32_16x16x32_bf16 v[58:61], v[158:161], v[194:197], v[58:61]
	v_mfma_f32_16x16x32_bf16 v[46:49], v[150:153], v[202:205], v[46:49]
	v_mfma_f32_16x16x32_bf16 v[42:45], v[158:161], v[202:205], v[42:45]
	v_mfma_f32_16x16x32_bf16 v[30:33], v[150:153], v[210:213], v[30:33]
	v_mfma_f32_16x16x32_bf16 v[26:29], v[158:161], v[210:213], v[26:29]
	v_mfma_f32_16x16x32_bf16 v[14:17], v[150:153], v[218:221], v[14:17]
	v_mfma_f32_16x16x32_bf16 v[10:13], v[158:161], v[218:221], v[10:13]
	v_mfma_f32_16x16x32_bf16 v[54:57], v[174:177], v[190:193], v[54:57]
	v_mfma_f32_16x16x32_bf16 v[50:53], v[182:185], v[190:193], v[50:53]
	v_mfma_f32_16x16x32_bf16 v[38:41], v[174:177], v[198:201], v[38:41]
	v_mfma_f32_16x16x32_bf16 v[34:37], v[182:185], v[198:201], v[34:37]
	v_mfma_f32_16x16x32_bf16 v[22:25], v[174:177], v[206:209], v[22:25]
	v_mfma_f32_16x16x32_bf16 v[18:21], v[182:185], v[206:209], v[18:21]
	v_mfma_f32_16x16x32_bf16 v[6:9], v[174:177], v[214:217], v[6:9]
	v_mfma_f32_16x16x32_bf16 v[2:5], v[182:185], v[214:217], v[2:5]
	v_mfma_f32_16x16x32_bf16 v[54:57], v[178:181], v[194:197], v[54:57]
	v_mfma_f32_16x16x32_bf16 v[50:53], v[186:189], v[194:197], v[50:53]
	v_mfma_f32_16x16x32_bf16 v[38:41], v[178:181], v[202:205], v[38:41]
	v_mfma_f32_16x16x32_bf16 v[34:37], v[186:189], v[202:205], v[34:37]
	v_mfma_f32_16x16x32_bf16 v[22:25], v[178:181], v[210:213], v[22:25]
	v_mfma_f32_16x16x32_bf16 v[18:21], v[186:189], v[210:213], v[18:21]
	v_mfma_f32_16x16x32_bf16 v[6:9], v[178:181], v[218:221], v[6:9]
	v_mfma_f32_16x16x32_bf16 v[2:5], v[186:189], v[218:221], v[2:5]
	s_barrier
	s_add_i32 s22, s22, 2
	s_add_u32 s34, s34, 0x100
	s_addc_u32 s35, s35, 0
	s_add_u32 s13, s13, 0x100
	s_addc_u32 s20, s20, 0
	s_cmp_gt_u32 s22, 29
	s_cbranch_scc0 .LBB0_668
	s_setprio 2
	v_lshl_add_u32 v142, s16, 8, v146
	v_lshl_or_b32 v140, s12, 8, v148
	v_lshlrev_b32_e32 v141, 12, v142
	v_lshl_add_u32 v150, v140, 1, v141
	v_add_u32_e32 v151, 0x10000, v150
	v_add_u32_e32 v152, 0x20000, v150
	v_add_u32_e32 v153, 0x30000, v150
	v_add_u32_e32 v154, 0x80000, v150
	v_add_u32_e32 v155, 0x90000, v150
	v_add_u32_e32 v156, 0xa0000, v150
	v_add_u32_e32 v157, 0xb0000, v150
	global_load_dwordx4 v[174:177], v150, s[42:43]
	global_load_dwordx4 v[178:181], v150, s[42:43] offset:64
	global_load_dwordx4 v[182:185], v151, s[42:43]
	global_load_dwordx4 v[186:189], v151, s[42:43] offset:64
	global_load_dwordx4 v[190:193], v152, s[42:43]
	global_load_dwordx4 v[194:197], v152, s[42:43] offset:64
	global_load_dwordx4 v[198:201], v153, s[42:43]
	global_load_dwordx4 v[202:205], v153, s[42:43] offset:64
	global_load_dwordx4 v[206:209], v154, s[42:43]
	global_load_dwordx4 v[210:213], v154, s[42:43] offset:64
	global_load_dwordx4 v[214:217], v155, s[42:43]
	global_load_dwordx4 v[218:221], v155, s[42:43] offset:64
	global_load_dwordx4 v[222:225], v156, s[42:43]
	global_load_dwordx4 v[226:229], v156, s[42:43] offset:64
	global_load_dwordx4 v[230:233], v157, s[42:43]
	global_load_dwordx4 v[234:237], v157, s[42:43] offset:64
	s_lshl_b32 s56, s12, 4
	s_lshl_b32 s22, s82, 2
	s_add_i32 s56, s56, s22
	v_lshl_add_u32 v158, v142, 7, s56
	v_add_u32_e32 v159, 0x1000, v158
	v_add_u32_e32 v160, 0x4000, v158
	v_add_u32_e32 v161, 0x5000, v158
	v_xor_b32_e32 v239, 16, v241
	v_xor_b32_e32 v252, 32, v241
	v_lshlrev_b32_e32 v239, 2, v239
	v_lshlrev_b32_e32 v252, 2, v252
	s_and_b64 vcc, exec, s[48:49]
	s_cbranch_vccnz .Lg0bar_p4
	s_setprio 1
	s_branch .LBB0_671
.Lg0bar_p4:
	s_barrier
; __device__ __forceinline__ float bf_lo(unsigned w) { return __uint_as_float(w << 16); }
; __device__ __forceinline__ float bf_hi(unsigned w) { return __uint_as_float(w & 0xffff0000u); }
; __device__ __forceinline__ u32x4 pack8(f32x4 a, f32x4 b) { u32x4 w; w.x = cvt_pk_bf16(a[0], a[1]); w.y = cvt_pk_bf16(a[2], a[3]); w.z = cvt_pk_bf16(b[0], b[1]); w.w = cvt_pk_bf16(b[2], b[3]); return w; }
;     __device__ __forceinline__ void operator()(f32x4 (&acc)[2][2][4][2], const Unit& u, int wr, int wc, int fr, int fq) const {
;     ...
;                 const int row = row0 + ai * HALF + m * 16; float sq = 0.f;
; #pragma unroll
;                 for (int bj = 0; bj < 2; ++bj) {
;                     const size_t off = (size_t)row * D + col0 + bj * 32;
;                     const u32x4 xw = *(const u32x4*)(xin + off);
;                     const f32x4 v0 = acc[ai][bj][m][0] + (f32x4){bf_lo(xw.x), bf_hi(xw.x), bf_lo(xw.y), bf_hi(xw.y)}, v1 = acc[ai][bj][m][1] + (f32x4){bf_lo(xw.z), bf_hi(xw.z), bf_lo(xw.w), bf_hi(xw.w)};
;                     *(u32x4*)(xb + off) = pack8(v0, v1);
;                     sq += (v0[0] * v0[0] + v0[1] * v0[1]) + (v0[2] * v0[2] + v0[3] * v0[3]) + (v1[0] * v1[0] + v1[1] * v1[1]) + (v1[2] * v1[2] + v1[3] * v1[3]);
.LBB0_671:
	s_waitcnt vmcnt(15)
	v_lshlrev_b32_e32 v246, 16, v174
	v_and_b32_e32 v247, 0xffff0000, v174
	v_lshlrev_b32_e32 v248, 16, v175
	v_and_b32_e32 v249, 0xffff0000, v175
	v_pk_add_f32 v[126:127], v[126:127], v[246:247]
	v_pk_add_f32 v[128:129], v[128:129], v[248:249]
	v_lshlrev_b32_e32 v246, 16, v176
	v_and_b32_e32 v247, 0xffff0000, v176
	v_lshlrev_b32_e32 v248, 16, v177
	v_and_b32_e32 v249, 0xffff0000, v177
	v_pk_add_f32 v[122:123], v[122:123], v[246:247]
	v_pk_add_f32 v[124:125], v[124:125], v[248:249]
	v_cvt_pk_bf16_f32 v174, v126, v127
	v_cvt_pk_bf16_f32 v175, v128, v129
	v_cvt_pk_bf16_f32 v176, v122, v123
	v_cvt_pk_bf16_f32 v177, v124, v125
	global_store_dwordx4 v150, v[174:177], s[44:45]
	v_pk_mul_f32 v[250:251], v[126:127], v[126:127]
	v_pk_fma_f32 v[250:251], v[128:129], v[128:129], v[250:251]
	v_pk_fma_f32 v[250:251], v[122:123], v[122:123], v[250:251]
	v_pk_fma_f32 v[250:251], v[124:125], v[124:125], v[250:251]
	s_waitcnt vmcnt(15)
	v_lshlrev_b32_e32 v246, 16, v178
	v_and_b32_e32 v247, 0xffff0000, v178
	v_lshlrev_b32_e32 v248, 16, v179
	v_and_b32_e32 v249, 0xffff0000, v179
	v_pk_add_f32 v[118:119], v[118:119], v[246:247]
	v_pk_add_f32 v[120:121], v[120:121], v[248:249]
	v_lshlrev_b32_e32 v246, 16, v180
	v_and_b32_e32 v247, 0xffff0000, v180
	v_lshlrev_b32_e32 v248, 16, v181
	v_and_b32_e32 v249, 0xffff0000, v181
	v_pk_add_f32 v[114:115], v[114:115], v[246:247]
	v_pk_add_f32 v[116:117], v[116:117], v[248:249]
	v_cvt_pk_bf16_f32 v178, v118, v119
	v_cvt_pk_bf16_f32 v179, v120, v121
	v_cvt_pk_bf16_f32 v180, v114, v115
	v_cvt_pk_bf16_f32 v181, v116, v117
	global_store_dwordx4 v150, v[178:181], s[44:45] offset:64
	v_pk_fma_f32 v[250:251], v[118:119], v[118:119], v[250:251]
	v_pk_fma_f32 v[250:251], v[120:121], v[120:121], v[250:251]
	v_pk_fma_f32 v[250:251], v[114:115], v[114:115], v[250:251]
	v_pk_fma_f32 v[250:251], v[116:117], v[116:117], v[250:251]
	v_add_f32_e32 v140, v250, v251
	s_waitcnt vmcnt(15)
	v_lshlrev_b32_e32 v246, 16, v182
	v_and_b32_e32 v247, 0xffff0000, v182
	v_lshlrev_b32_e32 v248, 16, v183
	v_and_b32_e32 v249, 0xffff0000, v183
	v_pk_add_f32 v[110:111], v[110:111], v[246:247]
	v_pk_add_f32 v[112:113], v[112:113], v[248:249]
	v_lshlrev_b32_e32 v246, 16, v184
	v_and_b32_e32 v247, 0xffff0000, v184
	v_lshlrev_b32_e32 v248, 16, v185
	v_and_b32_e32 v249, 0xffff0000, v185
	v_pk_add_f32 v[106:107], v[106:107], v[246:247]
	v_pk_add_f32 v[108:109], v[108:109], v[248:249]
	v_cvt_pk_bf16_f32 v182, v110, v111
	v_cvt_pk_bf16_f32 v183, v112, v113
	v_cvt_pk_bf16_f32 v184, v106, v107
	v_cvt_pk_bf16_f32 v185, v108, v109
	global_store_dwordx4 v151, v[182:185], s[44:45]
	v_pk_mul_f32 v[250:251], v[110:111], v[110:111]
	v_pk_fma_f32 v[250:251], v[112:113], v[112:113], v[250:251]
	v_pk_fma_f32 v[250:251], v[106:107], v[106:107], v[250:251]
	v_pk_fma_f32 v[250:251], v[108:109], v[108:109], v[250:251]
	s_waitcnt vmcnt(15)
	v_lshlrev_b32_e32 v246, 16, v186
	v_and_b32_e32 v247, 0xffff0000, v186
	v_lshlrev_b32_e32 v248, 16, v187
	v_and_b32_e32 v249, 0xffff0000, v187
	v_pk_add_f32 v[102:103], v[102:103], v[246:247]
	v_pk_add_f32 v[104:105], v[104:105], v[248:249]
	v_lshlrev_b32_e32 v246, 16, v188
	v_and_b32_e32 v247, 0xffff0000, v188
	v_lshlrev_b32_e32 v248, 16, v189
	v_and_b32_e32 v249, 0xffff0000, v189
	v_pk_add_f32 v[98:99], v[98:99], v[246:247]
	v_pk_add_f32 v[100:101], v[100:101], v[248:249]
	v_cvt_pk_bf16_f32 v186, v102, v103
	v_cvt_pk_bf16_f32 v187, v104, v105
	v_cvt_pk_bf16_f32 v188, v98, v99
	v_cvt_pk_bf16_f32 v189, v100, v101
	global_store_dwordx4 v151, v[186:189], s[44:45] offset:64
	v_pk_fma_f32 v[250:251], v[102:103], v[102:103], v[250:251]
	v_pk_fma_f32 v[250:251], v[104:105], v[104:105], v[250:251]
	v_pk_fma_f32 v[250:251], v[98:99], v[98:99], v[250:251]
	v_pk_fma_f32 v[250:251], v[100:101], v[100:101], v[250:251]
	v_add_f32_e32 v141, v250, v251
	s_waitcnt vmcnt(15)
	v_lshlrev_b32_e32 v246, 16, v190
	v_and_b32_e32 v247, 0xffff0000, v190
	v_lshlrev_b32_e32 v248, 16, v191
	v_and_b32_e32 v249, 0xffff0000, v191
	v_pk_add_f32 v[94:95], v[94:95], v[246:247]
	v_pk_add_f32 v[96:97], v[96:97], v[248:249]
	v_lshlrev_b32_e32 v246, 16, v192
	v_and_b32_e32 v247, 0xffff0000, v192
	v_lshlrev_b32_e32 v248, 16, v193
	v_and_b32_e32 v249, 0xffff0000, v193
	v_pk_add_f32 v[90:91], v[90:91], v[246:247]
	v_pk_add_f32 v[92:93], v[92:93], v[248:249]
	v_cvt_pk_bf16_f32 v190, v94, v95
	v_cvt_pk_bf16_f32 v191, v96, v97
	v_cvt_pk_bf16_f32 v192, v90, v91
	v_cvt_pk_bf16_f32 v193, v92, v93
	global_store_dwordx4 v152, v[190:193], s[44:45]
	v_pk_mul_f32 v[250:251], v[94:95], v[94:95]
	v_pk_fma_f32 v[250:251], v[96:97], v[96:97], v[250:251]
	v_pk_fma_f32 v[250:251], v[90:91], v[90:91], v[250:251]
	v_pk_fma_f32 v[250:251], v[92:93], v[92:93], v[250:251]
	s_waitcnt vmcnt(15)
	v_lshlrev_b32_e32 v246, 16, v194
	v_and_b32_e32 v247, 0xffff0000, v194
	v_lshlrev_b32_e32 v248, 16, v195
	v_and_b32_e32 v249, 0xffff0000, v195
	v_pk_add_f32 v[86:87], v[86:87], v[246:247]
	v_pk_add_f32 v[88:89], v[88:89], v[248:249]
	v_lshlrev_b32_e32 v246, 16, v196
	v_and_b32_e32 v247, 0xffff0000, v196
	v_lshlrev_b32_e32 v248, 16, v197
	v_and_b32_e32 v249, 0xffff0000, v197
	v_pk_add_f32 v[82:83], v[82:83], v[246:247]
	v_pk_add_f32 v[84:85], v[84:85], v[248:249]
	v_cvt_pk_bf16_f32 v194, v86, v87
	v_cvt_pk_bf16_f32 v195, v88, v89
	v_cvt_pk_bf16_f32 v196, v82, v83
	v_cvt_pk_bf16_f32 v197, v84, v85
	global_store_dwordx4 v152, v[194:197], s[44:45] offset:64
	v_pk_fma_f32 v[250:251], v[86:87], v[86:87], v[250:251]
	v_pk_fma_f32 v[250:251], v[88:89], v[88:89], v[250:251]
	v_pk_fma_f32 v[250:251], v[82:83], v[82:83], v[250:251]
	v_pk_fma_f32 v[250:251], v[84:85], v[84:85], v[250:251]
	v_add_f32_e32 v142, v250, v251
	s_waitcnt vmcnt(15)
; __device__ __forceinline__ float bf_lo(unsigned w) { return __uint_as_float(w << 16); }
; __device__ __forceinline__ float bf_hi(unsigned w) { return __uint_as_float(w & 0xffff0000u); }
; __device__ __forceinline__ u32x4 pack8(f32x4 a, f32x4 b) { u32x4 w; w.x = cvt_pk_bf16(a[0], a[1]); w.y = cvt_pk_bf16(a[2], a[3]); w.z = cvt_pk_bf16(b[0], b[1]); w.w = cvt_pk_bf16(b[2], b[3]); return w; }
;     __device__ __forceinline__ void operator()(f32x4 (&acc)[2][2][4][2], const Unit& u, int wr, int wc, int fr, int fq) const {
;     ...
;                 const int row = row0 + ai * HALF + m * 16; float sq = 0.f;
; #pragma unroll
;                 for (int bj = 0; bj < 2; ++bj) {
;                     const size_t off = (size_t)row * D + col0 + bj * 32;
;                     const u32x4 xw = *(const u32x4*)(xin + off);
;                     const f32x4 v0 = acc[ai][bj][m][0] + (f32x4){bf_lo(xw.x), bf_hi(xw.x), bf_lo(xw.y), bf_hi(xw.y)}, v1 = acc[ai][bj][m][1] + (f32x4){bf_lo(xw.z), bf_hi(xw.z), bf_lo(xw.w), bf_hi(xw.w)};
;                     *(u32x4*)(xb + off) = pack8(v0, v1);
;                     sq += (v0[0] * v0[0] + v0[1] * v0[1]) + (v0[2] * v0[2] + v0[3] * v0[3]) + (v1[0] * v1[0] + v1[1] * v1[1]) + (v1[2] * v1[2] + v1[3] * v1[3]);
	v_lshlrev_b32_e32 v246, 16, v198
	v_and_b32_e32 v247, 0xffff0000, v198
	v_lshlrev_b32_e32 v248, 16, v199
	v_and_b32_e32 v249, 0xffff0000, v199
	v_pk_add_f32 v[78:79], v[78:79], v[246:247]
	v_pk_add_f32 v[80:81], v[80:81], v[248:249]
	v_lshlrev_b32_e32 v246, 16, v200
	v_and_b32_e32 v247, 0xffff0000, v200
	v_lshlrev_b32_e32 v248, 16, v201
	v_and_b32_e32 v249, 0xffff0000, v201
	v_pk_add_f32 v[74:75], v[74:75], v[246:247]
	v_pk_add_f32 v[76:77], v[76:77], v[248:249]
	v_cvt_pk_bf16_f32 v198, v78, v79
	v_cvt_pk_bf16_f32 v199, v80, v81
	v_cvt_pk_bf16_f32 v200, v74, v75
	v_cvt_pk_bf16_f32 v201, v76, v77
	global_store_dwordx4 v153, v[198:201], s[44:45]
	v_pk_mul_f32 v[250:251], v[78:79], v[78:79]
	v_pk_fma_f32 v[250:251], v[80:81], v[80:81], v[250:251]
	v_pk_fma_f32 v[250:251], v[74:75], v[74:75], v[250:251]
	v_pk_fma_f32 v[250:251], v[76:77], v[76:77], v[250:251]
	s_waitcnt vmcnt(15)
	v_lshlrev_b32_e32 v246, 16, v202
	v_and_b32_e32 v247, 0xffff0000, v202
	v_lshlrev_b32_e32 v248, 16, v203
	v_and_b32_e32 v249, 0xffff0000, v203
	v_pk_add_f32 v[70:71], v[70:71], v[246:247]
	v_pk_add_f32 v[72:73], v[72:73], v[248:249]
	v_lshlrev_b32_e32 v246, 16, v204
	v_and_b32_e32 v247, 0xffff0000, v204
	v_lshlrev_b32_e32 v248, 16, v205
	v_and_b32_e32 v249, 0xffff0000, v205
	v_pk_add_f32 v[66:67], v[66:67], v[246:247]
	v_pk_add_f32 v[68:69], v[68:69], v[248:249]
	v_cvt_pk_bf16_f32 v202, v70, v71
	v_cvt_pk_bf16_f32 v203, v72, v73
	v_cvt_pk_bf16_f32 v204, v66, v67
	v_cvt_pk_bf16_f32 v205, v68, v69
	global_store_dwordx4 v153, v[202:205], s[44:45] offset:64
	v_pk_fma_f32 v[250:251], v[70:71], v[70:71], v[250:251]
	v_pk_fma_f32 v[250:251], v[72:73], v[72:73], v[250:251]
	v_pk_fma_f32 v[250:251], v[66:67], v[66:67], v[250:251]
	v_pk_fma_f32 v[250:251], v[68:69], v[68:69], v[250:251]
	v_add_f32_e32 v143, v250, v251
	s_waitcnt vmcnt(15)
	v_lshlrev_b32_e32 v246, 16, v206
	v_and_b32_e32 v247, 0xffff0000, v206
	v_lshlrev_b32_e32 v248, 16, v207
	v_and_b32_e32 v249, 0xffff0000, v207
	v_pk_add_f32 v[62:63], v[62:63], v[246:247]
	v_pk_add_f32 v[64:65], v[64:65], v[248:249]
	v_lshlrev_b32_e32 v246, 16, v208
	v_and_b32_e32 v247, 0xffff0000, v208
	v_lshlrev_b32_e32 v248, 16, v209
	v_and_b32_e32 v249, 0xffff0000, v209
	v_pk_add_f32 v[58:59], v[58:59], v[246:247]
	v_pk_add_f32 v[60:61], v[60:61], v[248:249]
	v_cvt_pk_bf16_f32 v206, v62, v63
	v_cvt_pk_bf16_f32 v207, v64, v65
	v_cvt_pk_bf16_f32 v208, v58, v59
	v_cvt_pk_bf16_f32 v209, v60, v61
	global_store_dwordx4 v154, v[206:209], s[44:45]
	v_pk_mul_f32 v[250:251], v[62:63], v[62:63]
	v_pk_fma_f32 v[250:251], v[64:65], v[64:65], v[250:251]
	v_pk_fma_f32 v[250:251], v[58:59], v[58:59], v[250:251]
	v_pk_fma_f32 v[250:251], v[60:61], v[60:61], v[250:251]
	s_waitcnt vmcnt(15)
	v_lshlrev_b32_e32 v246, 16, v210
	v_and_b32_e32 v247, 0xffff0000, v210
	v_lshlrev_b32_e32 v248, 16, v211
	v_and_b32_e32 v249, 0xffff0000, v211
	v_pk_add_f32 v[54:55], v[54:55], v[246:247]
	v_pk_add_f32 v[56:57], v[56:57], v[248:249]
	v_lshlrev_b32_e32 v246, 16, v212
	v_and_b32_e32 v247, 0xffff0000, v212
	v_lshlrev_b32_e32 v248, 16, v213
	v_and_b32_e32 v249, 0xffff0000, v213
	v_pk_add_f32 v[50:51], v[50:51], v[246:247]
	v_pk_add_f32 v[52:53], v[52:53], v[248:249]
	v_cvt_pk_bf16_f32 v210, v54, v55
	v_cvt_pk_bf16_f32 v211, v56, v57
	v_cvt_pk_bf16_f32 v212, v50, v51
	v_cvt_pk_bf16_f32 v213, v52, v53
	global_store_dwordx4 v154, v[210:213], s[44:45] offset:64
	v_pk_fma_f32 v[250:251], v[54:55], v[54:55], v[250:251]
	v_pk_fma_f32 v[250:251], v[56:57], v[56:57], v[250:251]
	v_pk_fma_f32 v[250:251], v[50:51], v[50:51], v[250:251]
	v_pk_fma_f32 v[250:251], v[52:53], v[52:53], v[250:251]
	v_add_f32_e32 v144, v250, v251
	s_waitcnt vmcnt(15)
	v_lshlrev_b32_e32 v246, 16, v214
	v_and_b32_e32 v247, 0xffff0000, v214
	v_lshlrev_b32_e32 v248, 16, v215
	v_and_b32_e32 v249, 0xffff0000, v215
	v_pk_add_f32 v[46:47], v[46:47], v[246:247]
	v_pk_add_f32 v[48:49], v[48:49], v[248:249]
	v_lshlrev_b32_e32 v246, 16, v216
	v_and_b32_e32 v247, 0xffff0000, v216
	v_lshlrev_b32_e32 v248, 16, v217
	v_and_b32_e32 v249, 0xffff0000, v217
	v_pk_add_f32 v[42:43], v[42:43], v[246:247]
	v_pk_add_f32 v[44:45], v[44:45], v[248:249]
	v_cvt_pk_bf16_f32 v214, v46, v47
	v_cvt_pk_bf16_f32 v215, v48, v49
	v_cvt_pk_bf16_f32 v216, v42, v43
	v_cvt_pk_bf16_f32 v217, v44, v45
	global_store_dwordx4 v155, v[214:217], s[44:45]
	v_pk_mul_f32 v[250:251], v[46:47], v[46:47]
	v_pk_fma_f32 v[250:251], v[48:49], v[48:49], v[250:251]
	v_pk_fma_f32 v[250:251], v[42:43], v[42:43], v[250:251]
	v_pk_fma_f32 v[250:251], v[44:45], v[44:45], v[250:251]
	s_waitcnt vmcnt(15)
	v_lshlrev_b32_e32 v246, 16, v218
	v_and_b32_e32 v247, 0xffff0000, v218
	v_lshlrev_b32_e32 v248, 16, v219
	v_and_b32_e32 v249, 0xffff0000, v219
	v_pk_add_f32 v[38:39], v[38:39], v[246:247]
	v_pk_add_f32 v[40:41], v[40:41], v[248:249]
	v_lshlrev_b32_e32 v246, 16, v220
	v_and_b32_e32 v247, 0xffff0000, v220
	v_lshlrev_b32_e32 v248, 16, v221
	v_and_b32_e32 v249, 0xffff0000, v221
	v_pk_add_f32 v[34:35], v[34:35], v[246:247]
	v_pk_add_f32 v[36:37], v[36:37], v[248:249]
	v_cvt_pk_bf16_f32 v218, v38, v39
	v_cvt_pk_bf16_f32 v219, v40, v41
	v_cvt_pk_bf16_f32 v220, v34, v35
	v_cvt_pk_bf16_f32 v221, v36, v37
	global_store_dwordx4 v155, v[218:221], s[44:45] offset:64
	v_pk_fma_f32 v[250:251], v[38:39], v[38:39], v[250:251]
	v_pk_fma_f32 v[250:251], v[40:41], v[40:41], v[250:251]
	v_pk_fma_f32 v[250:251], v[34:35], v[34:35], v[250:251]
	v_pk_fma_f32 v[250:251], v[36:37], v[36:37], v[250:251]
	v_add_f32_e32 v145, v250, v251
	s_waitcnt vmcnt(15)
; __device__ __forceinline__ float bf_lo(unsigned w) { return __uint_as_float(w << 16); }
; __device__ __forceinline__ float bf_hi(unsigned w) { return __uint_as_float(w & 0xffff0000u); }
; __device__ __forceinline__ u32x4 pack8(f32x4 a, f32x4 b) { u32x4 w; w.x = cvt_pk_bf16(a[0], a[1]); w.y = cvt_pk_bf16(a[2], a[3]); w.z = cvt_pk_bf16(b[0], b[1]); w.w = cvt_pk_bf16(b[2], b[3]); return w; }
; #define PG8_BAR __builtin_amdgcn_s_barrier()
; template <class Epi, class SchedT, bool ALIGN_EPI, bool SP2>
; __device__ __forceinline__ void gemm_phase(LAS unsigned char* lds, const int ldk, const int nt, const SchedT& S, const Epi& E) {
;     ...
;         if (!has_next) break;
;         if (!(SchedT::kMode == 2 && cur.kind == 0)) {
; #pragma unroll
;         for (int a = 0; a < 2; ++a)
; #pragma unroll
;             for (int b = 0; b < 2; ++b)
; #pragma unroll
;                 for (int m = 0; m < 4; ++m)
; #pragma unroll
;                     for (int n = 0; n < 2; ++n) acc[a][b][m][n] = (f32x4){0.f, 0.f, 0.f, 0.f};
;         }
;         cur = nxt; cA = nA; cB = nB; ++ui;
;         if constexpr (ALIGN_EPI) { if (wr == 1) PG8_BAR; }
;     __device__ __forceinline__ void operator()(f32x4 (&acc)[2][2][4][2], const Unit& u, int wr, int wc, int fr, int fq) const {
;     ...
;                 const int row = row0 + ai * HALF + m * 16; float sq = 0.f;
; #pragma unroll
;                 for (int bj = 0; bj < 2; ++bj) {
;                     const size_t off = (size_t)row * D + col0 + bj * 32;
;                     const u32x4 xw = *(const u32x4*)(xin + off);
;                     const f32x4 v0 = acc[ai][bj][m][0] + (f32x4){bf_lo(xw.x), bf_hi(xw.x), bf_lo(xw.y), bf_hi(xw.y)}, v1 = acc[ai][bj][m][1] + (f32x4){bf_lo(xw.z), bf_hi(xw.z), bf_lo(xw.w), bf_hi(xw.w)};
;                     *(u32x4*)(xb + off) = pack8(v0, v1);
;                     sq += (v0[0] * v0[0] + v0[1] * v0[1]) + (v0[2] * v0[2] + v0[3] * v0[3]) + (v1[0] * v1[0] + v1[1] * v1[1]) + (v1[2] * v1[2] + v1[3] * v1[3]);
;                 }
;                 sq += __shfl_xor(sq, 16); sq += __shfl_xor(sq, 32);
;                 if (fq == 0) ss[(size_t)row * 32 + u.pn * 4 + wc] = sq;
	v_lshlrev_b32_e32 v246, 16, v222
	v_and_b32_e32 v247, 0xffff0000, v222
	v_lshlrev_b32_e32 v248, 16, v223
	v_and_b32_e32 v249, 0xffff0000, v223
	v_pk_add_f32 v[30:31], v[30:31], v[246:247]
	v_pk_add_f32 v[32:33], v[32:33], v[248:249]
	v_lshlrev_b32_e32 v246, 16, v224
	v_and_b32_e32 v247, 0xffff0000, v224
	v_lshlrev_b32_e32 v248, 16, v225
	v_and_b32_e32 v249, 0xffff0000, v225
	v_pk_add_f32 v[26:27], v[26:27], v[246:247]
	v_pk_add_f32 v[28:29], v[28:29], v[248:249]
	v_cvt_pk_bf16_f32 v222, v30, v31
	v_cvt_pk_bf16_f32 v223, v32, v33
	v_cvt_pk_bf16_f32 v224, v26, v27
	v_cvt_pk_bf16_f32 v225, v28, v29
	global_store_dwordx4 v156, v[222:225], s[44:45]
	v_pk_mul_f32 v[250:251], v[30:31], v[30:31]
	v_pk_fma_f32 v[250:251], v[32:33], v[32:33], v[250:251]
	v_pk_fma_f32 v[250:251], v[26:27], v[26:27], v[250:251]
	v_pk_fma_f32 v[250:251], v[28:29], v[28:29], v[250:251]
	s_waitcnt vmcnt(15)
	v_lshlrev_b32_e32 v246, 16, v226
	v_and_b32_e32 v247, 0xffff0000, v226
	v_lshlrev_b32_e32 v248, 16, v227
	v_and_b32_e32 v249, 0xffff0000, v227
	v_pk_add_f32 v[22:23], v[22:23], v[246:247]
	v_pk_add_f32 v[24:25], v[24:25], v[248:249]
	v_lshlrev_b32_e32 v246, 16, v228
	v_and_b32_e32 v247, 0xffff0000, v228
	v_lshlrev_b32_e32 v248, 16, v229
	v_and_b32_e32 v249, 0xffff0000, v229
	v_pk_add_f32 v[18:19], v[18:19], v[246:247]
	v_pk_add_f32 v[20:21], v[20:21], v[248:249]
	v_cvt_pk_bf16_f32 v226, v22, v23
	v_cvt_pk_bf16_f32 v227, v24, v25
	v_cvt_pk_bf16_f32 v228, v18, v19
	v_cvt_pk_bf16_f32 v229, v20, v21
	global_store_dwordx4 v156, v[226:229], s[44:45] offset:64
	v_pk_fma_f32 v[250:251], v[22:23], v[22:23], v[250:251]
	v_pk_fma_f32 v[250:251], v[24:25], v[24:25], v[250:251]
	v_pk_fma_f32 v[250:251], v[18:19], v[18:19], v[250:251]
	v_pk_fma_f32 v[250:251], v[20:21], v[20:21], v[250:251]
	v_add_f32_e32 v162, v250, v251
	s_waitcnt vmcnt(15)
	v_lshlrev_b32_e32 v246, 16, v230
	v_and_b32_e32 v247, 0xffff0000, v230
	v_lshlrev_b32_e32 v248, 16, v231
	v_and_b32_e32 v249, 0xffff0000, v231
	v_pk_add_f32 v[14:15], v[14:15], v[246:247]
	v_pk_add_f32 v[16:17], v[16:17], v[248:249]
	v_lshlrev_b32_e32 v246, 16, v232
	v_and_b32_e32 v247, 0xffff0000, v232
	v_lshlrev_b32_e32 v248, 16, v233
	v_and_b32_e32 v249, 0xffff0000, v233
	v_pk_add_f32 v[10:11], v[10:11], v[246:247]
	v_pk_add_f32 v[12:13], v[12:13], v[248:249]
	v_cvt_pk_bf16_f32 v230, v14, v15
	v_cvt_pk_bf16_f32 v231, v16, v17
	v_cvt_pk_bf16_f32 v232, v10, v11
	v_cvt_pk_bf16_f32 v233, v12, v13
	global_store_dwordx4 v157, v[230:233], s[44:45]
	v_pk_mul_f32 v[250:251], v[14:15], v[14:15]
	v_pk_fma_f32 v[250:251], v[16:17], v[16:17], v[250:251]
	v_pk_fma_f32 v[250:251], v[10:11], v[10:11], v[250:251]
	v_pk_fma_f32 v[250:251], v[12:13], v[12:13], v[250:251]
	s_waitcnt vmcnt(15)
	v_lshlrev_b32_e32 v246, 16, v234
	v_and_b32_e32 v247, 0xffff0000, v234
	v_lshlrev_b32_e32 v248, 16, v235
	v_and_b32_e32 v249, 0xffff0000, v235
	v_pk_add_f32 v[6:7], v[6:7], v[246:247]
	v_pk_add_f32 v[8:9], v[8:9], v[248:249]
	v_lshlrev_b32_e32 v246, 16, v236
	v_and_b32_e32 v247, 0xffff0000, v236
	v_lshlrev_b32_e32 v248, 16, v237
	v_and_b32_e32 v249, 0xffff0000, v237
	v_pk_add_f32 v[2:3], v[2:3], v[246:247]
	v_pk_add_f32 v[4:5], v[4:5], v[248:249]
	v_cvt_pk_bf16_f32 v234, v6, v7
	v_cvt_pk_bf16_f32 v235, v8, v9
	v_cvt_pk_bf16_f32 v236, v2, v3
	v_cvt_pk_bf16_f32 v237, v4, v5
	global_store_dwordx4 v157, v[234:237], s[44:45] offset:64
	v_pk_fma_f32 v[250:251], v[6:7], v[6:7], v[250:251]
	v_pk_fma_f32 v[250:251], v[8:9], v[8:9], v[250:251]
	v_pk_fma_f32 v[250:251], v[2:3], v[2:3], v[250:251]
	v_pk_fma_f32 v[250:251], v[4:5], v[4:5], v[250:251]
	v_add_f32_e32 v238, v250, v251
	ds_bpermute_b32 v174, v239, v140
	ds_bpermute_b32 v175, v239, v141
	ds_bpermute_b32 v176, v239, v142
	ds_bpermute_b32 v177, v239, v143
	ds_bpermute_b32 v178, v239, v144
	ds_bpermute_b32 v179, v239, v145
	ds_bpermute_b32 v180, v239, v162
	ds_bpermute_b32 v181, v239, v238
	s_waitcnt lgkmcnt(0)
	v_add_f32_e32 v140, v140, v174
	v_add_f32_e32 v141, v141, v175
	v_add_f32_e32 v142, v142, v176
	v_add_f32_e32 v143, v143, v177
	v_add_f32_e32 v144, v144, v178
	v_add_f32_e32 v145, v145, v179
	v_add_f32_e32 v162, v162, v180
	v_add_f32_e32 v238, v238, v181
	ds_bpermute_b32 v174, v252, v140
	ds_bpermute_b32 v175, v252, v141
	ds_bpermute_b32 v176, v252, v142
	ds_bpermute_b32 v177, v252, v143
	ds_bpermute_b32 v178, v252, v144
	ds_bpermute_b32 v179, v252, v145
	ds_bpermute_b32 v180, v252, v162
	ds_bpermute_b32 v181, v252, v238
	s_waitcnt lgkmcnt(0)
	v_add_f32_e32 v140, v140, v174
	v_add_f32_e32 v141, v141, v175
	v_add_f32_e32 v142, v142, v176
	v_add_f32_e32 v143, v143, v177
	v_add_f32_e32 v144, v144, v178
	v_add_f32_e32 v145, v145, v179
	v_add_f32_e32 v162, v162, v180
	v_add_f32_e32 v238, v238, v181
	s_and_saveexec_b64 s[12:13], s[38:39]
	global_store_dword v158, v140, s[46:47]
	global_store_dword v158, v141, s[46:47] offset:2048
	global_store_dword v159, v142, s[46:47]
	global_store_dword v159, v143, s[46:47] offset:2048
	global_store_dword v160, v144, s[46:47]
	global_store_dword v160, v145, s[46:47] offset:2048
	global_store_dword v161, v162, s[46:47]
	global_store_dword v161, v238, s[46:47] offset:2048
	s_mov_b32 s86, 0x20000
	s_mov_b32 s87, 0x28000
	s_or_b64 exec, exec, s[12:13]
	s_and_b64 vcc, exec, s[40:41]
	s_mov_b64 s[12:13], -1
	s_cbranch_vccnz .LBB0_662
	s_setprio 0
	s_andn2_b64 vcc, exec, s[18:19]
	s_cbranch_vccnz .LBB0_661
	s_barrier
	s_setprio 1
	s_branch .LBB0_661

; #define PG8_STAGE(bufoff, gbase, voff) do { _Pragma("unroll") for (int _i = 0; _i < 2; ++_i) \
;         __builtin_amdgcn_global_load_lds((const __attribute__((address_space(1))) unsigned*)((const char*)(gbase) + (voff)[_i]), (LAS unsigned*)(lds + (bufoff) + ldsw + _i * 8192), 16, 0, 0); } while (0)
; #define PG8_LDA(dst, b, h) do { _Pragma("unroll") for (int m = 0; m < 4; ++m) _Pragma("unroll") for (int k = 0; k < 2; ++k) dst[m][k] = *(const LAS bf16x8*)(lds + PG8_SA(b, h) + aoff + m * 2048 + k * 1024); } while (0)
; #define PG8_LDB(dst, b, h) do { _Pragma("unroll") for (int n = 0; n < 2; ++n) _Pragma("unroll") for (int k = 0; k < 2; ++k) dst[n][k] = *(const LAS bf16x8*)(lds + PG8_SB(b, h) + boff + n * 2048 + k * 1024); } while (0)
; #define PG8_MMA(ai, bj, At, Bt) do { __builtin_amdgcn_s_setprio(1); _Pragma("unroll") for (int m = 0; m < 4; ++m) _Pragma("unroll") for (int n = 0; n < 2; ++n) _Pragma("unroll") for (int k = 0; k < 2; ++k) \
;         acc[ai][bj][m][n] = __builtin_amdgcn_mfma_f32_16x16x32_bf16(Bt[n][k], At[m][k], acc[ai][bj][m][n], 0, 0, 0); __builtin_amdgcn_s_setprio(0); } while (0)
; #define PG8_WAIT_V(n) asm volatile("s_waitcnt vmcnt(" #n ")" ::: "memory")
; #define PG8_WAIT_L(n) asm volatile("s_waitcnt lgkmcnt(" #n ")" ::: "memory")
; #define PG8_BAR __builtin_amdgcn_s_barrier()
; template <class Epi, class SchedT, bool ALIGN_EPI, bool SP2>
; __device__ __forceinline__ void gemm_phase(LAS unsigned char* lds, const int ldk, const int nt, const SchedT& S, const Epi& E) {
;     ...
;             const bool last = (t == nt - 2);
;             const char* a1 = cA + (size_t)(t + 1) * kstep;
;             const char* a2 = last ? nA : cA + (size_t)(t + 2) * kstep; const char* b2 = last ? nB : cB + (size_t)(t + 2) * kstep;
;             const char* a3 = a2 + kstep; const char* b3 = b2 + kstep;
;             if constexpr (SP2) {
;             PG8_LDB(B0, 0, 0); PG8_LDB(B1, 0, 1); PG8_SCHED; PG8_LDA(At, 0, 0); PG8_STAGE(PG8_SA(1, 1), a1 + hstep, voffA);
;             PG8_WAIT_V(8); PG8_WAIT_L(0); PG8_BAR; PG8_MMA(0, 0, At, B0); PG8_MMA(0, 1, At, B1); PG8_BAR; PG8_SCHED;
;             PG8_LDA(At, 0, 1); PG8_STAGE(PG8_SB(0, 0), b2, voffB); PG8_STAGE(PG8_SB(0, 1), b2 + hstepB, voffB); PG8_STAGE(PG8_SA(0, 0), a2, voffA);
;             PG8_WAIT_V(8); PG8_WAIT_L(0); PG8_BAR; PG8_MMA(1, 0, At, B0); PG8_MMA(1, 1, At, B1); PG8_BAR; PG8_SCHED;
.LBB0_752:
	s_add_u32 s36, s34, 0xfff80080
	s_addc_u32 s37, s35, -1
	s_add_i32 s61, 0, 0x10000
	s_cmp_eq_u32 s59, 28
	s_cselect_b32 vcc_hi, s1, s37
	s_cselect_b32 vcc_lo, s0, s36
	s_cselect_b32 s37, s63, s17
	s_cselect_b32 s36, s62, s13
	s_add_i32 s64, 0, 0x14000
	v_add_u32_e32 v142, s61, v248
	v_add_u32_e32 v182, s64, v248
	ds_read_b128 v[130:133], v142
	ds_read_b128 v[134:137], v142 offset:1024
	ds_read_b128 v[138:141], v142 offset:2048
	ds_read_b128 v[142:145], v142 offset:3072
	ds_read_b128 v[158:161], v182
	ds_read_b128 v[174:177], v182 offset:1024
	ds_read_b128 v[178:181], v182 offset:2048
	ds_read_b128 v[182:185], v182 offset:3072
	v_lshl_add_u64 v[218:219], s[34:35], 0, v[154:155]
	s_add_i32 m0, s85, 0xc000
	ds_read_b128 v[186:189], v251
	ds_read_b128 v[190:193], v251 offset:1024
	ds_read_b128 v[194:197], v251 offset:2048
	ds_read_b128 v[198:201], v251 offset:3072
	ds_read_b128 v[202:205], v251 offset:4096
	ds_read_b128 v[206:209], v251 offset:5120
	ds_read_b128 v[210:213], v251 offset:6144
	ds_read_b128 v[214:217], v251 offset:7168
	global_load_lds_dwordx4 v[218:219], off
	v_lshl_add_u64 v[218:219], s[34:35], 0, v[156:157]
	s_add_i32 m0, s85, 0xe000
	s_nop 0
	global_load_lds_dwordx4 v[218:219], off
	s_waitcnt vmcnt(8)
	s_waitcnt lgkmcnt(0)
	s_barrier
	s_waitcnt lgkmcnt(0)
	v_mfma_f32_16x16x32_bf16 v[126:129], v[130:133], v[186:189], v[126:129]
	v_mfma_f32_16x16x32_bf16 v[62:65], v[138:141], v[186:189], v[62:65]
	v_mfma_f32_16x16x32_bf16 v[118:121], v[130:133], v[194:197], v[118:121]
	v_mfma_f32_16x16x32_bf16 v[58:61], v[138:141], v[194:197], v[58:61]
	v_mfma_f32_16x16x32_bf16 v[110:113], v[130:133], v[202:205], v[110:113]
	v_mfma_f32_16x16x32_bf16 v[46:49], v[138:141], v[202:205], v[46:49]
	v_mfma_f32_16x16x32_bf16 v[106:109], v[130:133], v[210:213], v[106:109]
	v_mfma_f32_16x16x32_bf16 v[42:45], v[138:141], v[210:213], v[42:45]
	v_mfma_f32_16x16x32_bf16 v[126:129], v[134:137], v[190:193], v[126:129]
	v_mfma_f32_16x16x32_bf16 v[62:65], v[142:145], v[190:193], v[62:65]
	v_mfma_f32_16x16x32_bf16 v[118:121], v[134:137], v[198:201], v[118:121]
	v_mfma_f32_16x16x32_bf16 v[58:61], v[142:145], v[198:201], v[58:61]
	v_mfma_f32_16x16x32_bf16 v[110:113], v[134:137], v[206:209], v[110:113]
	v_mfma_f32_16x16x32_bf16 v[46:49], v[142:145], v[206:209], v[46:49]
	v_mfma_f32_16x16x32_bf16 v[106:109], v[134:137], v[214:217], v[106:109]
	v_mfma_f32_16x16x32_bf16 v[42:45], v[142:145], v[214:217], v[42:45]
	v_mfma_f32_16x16x32_bf16 v[122:125], v[158:161], v[186:189], v[122:125]
	v_mfma_f32_16x16x32_bf16 v[54:57], v[178:181], v[186:189], v[54:57]
	v_mfma_f32_16x16x32_bf16 v[114:117], v[158:161], v[194:197], v[114:117]
	v_mfma_f32_16x16x32_bf16 v[50:53], v[178:181], v[194:197], v[50:53]
	v_mfma_f32_16x16x32_bf16 v[102:105], v[158:161], v[202:205], v[102:105]
	v_mfma_f32_16x16x32_bf16 v[38:41], v[178:181], v[202:205], v[38:41]
	v_mfma_f32_16x16x32_bf16 v[98:101], v[158:161], v[210:213], v[98:101]
	v_mfma_f32_16x16x32_bf16 v[34:37], v[178:181], v[210:213], v[34:37]
	v_mfma_f32_16x16x32_bf16 v[122:125], v[174:177], v[190:193], v[122:125]
	v_mfma_f32_16x16x32_bf16 v[54:57], v[182:185], v[190:193], v[54:57]
	v_mfma_f32_16x16x32_bf16 v[114:117], v[174:177], v[198:201], v[114:117]
	v_mfma_f32_16x16x32_bf16 v[50:53], v[182:185], v[198:201], v[50:53]
	v_mfma_f32_16x16x32_bf16 v[102:105], v[174:177], v[206:209], v[102:105]
	v_mfma_f32_16x16x32_bf16 v[38:41], v[182:185], v[206:209], v[38:41]
	v_mfma_f32_16x16x32_bf16 v[98:101], v[174:177], v[214:217], v[98:101]
	v_mfma_f32_16x16x32_bf16 v[34:37], v[182:185], v[214:217], v[34:37]
	s_barrier
	s_add_i32 s61, s61, s84
	v_lshl_add_u64 v[218:219], s[36:37], 0, v[0:1]
	s_mov_b32 m0, s61
	ds_read_b128 v[186:189], v251 offset:16384
	ds_read_b128 v[190:193], v251 offset:17408
	ds_read_b128 v[194:197], v251 offset:18432
	ds_read_b128 v[198:201], v251 offset:19456
	ds_read_b128 v[202:205], v251 offset:20480
	ds_read_b128 v[206:209], v251 offset:21504
	ds_read_b128 v[210:213], v251 offset:22528
	ds_read_b128 v[214:217], v251 offset:23552
	global_load_lds_dwordx4 v[218:219], off
	s_add_i32 m0, s61, 0x2000
	s_add_u32 s94, s36, 0x20000
	v_lshl_add_u64 v[220:221], s[36:37], 0, v[150:151]
	s_addc_u32 s95, s37, 0
	s_add_i32 s61, s64, s84
	global_load_lds_dwordx4 v[220:221], off
	v_lshl_add_u64 v[222:223], s[94:95], 0, v[0:1]
	s_mov_b32 m0, s61
	v_lshl_add_u64 v[224:225], vcc, 0, v[148:149]
	global_load_lds_dwordx4 v[222:223], off
	v_lshl_add_u64 v[222:223], s[94:95], 0, v[150:151]
	s_add_i32 m0, s61, 0x2000
	s_nop 0
	global_load_lds_dwordx4 v[222:223], off
	v_lshl_add_u64 v[222:223], vcc, 0, v[146:147]
	s_mov_b32 m0, s85
	s_nop 0
	global_load_lds_dwordx4 v[222:223], off
	s_mov_b32 m0, s86
	s_nop 0
	global_load_lds_dwordx4 v[224:225], off
	s_waitcnt vmcnt(8)
	s_waitcnt lgkmcnt(0)
	s_barrier
; #define PG8_STAGE(bufoff, gbase, voff) do { _Pragma("unroll") for (int _i = 0; _i < 2; ++_i) \
;         __builtin_amdgcn_global_load_lds((const __attribute__((address_space(1))) unsigned*)((const char*)(gbase) + (voff)[_i]), (LAS unsigned*)(lds + (bufoff) + ldsw + _i * 8192), 16, 0, 0); } while (0)
; #define PG8_LDA(dst, b, h) do { _Pragma("unroll") for (int m = 0; m < 4; ++m) _Pragma("unroll") for (int k = 0; k < 2; ++k) dst[m][k] = *(const LAS bf16x8*)(lds + PG8_SA(b, h) + aoff + m * 2048 + k * 1024); } while (0)
; #define PG8_LDB(dst, b, h) do { _Pragma("unroll") for (int n = 0; n < 2; ++n) _Pragma("unroll") for (int k = 0; k < 2; ++k) dst[n][k] = *(const LAS bf16x8*)(lds + PG8_SB(b, h) + boff + n * 2048 + k * 1024); } while (0)
; #define PG8_MMA(ai, bj, At, Bt) do { __builtin_amdgcn_s_setprio(1); _Pragma("unroll") for (int m = 0; m < 4; ++m) _Pragma("unroll") for (int n = 0; n < 2; ++n) _Pragma("unroll") for (int k = 0; k < 2; ++k) \
;         acc[ai][bj][m][n] = __builtin_amdgcn_mfma_f32_16x16x32_bf16(Bt[n][k], At[m][k], acc[ai][bj][m][n], 0, 0, 0); __builtin_amdgcn_s_setprio(0); } while (0)
; #define PG8_WAIT_V(n) asm volatile("s_waitcnt vmcnt(" #n ")" ::: "memory")
; #define PG8_WAIT_L(n) asm volatile("s_waitcnt lgkmcnt(" #n ")" ::: "memory")
; #define PG8_BAR __builtin_amdgcn_s_barrier()
; #define PG8_SCHED __builtin_amdgcn_sched_barrier(0)
; template <class Epi, class SchedT, bool ALIGN_EPI, bool SP2>
; __device__ __forceinline__ void gemm_phase(LAS unsigned char* lds, const int ldk, const int nt, const SchedT& S, const Epi& E) {
;     ...
;             PG8_WAIT_V(8); PG8_WAIT_L(0); PG8_BAR; PG8_MMA(1, 0, At, B0); PG8_MMA(1, 1, At, B1); PG8_BAR; PG8_SCHED;
;             PG8_LDB(B0, 1, 0); PG8_LDB(B1, 1, 1); PG8_SCHED; PG8_LDA(At, 1, 0); PG8_STAGE(PG8_SA(0, 1), a2 + hstep, voffA);
;             PG8_WAIT_V(8); PG8_WAIT_L(0); PG8_BAR; PG8_MMA(0, 0, At, B0); PG8_MMA(0, 1, At, B1); PG8_BAR; PG8_SCHED;
	s_waitcnt lgkmcnt(0)
	v_mfma_f32_16x16x32_bf16 v[94:97], v[130:133], v[186:189], v[94:97]
	v_mfma_f32_16x16x32_bf16 v[30:33], v[138:141], v[186:189], v[30:33]
	v_mfma_f32_16x16x32_bf16 v[90:93], v[130:133], v[194:197], v[90:93]
	v_mfma_f32_16x16x32_bf16 v[26:29], v[138:141], v[194:197], v[26:29]
	v_mfma_f32_16x16x32_bf16 v[78:81], v[130:133], v[202:205], v[78:81]
	v_mfma_f32_16x16x32_bf16 v[14:17], v[138:141], v[202:205], v[14:17]
	v_mfma_f32_16x16x32_bf16 v[74:77], v[130:133], v[210:213], v[74:77]
	v_mfma_f32_16x16x32_bf16 v[10:13], v[138:141], v[210:213], v[10:13]
	v_mfma_f32_16x16x32_bf16 v[94:97], v[134:137], v[190:193], v[94:97]
	v_mfma_f32_16x16x32_bf16 v[30:33], v[142:145], v[190:193], v[30:33]
	v_mfma_f32_16x16x32_bf16 v[90:93], v[134:137], v[198:201], v[90:93]
	v_mfma_f32_16x16x32_bf16 v[26:29], v[142:145], v[198:201], v[26:29]
	v_mfma_f32_16x16x32_bf16 v[78:81], v[134:137], v[206:209], v[78:81]
	v_mfma_f32_16x16x32_bf16 v[14:17], v[142:145], v[206:209], v[14:17]
	v_mfma_f32_16x16x32_bf16 v[74:77], v[134:137], v[214:217], v[74:77]
	v_mfma_f32_16x16x32_bf16 v[10:13], v[142:145], v[214:217], v[10:13]
	v_mfma_f32_16x16x32_bf16 v[86:89], v[158:161], v[186:189], v[86:89]
	v_mfma_f32_16x16x32_bf16 v[22:25], v[178:181], v[186:189], v[22:25]
	v_mfma_f32_16x16x32_bf16 v[82:85], v[158:161], v[194:197], v[82:85]
	v_mfma_f32_16x16x32_bf16 v[18:21], v[178:181], v[194:197], v[18:21]
	v_mfma_f32_16x16x32_bf16 v[70:73], v[158:161], v[202:205], v[70:73]
	v_mfma_f32_16x16x32_bf16 v[6:9], v[178:181], v[202:205], v[6:9]
	v_mfma_f32_16x16x32_bf16 v[66:69], v[158:161], v[210:213], v[66:69]
	v_mfma_f32_16x16x32_bf16 v[2:5], v[178:181], v[210:213], v[2:5]
	v_mfma_f32_16x16x32_bf16 v[86:89], v[174:177], v[190:193], v[86:89]
	v_mfma_f32_16x16x32_bf16 v[22:25], v[182:185], v[190:193], v[22:25]
	v_mfma_f32_16x16x32_bf16 v[82:85], v[174:177], v[198:201], v[82:85]
	v_mfma_f32_16x16x32_bf16 v[18:21], v[182:185], v[198:201], v[18:21]
	v_mfma_f32_16x16x32_bf16 v[70:73], v[174:177], v[206:209], v[70:73]
	v_mfma_f32_16x16x32_bf16 v[6:9], v[182:185], v[206:209], v[6:9]
	v_mfma_f32_16x16x32_bf16 v[66:69], v[174:177], v[214:217], v[66:69]
	v_mfma_f32_16x16x32_bf16 v[2:5], v[182:185], v[214:217], v[2:5]
	s_barrier
	s_add_i32 s61, 0, 0x18000
	s_add_i32 s64, 0, 0x1c000
	v_add_u32_e32 v142, s61, v248
	v_add_u32_e32 v182, s64, v248
	ds_read_b128 v[130:133], v142
	ds_read_b128 v[134:137], v142 offset:1024
	ds_read_b128 v[138:141], v142 offset:2048
	ds_read_b128 v[142:145], v142 offset:3072
	ds_read_b128 v[158:161], v182
	ds_read_b128 v[174:177], v182 offset:1024
	ds_read_b128 v[178:181], v182 offset:2048
	ds_read_b128 v[182:185], v182 offset:3072
	s_add_u32 s94, vcc_lo, 0x80000
	s_addc_u32 s95, vcc_hi, 0
	s_mov_b32 m0, s87
	v_lshl_add_u64 v[226:227], s[94:95], 0, v[146:147]
	ds_read_b128 v[186:189], v251 offset:32768
	ds_read_b128 v[190:193], v251 offset:33792
	ds_read_b128 v[194:197], v251 offset:34816
	ds_read_b128 v[198:201], v251 offset:35840
	ds_read_b128 v[202:205], v251 offset:36864
	ds_read_b128 v[206:209], v251 offset:37888
	ds_read_b128 v[210:213], v251 offset:38912
	ds_read_b128 v[214:217], v251 offset:39936
	global_load_lds_dwordx4 v[226:227], off
	v_lshl_add_u64 v[226:227], s[94:95], 0, v[148:149]
	s_mov_b32 m0, s88
	s_nop 0
	global_load_lds_dwordx4 v[226:227], off
	s_waitcnt vmcnt(8)
	s_waitcnt lgkmcnt(0)
	s_barrier
	s_waitcnt lgkmcnt(0)
	v_mfma_f32_16x16x32_bf16 v[126:129], v[130:133], v[186:189], v[126:129]
	v_mfma_f32_16x16x32_bf16 v[62:65], v[138:141], v[186:189], v[62:65]
	v_mfma_f32_16x16x32_bf16 v[118:121], v[130:133], v[194:197], v[118:121]
	v_mfma_f32_16x16x32_bf16 v[58:61], v[138:141], v[194:197], v[58:61]
	v_mfma_f32_16x16x32_bf16 v[110:113], v[130:133], v[202:205], v[110:113]
	v_mfma_f32_16x16x32_bf16 v[46:49], v[138:141], v[202:205], v[46:49]
	v_mfma_f32_16x16x32_bf16 v[106:109], v[130:133], v[210:213], v[106:109]
	v_mfma_f32_16x16x32_bf16 v[42:45], v[138:141], v[210:213], v[42:45]
	v_mfma_f32_16x16x32_bf16 v[126:129], v[134:137], v[190:193], v[126:129]
	v_mfma_f32_16x16x32_bf16 v[62:65], v[142:145], v[190:193], v[62:65]
	v_mfma_f32_16x16x32_bf16 v[118:121], v[134:137], v[198:201], v[118:121]
	v_mfma_f32_16x16x32_bf16 v[58:61], v[142:145], v[198:201], v[58:61]
	v_mfma_f32_16x16x32_bf16 v[110:113], v[134:137], v[206:209], v[110:113]
	v_mfma_f32_16x16x32_bf16 v[46:49], v[142:145], v[206:209], v[46:49]
	v_mfma_f32_16x16x32_bf16 v[106:109], v[134:137], v[214:217], v[106:109]
	v_mfma_f32_16x16x32_bf16 v[42:45], v[142:145], v[214:217], v[42:45]
	v_mfma_f32_16x16x32_bf16 v[122:125], v[158:161], v[186:189], v[122:125]
	v_mfma_f32_16x16x32_bf16 v[54:57], v[178:181], v[186:189], v[54:57]
	v_mfma_f32_16x16x32_bf16 v[114:117], v[158:161], v[194:197], v[114:117]
	v_mfma_f32_16x16x32_bf16 v[50:53], v[178:181], v[194:197], v[50:53]
	v_mfma_f32_16x16x32_bf16 v[102:105], v[158:161], v[202:205], v[102:105]
	v_mfma_f32_16x16x32_bf16 v[38:41], v[178:181], v[202:205], v[38:41]
	v_mfma_f32_16x16x32_bf16 v[98:101], v[158:161], v[210:213], v[98:101]
	v_mfma_f32_16x16x32_bf16 v[34:37], v[178:181], v[210:213], v[34:37]
	v_mfma_f32_16x16x32_bf16 v[122:125], v[174:177], v[190:193], v[122:125]
	v_mfma_f32_16x16x32_bf16 v[54:57], v[182:185], v[190:193], v[54:57]
	v_mfma_f32_16x16x32_bf16 v[114:117], v[174:177], v[198:201], v[114:117]
	v_mfma_f32_16x16x32_bf16 v[50:53], v[182:185], v[198:201], v[50:53]
	v_mfma_f32_16x16x32_bf16 v[102:105], v[174:177], v[206:209], v[102:105]
	v_mfma_f32_16x16x32_bf16 v[38:41], v[182:185], v[206:209], v[38:41]
	v_mfma_f32_16x16x32_bf16 v[98:101], v[174:177], v[214:217], v[98:101]
	v_mfma_f32_16x16x32_bf16 v[34:37], v[182:185], v[214:217], v[34:37]
	s_barrier
; #define PG8_STAGE(bufoff, gbase, voff) do { _Pragma("unroll") for (int _i = 0; _i < 2; ++_i) \
;         __builtin_amdgcn_global_load_lds((const __attribute__((address_space(1))) unsigned*)((const char*)(gbase) + (voff)[_i]), (LAS unsigned*)(lds + (bufoff) + ldsw + _i * 8192), 16, 0, 0); } while (0)
; #define PG8_BAR __builtin_amdgcn_s_barrier()
; __device__ __forceinline__ float row_rstd(const float* ssp, int row, int fq) {
;     const f32x4 a = *(const f32x4*)(ssp + (size_t)row * 32 + 8 * fq), b = *(const f32x4*)(ssp + (size_t)row * 32 + 8 * fq + 4);
; template <class Epi, class SchedT, bool ALIGN_EPI, bool SP2>
; __device__ __forceinline__ void gemm_phase(LAS unsigned char* lds, const int ldk, const int nt, const SchedT& S, const Epi& E) {
;     ...
;             PG8_LDA(At, 1, 1); PG8_STAGE(PG8_SB(1, 0), b3, voffB); PG8_STAGE(PG8_SB(1, 1), b3 + hstepB, voffB); PG8_STAGE(PG8_SA(1, 0), a3, voffA);
;             PG8_WAIT_V(8); PG8_WAIT_L(0); PG8_BAR; PG8_MMA(1, 0, At, B0); PG8_MMA(1, 1, At, B1); PG8_BAR; PG8_SCHED;
;             } else {
;             PG8_LDB(B0, 0, 0); PG8_SCHED; PG8_LDA(At, 0, 0); PG8_STAGE(PG8_SA(1, 1), a1 + hstep, voffA);
;             PG8_WAIT_L(8); PG8_BAR; PG8_WAIT_L(0); PG8_MMA(0, 0, At, B0); PG8_BAR; PG8_SCHED;
;             PG8_LDB(B1, 0, 1); PG8_STAGE(PG8_SB(0, 0), b2, voffB);
;             PG8_BAR; PG8_WAIT_L(0); PG8_MMA(0, 1, At, B1); PG8_BAR;
;             PG8_LDA(At, 0, 1); PG8_STAGE(PG8_SA(0, 0), a2, voffA);
;             PG8_BAR; PG8_WAIT_L(0); PG8_MMA(1, 0, At, B0); PG8_BAR; PG8_SCHED;
;             PG8_STAGE(PG8_SB(0, 1), b2 + hstepB, voffB);
;             PG8_WAIT_V(6); PG8_BAR; PG8_MMA(1, 1, At, B1); PG8_BAR;
;             PG8_LDB(B0, 1, 0); PG8_SCHED; PG8_LDA(At, 1, 0); PG8_STAGE(PG8_SA(0, 1), a2 + hstep, voffA);
;             PG8_WAIT_L(8); PG8_BAR; PG8_WAIT_L(0); PG8_MMA(0, 0, At, B0); PG8_BAR; PG8_SCHED;
;             PG8_LDB(B1, 1, 1); PG8_STAGE(PG8_SB(1, 0), b3, voffB);
;             PG8_BAR; PG8_WAIT_L(0); PG8_MMA(0, 1, At, B1); PG8_BAR;
;             PG8_LDA(At, 1, 1); PG8_STAGE(PG8_SA(1, 0), a3, voffA);
;             PG8_BAR; PG8_WAIT_L(0); PG8_MMA(1, 0, At, B0); PG8_BAR; PG8_SCHED;
;             PG8_STAGE(PG8_SB(1, 1), b3 + hstepB, voffB);
;             PG8_WAIT_V(6); PG8_BAR; PG8_MMA(1, 1, At, B1); PG8_BAR;
;             }
;         }
;         if constexpr (ALIGN_EPI) { if (wr == 0) PG8_BAR; }
	s_add_i32 s61, s61, s84
	v_lshl_add_u64 v[218:219], v[218:219], 0, s[24:25]
	s_mov_b32 m0, s61
	ds_read_b128 v[186:189], v251 offset:49152
	ds_read_b128 v[190:193], v251 offset:50176
	ds_read_b128 v[194:197], v251 offset:51200
	ds_read_b128 v[198:201], v251 offset:52224
	ds_read_b128 v[202:205], v251 offset:53248
	ds_read_b128 v[206:209], v251 offset:54272
	ds_read_b128 v[210:213], v251 offset:55296
	ds_read_b128 v[214:217], v251 offset:56320
	global_load_lds_dwordx4 v[218:219], off
	s_add_i32 m0, s61, 0x2000
	s_add_u32 s36, s36, 0x20080
	v_lshl_add_u64 v[218:219], v[220:221], 0, s[24:25]
	s_addc_u32 s37, s37, 0
	s_add_i32 s61, s64, s84
	global_load_lds_dwordx4 v[218:219], off
	v_lshl_add_u64 v[218:219], s[36:37], 0, v[0:1]
	s_mov_b32 m0, s61
	s_nop 0
	global_load_lds_dwordx4 v[218:219], off
	v_lshl_add_u64 v[218:219], s[36:37], 0, v[150:151]
	s_add_i32 m0, s61, 0x2000
	s_nop 0
	global_load_lds_dwordx4 v[218:219], off
	v_lshl_add_u64 v[218:219], v[222:223], 0, s[24:25]
	s_mov_b32 m0, s89
	s_nop 0
	global_load_lds_dwordx4 v[218:219], off
	v_lshl_add_u64 v[218:219], v[224:225], 0, s[24:25]
	s_mov_b32 m0, s90
	s_nop 0
	global_load_lds_dwordx4 v[218:219], off
	s_waitcnt vmcnt(8)
	s_waitcnt lgkmcnt(0)
	s_barrier
	s_waitcnt lgkmcnt(0)
	v_mfma_f32_16x16x32_bf16 v[94:97], v[130:133], v[186:189], v[94:97]
	v_mfma_f32_16x16x32_bf16 v[30:33], v[138:141], v[186:189], v[30:33]
	v_mfma_f32_16x16x32_bf16 v[90:93], v[130:133], v[194:197], v[90:93]
	v_mfma_f32_16x16x32_bf16 v[26:29], v[138:141], v[194:197], v[26:29]
	v_mfma_f32_16x16x32_bf16 v[78:81], v[130:133], v[202:205], v[78:81]
	v_mfma_f32_16x16x32_bf16 v[14:17], v[138:141], v[202:205], v[14:17]
	v_mfma_f32_16x16x32_bf16 v[74:77], v[130:133], v[210:213], v[74:77]
	v_mfma_f32_16x16x32_bf16 v[10:13], v[138:141], v[210:213], v[10:13]
	v_mfma_f32_16x16x32_bf16 v[94:97], v[134:137], v[190:193], v[94:97]
	v_mfma_f32_16x16x32_bf16 v[30:33], v[142:145], v[190:193], v[30:33]
	v_mfma_f32_16x16x32_bf16 v[90:93], v[134:137], v[198:201], v[90:93]
	v_mfma_f32_16x16x32_bf16 v[26:29], v[142:145], v[198:201], v[26:29]
	v_mfma_f32_16x16x32_bf16 v[78:81], v[134:137], v[206:209], v[78:81]
	v_mfma_f32_16x16x32_bf16 v[14:17], v[142:145], v[206:209], v[14:17]
	v_mfma_f32_16x16x32_bf16 v[74:77], v[134:137], v[214:217], v[74:77]
	v_mfma_f32_16x16x32_bf16 v[10:13], v[142:145], v[214:217], v[10:13]
	v_mfma_f32_16x16x32_bf16 v[86:89], v[158:161], v[186:189], v[86:89]
	v_mfma_f32_16x16x32_bf16 v[22:25], v[178:181], v[186:189], v[22:25]
	v_mfma_f32_16x16x32_bf16 v[82:85], v[158:161], v[194:197], v[82:85]
	v_mfma_f32_16x16x32_bf16 v[18:21], v[178:181], v[194:197], v[18:21]
	v_mfma_f32_16x16x32_bf16 v[70:73], v[158:161], v[202:205], v[70:73]
	v_mfma_f32_16x16x32_bf16 v[6:9], v[178:181], v[202:205], v[6:9]
	v_mfma_f32_16x16x32_bf16 v[66:69], v[158:161], v[210:213], v[66:69]
	v_mfma_f32_16x16x32_bf16 v[2:5], v[178:181], v[210:213], v[2:5]
	v_mfma_f32_16x16x32_bf16 v[86:89], v[174:177], v[190:193], v[86:89]
	v_mfma_f32_16x16x32_bf16 v[22:25], v[182:185], v[190:193], v[22:25]
	v_mfma_f32_16x16x32_bf16 v[82:85], v[174:177], v[198:201], v[82:85]
	v_mfma_f32_16x16x32_bf16 v[18:21], v[182:185], v[198:201], v[18:21]
	v_mfma_f32_16x16x32_bf16 v[70:73], v[174:177], v[206:209], v[70:73]
	v_mfma_f32_16x16x32_bf16 v[6:9], v[182:185], v[206:209], v[6:9]
	v_mfma_f32_16x16x32_bf16 v[66:69], v[174:177], v[214:217], v[66:69]
	v_mfma_f32_16x16x32_bf16 v[2:5], v[182:185], v[214:217], v[2:5]
	s_barrier
	s_add_i32 s59, s59, 2
	s_add_u32 s34, s34, 0x100
	s_addc_u32 s35, s35, 0
	s_add_u32 s13, s13, 0x100
	s_addc_u32 s17, s17, 0
	s_cmp_gt_u32 s59, 29
	s_cbranch_scc0 .LBB0_752
	s_setprio 2
	v_lshl_add_u32 v130, s12, 8, v247
	v_lshlrev_b32_e32 v140, 7, v130
	v_mov_b32_e32 v141, 0
	v_lshl_add_u64 v[132:133], v[152:153], 0, v[140:141]
	v_add_u32_e32 v140, 0x1000, v140
	v_lshl_add_u64 v[134:135], v[152:153], 0, v[140:141]
	v_add_u32_e32 v140, 0x3000, v140
	v_lshl_add_u64 v[136:137], v[152:153], 0, v[140:141]
	v_add_u32_e32 v140, 0x1000, v140
	v_lshl_add_u64 v[138:139], v[152:153], 0, v[140:141]
	global_load_dwordx4 v[174:177], v[132:133], off
	global_load_dwordx4 v[178:181], v[132:133], off offset:16
	global_load_dwordx4 v[182:185], v[132:133], off offset:2048
	global_load_dwordx4 v[186:189], v[132:133], off offset:2064
	global_load_dwordx4 v[190:193], v[134:135], off
	global_load_dwordx4 v[194:197], v[134:135], off offset:16
	global_load_dwordx4 v[198:201], v[134:135], off offset:2048
	global_load_dwordx4 v[202:205], v[134:135], off offset:2064
	global_load_dwordx4 v[206:209], v[136:137], off
	global_load_dwordx4 v[210:213], v[136:137], off offset:16
	global_load_dwordx4 v[214:217], v[136:137], off offset:2048
	global_load_dwordx4 v[218:221], v[136:137], off offset:2064
	global_load_dwordx4 v[222:225], v[138:139], off
	global_load_dwordx4 v[226:229], v[138:139], off offset:16
	global_load_dwordx4 v[230:233], v[138:139], off offset:2048
	global_load_dwordx4 v[234:237], v[138:139], off offset:2064
	v_xor_b32_e32 v238, 16, v241
	v_xor_b32_e32 v239, 32, v241
	v_lshlrev_b32_e32 v238, 2, v238
	v_lshlrev_b32_e32 v239, 2, v239
	s_and_b64 vcc, exec, s[56:57]
	s_cbranch_vccnz .Lg0bar_p5
	s_setprio 1
	s_branch .LBB0_755
.Lg0bar_p5:
	s_barrier
; __device__ __forceinline__ float row_rstd(const float* ssp, int row, int fq) {
;     const f32x4 a = *(const f32x4*)(ssp + (size_t)row * 32 + 8 * fq), b = *(const f32x4*)(ssp + (size_t)row * 32 + 8 * fq + 4);
;     float s = ((a[0] + a[1]) + (a[2] + a[3])) + ((b[0] + b[1]) + (b[2] + b[3]));
;     s += __shfl_xor(s, 16); s += __shfl_xor(s, 32);
;     return __builtin_amdgcn_rsqf(s * (1.0f / 2048.0f) + 1e-6f);
; }
;     __device__ __forceinline__ void operator()(f32x4 (&acc)[2][2][4][2], const Unit& u, int wr, int wc, int fr, int fq) const {
;     ...
;             for (int m = 0; m < 4; ++m) { const float rstd = row_rstd(ss, row0 + ai * HALF + m * 16, fq);
; #pragma unroll
;                 for (int bj = 0; bj < 2; ++bj) { acc[ai][bj][m][0] *= rstd; acc[ai][bj][m][1] *= rstd; } }
; #pragma unroll
;         for (int n = 0; n < 2; ++n) {
;             const int j4 = u.pn * 128 + wc * 32 + 8 * fq + 4 * n;
;             f32x4 kc[2][3], bc[2];
; #pragma unroll
;             for (int bj = 0; bj < 2; ++bj) { bc[bj] = *(const f32x4*)(cb + bj * FF + j4);
; #pragma unroll
;                 for (int w = 0; w < 3; ++w) kc[bj][w] = *(const f32x4*)(ck + w * NUP + bj * FF + j4); }
.LBB0_755:
	s_waitcnt vmcnt(14)
	v_pk_add_f32 v[174:175], v[174:175], v[176:177]
	v_pk_add_f32 v[178:179], v[178:179], v[180:181]
	v_pk_add_f32 v[174:175], v[174:175], v[178:179]
	v_add_f32_e32 v130, v174, v175
	s_waitcnt vmcnt(12)
	v_pk_add_f32 v[182:183], v[182:183], v[184:185]
	v_pk_add_f32 v[186:187], v[186:187], v[188:189]
	v_pk_add_f32 v[182:183], v[182:183], v[186:187]
	v_add_f32_e32 v132, v182, v183
	s_waitcnt vmcnt(10)
	v_pk_add_f32 v[190:191], v[190:191], v[192:193]
	v_pk_add_f32 v[194:195], v[194:195], v[196:197]
	v_pk_add_f32 v[190:191], v[190:191], v[194:195]
	v_add_f32_e32 v134, v190, v191
	s_waitcnt vmcnt(8)
	v_pk_add_f32 v[198:199], v[198:199], v[200:201]
	v_pk_add_f32 v[202:203], v[202:203], v[204:205]
	v_pk_add_f32 v[198:199], v[198:199], v[202:203]
	v_add_f32_e32 v136, v198, v199
	s_waitcnt vmcnt(6)
	v_pk_add_f32 v[206:207], v[206:207], v[208:209]
	v_pk_add_f32 v[210:211], v[210:211], v[212:213]
	v_pk_add_f32 v[206:207], v[206:207], v[210:211]
	v_add_f32_e32 v138, v206, v207
	s_waitcnt vmcnt(4)
	v_pk_add_f32 v[214:215], v[214:215], v[216:217]
	v_pk_add_f32 v[218:219], v[218:219], v[220:221]
	v_pk_add_f32 v[214:215], v[214:215], v[218:219]
	v_add_f32_e32 v140, v214, v215
	s_waitcnt vmcnt(2)
	v_pk_add_f32 v[222:223], v[222:223], v[224:225]
	v_pk_add_f32 v[226:227], v[226:227], v[228:229]
	v_pk_add_f32 v[222:223], v[222:223], v[226:227]
	v_add_f32_e32 v142, v222, v223
	s_waitcnt vmcnt(0)
	v_pk_add_f32 v[230:231], v[230:231], v[232:233]
	v_pk_add_f32 v[234:235], v[234:235], v[236:237]
	v_pk_add_f32 v[230:231], v[230:231], v[234:235]
	v_add_f32_e32 v144, v230, v231
	v_lshl_or_b32 v242, s16, 7, v250
	v_lshlrev_b32_e32 v252, 1, v242
	v_lshlrev_b32_e32 v242, 2, v242
	v_add_u32_e32 v131, 0x5600, v242
	v_add_u32_e32 v133, 0xac00, v242
	v_add_u32_e32 v135, 0x10200, v242
	v_add_u32_e32 v137, 0x15800, v242
	v_add_u32_e32 v139, 0x1ae00, v242
	global_load_dwordx4 v[182:185], v242, s[18:19]
	global_load_dwordx4 v[186:189], v133, s[18:19]
	global_load_dwordx4 v[190:193], v137, s[18:19]
	global_load_dwordx4 v[194:197], v242, s[20:21]
	global_load_dwordx4 v[198:201], v131, s[18:19]
	global_load_dwordx4 v[202:205], v135, s[18:19]
	global_load_dwordx4 v[206:209], v139, s[18:19]
	global_load_dwordx4 v[210:213], v131, s[20:21]
	ds_bpermute_b32 v174, v238, v130
	ds_bpermute_b32 v175, v238, v132
	ds_bpermute_b32 v176, v238, v134
	ds_bpermute_b32 v177, v238, v136
	ds_bpermute_b32 v178, v238, v138
	ds_bpermute_b32 v179, v238, v140
	ds_bpermute_b32 v180, v238, v142
	ds_bpermute_b32 v181, v238, v144
	s_waitcnt lgkmcnt(0)
	v_add_f32_e32 v130, v130, v174
	v_add_f32_e32 v132, v132, v175
	v_add_f32_e32 v134, v134, v176
	v_add_f32_e32 v136, v136, v177
	v_add_f32_e32 v138, v138, v178
	v_add_f32_e32 v140, v140, v179
	v_add_f32_e32 v142, v142, v180
	v_add_f32_e32 v144, v144, v181
	ds_bpermute_b32 v174, v239, v130
	ds_bpermute_b32 v175, v239, v132
	ds_bpermute_b32 v176, v239, v134
	ds_bpermute_b32 v177, v239, v136
	ds_bpermute_b32 v178, v239, v138
	ds_bpermute_b32 v179, v239, v140
	ds_bpermute_b32 v180, v239, v142
	ds_bpermute_b32 v181, v239, v144
	s_waitcnt lgkmcnt(0)
	v_add_f32_e32 v130, v130, v174
	v_add_f32_e32 v132, v132, v175
	v_add_f32_e32 v134, v134, v176
	v_add_f32_e32 v136, v136, v177
	v_add_f32_e32 v138, v138, v178
	v_add_f32_e32 v140, v140, v179
	v_add_f32_e32 v142, v142, v180
	v_add_f32_e32 v144, v144, v181
	v_fmamk_f32 v130, v130, 0x3a000000, v243
	v_fmamk_f32 v132, v132, 0x3a000000, v243
	v_fmamk_f32 v134, v134, 0x3a000000, v243
	v_fmamk_f32 v136, v136, 0x3a000000, v243
	v_fmamk_f32 v138, v138, 0x3a000000, v243
	v_fmamk_f32 v140, v140, 0x3a000000, v243
	v_fmamk_f32 v142, v142, 0x3a000000, v243
	v_fmamk_f32 v144, v144, 0x3a000000, v243
	v_rsq_f32_e32 v130, v130
	v_rsq_f32_e32 v132, v132
	v_rsq_f32_e32 v134, v134
	v_rsq_f32_e32 v136, v136
	v_rsq_f32_e32 v138, v138
	v_rsq_f32_e32 v140, v140
	v_rsq_f32_e32 v142, v142
	v_rsq_f32_e32 v144, v144
	s_nop 0
	v_pk_mul_f32 v[126:127], v[126:127], v[130:131] op_sel_hi:[1,0]
	v_pk_mul_f32 v[128:129], v[128:129], v[130:131] op_sel_hi:[1,0]
	v_pk_mul_f32 v[62:63], v[62:63], v[130:131] op_sel_hi:[1,0]
	v_pk_mul_f32 v[64:65], v[64:65], v[130:131] op_sel_hi:[1,0]
	v_pk_mul_f32 v[122:123], v[122:123], v[130:131] op_sel_hi:[1,0]
	v_pk_mul_f32 v[124:125], v[124:125], v[130:131] op_sel_hi:[1,0]
	v_pk_mul_f32 v[54:55], v[54:55], v[130:131] op_sel_hi:[1,0]
	v_pk_mul_f32 v[56:57], v[56:57], v[130:131] op_sel_hi:[1,0]
	v_pk_mul_f32 v[118:119], v[118:119], v[132:133] op_sel_hi:[1,0]
	v_pk_mul_f32 v[120:121], v[120:121], v[132:133] op_sel_hi:[1,0]
	v_pk_mul_f32 v[58:59], v[58:59], v[132:133] op_sel_hi:[1,0]
	v_pk_mul_f32 v[60:61], v[60:61], v[132:133] op_sel_hi:[1,0]
	v_pk_mul_f32 v[114:115], v[114:115], v[132:133] op_sel_hi:[1,0]
	v_pk_mul_f32 v[116:117], v[116:117], v[132:133] op_sel_hi:[1,0]
	v_pk_mul_f32 v[50:51], v[50:51], v[132:133] op_sel_hi:[1,0]
	v_pk_mul_f32 v[52:53], v[52:53], v[132:133] op_sel_hi:[1,0]
	v_pk_mul_f32 v[110:111], v[110:111], v[134:135] op_sel_hi:[1,0]
	v_pk_mul_f32 v[112:113], v[112:113], v[134:135] op_sel_hi:[1,0]
	v_pk_mul_f32 v[46:47], v[46:47], v[134:135] op_sel_hi:[1,0]
	v_pk_mul_f32 v[48:49], v[48:49], v[134:135] op_sel_hi:[1,0]
	v_pk_mul_f32 v[102:103], v[102:103], v[134:135] op_sel_hi:[1,0]
	v_pk_mul_f32 v[104:105], v[104:105], v[134:135] op_sel_hi:[1,0]
	v_pk_mul_f32 v[38:39], v[38:39], v[134:135] op_sel_hi:[1,0]
	v_pk_mul_f32 v[40:41], v[40:41], v[134:135] op_sel_hi:[1,0]
	v_pk_mul_f32 v[106:107], v[106:107], v[136:137] op_sel_hi:[1,0]
	v_pk_mul_f32 v[108:109], v[108:109], v[136:137] op_sel_hi:[1,0]
	v_pk_mul_f32 v[42:43], v[42:43], v[136:137] op_sel_hi:[1,0]
; __device__ __forceinline__ float sigmoid_f(float x) { return fast_rcp(1.0f + fast_exp2(-1.4426950409f * x)); }
;     __device__ __forceinline__ void operator()(f32x4 (&acc)[2][2][4][2], const Unit& u, int wr, int wc, int fr, int fq) const {
;     ...
;                 for (int bj = 0; bj < 2; ++bj) { acc[ai][bj][m][0] *= rstd; acc[ai][bj][m][1] *= rstd; } }
; #pragma unroll
;         for (int n = 0; n < 2; ++n) {
;             const int j4 = u.pn * 128 + wc * 32 + 8 * fq + 4 * n;
;             f32x4 kc[2][3], bc[2];
; #pragma unroll
;             for (int bj = 0; bj < 2; ++bj) { bc[bj] = *(const f32x4*)(cb + bj * FF + j4);
; #pragma unroll
;                 for (int w = 0; w < 3; ++w) kc[bj][w] = *(const f32x4*)(ck + w * NUP + bj * FF + j4); }
; #pragma unroll
;             for (int ai = 0; ai < 2; ++ai) {
;                 const int grp = u.pm * 4 + ai * 2 + wr;
; #pragma unroll
;                 for (int m = 0; m < 4; ++m) {
;                     f32x4 cv[2];
; #pragma unroll
;                     for (int bj = 0; bj < 2; ++bj) {
;                         const f32x4 cur = acc[ai][bj][m][n], lo = acc[ai][bj][m > 0 ? m - 1 : 0][n], hi = acc[ai][bj][m < 3 ? m + 1 : 3][n];
;                         f32x4 pv, nv;
; #pragma unroll
;                         for (int idx = 0; idx < 4; ++idx) {
;                             const float y = (fr == 15) ? lo[idx] : cur[idx], z = (fr == 0) ? hi[idx] : cur[idx];
;                             pv[idx] = __int_as_float(__builtin_amdgcn_update_dpp(0, __float_as_int(y), 0x121, 0xf, 0xf, false));
;                             nv[idx] = __int_as_float(__builtin_amdgcn_update_dpp(0, __float_as_int(z), 0x12f, 0xf, 0xf, false));
;                         }
;                         cv[bj] = kc[bj][0] * pv + kc[bj][1] * cur + kc[bj][2] * nv + bc[bj];
;                     }
;                     const int row = row0 + ai * HALF + m * 16;
;                     const bool edge = (m == 0 && fr == 0) || (m == 3 && fr == 15);
;                     if (!edge) { const f32x4 gt = cv[0], vl = cv[1];
;                         u32x2 w; w.x = cvt_pk_bf16(gt[0] * sigmoid_f(gt[0]) * vl[0], gt[1] * sigmoid_f(gt[1]) * vl[1]); w.y = cvt_pk_bf16(gt[2] * sigmoid_f(gt[2]) * vl[2], gt[3] * sigmoid_f(gt[3]) * vl[3]);
;                         *(u32x2*)(ACT + (size_t)row * FF + j4) = w; }
;                     if (m == 0 && fr < 2) {
; #pragma unroll
	v_pk_mul_f32 v[44:45], v[44:45], v[136:137] op_sel_hi:[1,0]
	v_pk_mul_f32 v[98:99], v[98:99], v[136:137] op_sel_hi:[1,0]
	v_pk_mul_f32 v[100:101], v[100:101], v[136:137] op_sel_hi:[1,0]
	v_pk_mul_f32 v[34:35], v[34:35], v[136:137] op_sel_hi:[1,0]
	v_pk_mul_f32 v[36:37], v[36:37], v[136:137] op_sel_hi:[1,0]
	v_pk_mul_f32 v[94:95], v[94:95], v[138:139] op_sel_hi:[1,0]
	v_pk_mul_f32 v[96:97], v[96:97], v[138:139] op_sel_hi:[1,0]
	v_pk_mul_f32 v[30:31], v[30:31], v[138:139] op_sel_hi:[1,0]
	v_pk_mul_f32 v[32:33], v[32:33], v[138:139] op_sel_hi:[1,0]
	v_pk_mul_f32 v[86:87], v[86:87], v[138:139] op_sel_hi:[1,0]
	v_pk_mul_f32 v[88:89], v[88:89], v[138:139] op_sel_hi:[1,0]
	v_pk_mul_f32 v[22:23], v[22:23], v[138:139] op_sel_hi:[1,0]
	v_pk_mul_f32 v[24:25], v[24:25], v[138:139] op_sel_hi:[1,0]
	v_pk_mul_f32 v[90:91], v[90:91], v[140:141] op_sel_hi:[1,0]
	v_pk_mul_f32 v[92:93], v[92:93], v[140:141] op_sel_hi:[1,0]
	v_pk_mul_f32 v[26:27], v[26:27], v[140:141] op_sel_hi:[1,0]
	v_pk_mul_f32 v[28:29], v[28:29], v[140:141] op_sel_hi:[1,0]
	v_pk_mul_f32 v[82:83], v[82:83], v[140:141] op_sel_hi:[1,0]
	v_pk_mul_f32 v[84:85], v[84:85], v[140:141] op_sel_hi:[1,0]
	v_pk_mul_f32 v[18:19], v[18:19], v[140:141] op_sel_hi:[1,0]
	v_pk_mul_f32 v[20:21], v[20:21], v[140:141] op_sel_hi:[1,0]
	v_pk_mul_f32 v[78:79], v[78:79], v[142:143] op_sel_hi:[1,0]
	v_pk_mul_f32 v[80:81], v[80:81], v[142:143] op_sel_hi:[1,0]
	v_pk_mul_f32 v[14:15], v[14:15], v[142:143] op_sel_hi:[1,0]
	v_pk_mul_f32 v[16:17], v[16:17], v[142:143] op_sel_hi:[1,0]
	v_pk_mul_f32 v[70:71], v[70:71], v[142:143] op_sel_hi:[1,0]
	v_pk_mul_f32 v[72:73], v[72:73], v[142:143] op_sel_hi:[1,0]
	v_pk_mul_f32 v[6:7], v[6:7], v[142:143] op_sel_hi:[1,0]
	v_pk_mul_f32 v[8:9], v[8:9], v[142:143] op_sel_hi:[1,0]
	v_pk_mul_f32 v[74:75], v[74:75], v[144:145] op_sel_hi:[1,0]
	v_pk_mul_f32 v[76:77], v[76:77], v[144:145] op_sel_hi:[1,0]
	v_pk_mul_f32 v[10:11], v[10:11], v[144:145] op_sel_hi:[1,0]
	v_pk_mul_f32 v[12:13], v[12:13], v[144:145] op_sel_hi:[1,0]
	v_pk_mul_f32 v[66:67], v[66:67], v[144:145] op_sel_hi:[1,0]
	v_pk_mul_f32 v[68:69], v[68:69], v[144:145] op_sel_hi:[1,0]
	v_pk_mul_f32 v[2:3], v[2:3], v[144:145] op_sel_hi:[1,0]
	v_pk_mul_f32 v[4:5], v[4:5], v[144:145] op_sel_hi:[1,0]
	s_mov_b32 s34, 0xbfb8aa3b
	s_mov_b32 s35, 0xbfb8aa3b
	s_mov_b32 s36, 1.0
	s_mov_b32 s37, 1.0
	v_lshl_add_u32 v238, s12, 8, v247
	v_mul_u32_u24_e32 v238, 0x2b00, v238
	v_add_u32_e32 v238, v238, v252
	s_lshl_b32 s13, s12, 4
	s_add_i32 s13, s13, s92
	v_add_u32_e32 v253, s13, v246
	v_mul_u32_u24_e32 v253, 0x5600, v253
	v_add_u32_e32 v253, v253, v252
	v_add_u32_e32 v239, 0x2b00, v253
	v_cvt_pk_bf16_f32 v230, v126, v127
	v_cvt_pk_bf16_f32 v231, v128, v129
	v_cvt_pk_bf16_f32 v232, v62, v63
	v_cvt_pk_bf16_f32 v233, v64, v65
	s_and_saveexec_b64 s[16:17], s[46:47]
	global_store_dwordx4 v253, v[230:233], s[54:55]
	s_or_b64 exec, exec, s[16:17]
	v_cvt_pk_bf16_f32 v234, v122, v123
	v_cvt_pk_bf16_f32 v235, v124, v125
	v_cvt_pk_bf16_f32 v236, v54, v55
	v_cvt_pk_bf16_f32 v237, v56, v57
	s_and_saveexec_b64 s[16:17], s[46:47]
	global_store_dwordx4 v239, v[234:237], s[54:55]
	s_or_b64 exec, exec, s[16:17]
	v_add_u32_e32 v253, s13, v246
	v_add_u32_e32 v253, 8, v253
	v_mul_u32_u24_e32 v253, 0x5600, v253
	v_add_u32_e32 v253, v253, v252
	v_add_u32_e32 v239, 0x2b00, v253
	v_cvt_pk_bf16_f32 v214, v94, v95
	v_cvt_pk_bf16_f32 v215, v96, v97
	v_cvt_pk_bf16_f32 v216, v30, v31
	v_cvt_pk_bf16_f32 v217, v32, v33
	s_and_saveexec_b64 s[16:17], s[46:47]
	global_store_dwordx4 v253, v[214:217], s[54:55]
	s_or_b64 exec, exec, s[16:17]
	v_cvt_pk_bf16_f32 v218, v86, v87
	v_cvt_pk_bf16_f32 v219, v88, v89
	v_cvt_pk_bf16_f32 v220, v22, v23
	v_cvt_pk_bf16_f32 v221, v24, v25
	s_and_saveexec_b64 s[16:17], s[46:47]
	global_store_dwordx4 v239, v[218:221], s[54:55]
	s_or_b64 exec, exec, s[16:17]
	v_add_u32_e32 v253, s13, v249
	v_mul_u32_u24_e32 v253, 0x5600, v253
	v_add_u32_e32 v253, v253, v252
	v_add_u32_e32 v239, 0x2b00, v253
	v_cvt_pk_bf16_f32 v230, v106, v107
	v_cvt_pk_bf16_f32 v231, v108, v109
	v_cvt_pk_bf16_f32 v232, v42, v43
	v_cvt_pk_bf16_f32 v233, v44, v45
	s_and_saveexec_b64 s[16:17], s[48:49]
	global_store_dwordx4 v253, v[230:233], s[54:55]
	s_or_b64 exec, exec, s[16:17]
	v_cvt_pk_bf16_f32 v234, v98, v99
	v_cvt_pk_bf16_f32 v235, v100, v101
	v_cvt_pk_bf16_f32 v236, v34, v35
	v_cvt_pk_bf16_f32 v237, v36, v37
	s_and_saveexec_b64 s[16:17], s[48:49]
	global_store_dwordx4 v239, v[234:237], s[54:55]
	s_or_b64 exec, exec, s[16:17]
	v_add_u32_e32 v253, s13, v249
	v_add_u32_e32 v253, 8, v253
	v_mul_u32_u24_e32 v253, 0x5600, v253
	v_add_u32_e32 v253, v253, v252
	v_add_u32_e32 v239, 0x2b00, v253
	v_cvt_pk_bf16_f32 v214, v74, v75
	v_cvt_pk_bf16_f32 v215, v76, v77
	v_cvt_pk_bf16_f32 v216, v10, v11
	v_cvt_pk_bf16_f32 v217, v12, v13
	s_and_saveexec_b64 s[16:17], s[48:49]
	global_store_dwordx4 v253, v[214:217], s[54:55]
	s_or_b64 exec, exec, s[16:17]
	v_cvt_pk_bf16_f32 v218, v66, v67
	v_cvt_pk_bf16_f32 v219, v68, v69
	v_cvt_pk_bf16_f32 v220, v2, v3
	v_cvt_pk_bf16_f32 v221, v4, v5
	s_and_saveexec_b64 s[16:17], s[48:49]
	global_store_dwordx4 v239, v[218:221], s[54:55]
	s_or_b64 exec, exec, s[16:17]
	s_waitcnt vmcnt(8)
; __device__ __forceinline__ unsigned cvt_pk_bf16(float lo, float hi) { unsigned r; asm volatile("v_cvt_pk_bf16_f32 %0, %1, %2" : "=v"(r) : "v"(lo), "v"(hi)); return r; }
; __device__ __forceinline__ float sigmoid_f(float x) { return fast_rcp(1.0f + fast_exp2(-1.4426950409f * x)); }
;     __device__ __forceinline__ void operator()(f32x4 (&acc)[2][2][4][2], const Unit& u, int wr, int wc, int fr, int fq) const {
;     ...
;             for (int ai = 0; ai < 2; ++ai) {
;                 const int grp = u.pm * 4 + ai * 2 + wr;
; #pragma unroll
;                 for (int m = 0; m < 4; ++m) {
;                     f32x4 cv[2];
; #pragma unroll
;                     for (int bj = 0; bj < 2; ++bj) {
;                         const f32x4 cur = acc[ai][bj][m][n], lo = acc[ai][bj][m > 0 ? m - 1 : 0][n], hi = acc[ai][bj][m < 3 ? m + 1 : 3][n];
;                         f32x4 pv, nv;
; #pragma unroll
;                         for (int idx = 0; idx < 4; ++idx) {
;                             const float y = (fr == 15) ? lo[idx] : cur[idx], z = (fr == 0) ? hi[idx] : cur[idx];
;                             pv[idx] = __int_as_float(__builtin_amdgcn_update_dpp(0, __float_as_int(y), 0x121, 0xf, 0xf, false));
;                             nv[idx] = __int_as_float(__builtin_amdgcn_update_dpp(0, __float_as_int(z), 0x12f, 0xf, 0xf, false));
;                         }
;                         cv[bj] = kc[bj][0] * pv + kc[bj][1] * cur + kc[bj][2] * nv + bc[bj];
;                     }
;                     const int row = row0 + ai * HALF + m * 16;
;                     const bool edge = (m == 0 && fr == 0) || (m == 3 && fr == 15);
;                     if (!edge) { const f32x4 gt = cv[0], vl = cv[1];
;                         u32x2 w; w.x = cvt_pk_bf16(gt[0] * sigmoid_f(gt[0]) * vl[0], gt[1] * sigmoid_f(gt[1]) * vl[1]); w.y = cvt_pk_bf16(gt[2] * sigmoid_f(gt[2]) * vl[2], gt[3] * sigmoid_f(gt[3]) * vl[3]);
	v_cndmask_b32_e64 v214, 0, v182, s[42:43]
	v_cndmask_b32_e64 v215, 0, v183, s[42:43]
	v_cndmask_b32_e64 v216, 0, v184, s[42:43]
	v_cndmask_b32_e64 v217, 0, v185, s[42:43]
	v_cndmask_b32_e64 v218, 0, v198, s[42:43]
	v_cndmask_b32_e64 v219, 0, v199, s[42:43]
	v_cndmask_b32_e64 v220, 0, v200, s[42:43]
	v_cndmask_b32_e64 v221, 0, v201, s[42:43]
	v_cndmask_b32_e64 v222, 0, v190, s[38:39]
	v_cndmask_b32_e64 v223, 0, v191, s[38:39]
	v_cndmask_b32_e64 v224, 0, v192, s[38:39]
	v_cndmask_b32_e64 v225, 0, v193, s[38:39]
	v_cndmask_b32_e64 v226, 0, v206, s[38:39]
	v_cndmask_b32_e64 v227, 0, v207, s[38:39]
	v_cndmask_b32_e64 v228, 0, v208, s[38:39]
	v_cndmask_b32_e64 v229, 0, v209, s[38:39]
	v_pk_fma_f32 v[230:231], v[126:127], v[186:187], v[194:195]
	v_pk_fma_f32 v[232:233], v[128:129], v[188:189], v[196:197]
	v_pk_fma_f32 v[234:235], v[122:123], v[202:203], v[210:211]
	v_pk_fma_f32 v[236:237], v[124:125], v[204:205], v[212:213]
	v_fmac_f32_dpp v230, v126, v182 row_shr:1 row_mask:0xf bank_mask:0xf
	v_fmac_f32_dpp v231, v127, v183 row_shr:1 row_mask:0xf bank_mask:0xf
	v_fmac_f32_dpp v232, v128, v184 row_shr:1 row_mask:0xf bank_mask:0xf
	v_fmac_f32_dpp v233, v129, v185 row_shr:1 row_mask:0xf bank_mask:0xf
	v_fmac_f32_dpp v234, v122, v198 row_shr:1 row_mask:0xf bank_mask:0xf
	v_fmac_f32_dpp v235, v123, v199 row_shr:1 row_mask:0xf bank_mask:0xf
	v_fmac_f32_dpp v236, v124, v200 row_shr:1 row_mask:0xf bank_mask:0xf
	v_fmac_f32_dpp v237, v125, v201 row_shr:1 row_mask:0xf bank_mask:0xf
	v_fmac_f32_dpp v230, v126, v190 row_shl:1 row_mask:0xf bank_mask:0xf
	v_fmac_f32_dpp v231, v127, v191 row_shl:1 row_mask:0xf bank_mask:0xf
	v_fmac_f32_dpp v232, v128, v192 row_shl:1 row_mask:0xf bank_mask:0xf
	v_fmac_f32_dpp v233, v129, v193 row_shl:1 row_mask:0xf bank_mask:0xf
	v_fmac_f32_dpp v234, v122, v206 row_shl:1 row_mask:0xf bank_mask:0xf
	v_fmac_f32_dpp v235, v123, v207 row_shl:1 row_mask:0xf bank_mask:0xf
	v_fmac_f32_dpp v236, v124, v208 row_shl:1 row_mask:0xf bank_mask:0xf
	v_fmac_f32_dpp v237, v125, v209 row_shl:1 row_mask:0xf bank_mask:0xf
	v_fmac_f32_dpp v230, v118, v222 row_ror:15 row_mask:0xf bank_mask:0xf
	v_fmac_f32_dpp v231, v119, v223 row_ror:15 row_mask:0xf bank_mask:0xf
	v_fmac_f32_dpp v232, v120, v224 row_ror:15 row_mask:0xf bank_mask:0xf
	v_fmac_f32_dpp v233, v121, v225 row_ror:15 row_mask:0xf bank_mask:0xf
	v_fmac_f32_dpp v234, v114, v226 row_ror:15 row_mask:0xf bank_mask:0xf
	v_fmac_f32_dpp v235, v115, v227 row_ror:15 row_mask:0xf bank_mask:0xf
	v_fmac_f32_dpp v236, v116, v228 row_ror:15 row_mask:0xf bank_mask:0xf
	v_fmac_f32_dpp v237, v117, v229 row_ror:15 row_mask:0xf bank_mask:0xf
	v_pk_mul_f32 v[174:175], v[230:231], s[34:35]
	v_pk_mul_f32 v[176:177], v[232:233], s[34:35]
	v_exp_f32_e32 v174, v174
	v_exp_f32_e32 v175, v175
	v_exp_f32_e32 v176, v176
	v_exp_f32_e32 v177, v177
	v_pk_add_f32 v[174:175], v[174:175], s[36:37]
	v_pk_add_f32 v[176:177], v[176:177], s[36:37]
	v_rcp_f32_e32 v174, v174
	v_rcp_f32_e32 v175, v175
	v_rcp_f32_e32 v176, v176
	v_rcp_f32_e32 v177, v177
	v_pk_mul_f32 v[174:175], v[230:231], v[174:175]
	v_pk_mul_f32 v[176:177], v[232:233], v[176:177]
	v_pk_mul_f32 v[174:175], v[174:175], v[234:235]
	v_pk_mul_f32 v[176:177], v[176:177], v[236:237]
	v_cvt_pk_bf16_f32 v130, v174, v175
	v_cvt_pk_bf16_f32 v131, v176, v177
	v_pk_fma_f32 v[230:231], v[118:119], v[186:187], v[194:195]
	v_pk_fma_f32 v[232:233], v[120:121], v[188:189], v[196:197]
	v_pk_fma_f32 v[234:235], v[114:115], v[202:203], v[210:211]
	v_pk_fma_f32 v[236:237], v[116:117], v[204:205], v[212:213]
	v_fmac_f32_dpp v230, v118, v182 row_shr:1 row_mask:0xf bank_mask:0xf
	v_fmac_f32_dpp v231, v119, v183 row_shr:1 row_mask:0xf bank_mask:0xf
	v_fmac_f32_dpp v232, v120, v184 row_shr:1 row_mask:0xf bank_mask:0xf
	v_fmac_f32_dpp v233, v121, v185 row_shr:1 row_mask:0xf bank_mask:0xf
	v_fmac_f32_dpp v234, v114, v198 row_shr:1 row_mask:0xf bank_mask:0xf
	v_fmac_f32_dpp v235, v115, v199 row_shr:1 row_mask:0xf bank_mask:0xf
	v_fmac_f32_dpp v236, v116, v200 row_shr:1 row_mask:0xf bank_mask:0xf
	v_fmac_f32_dpp v237, v117, v201 row_shr:1 row_mask:0xf bank_mask:0xf
	v_fmac_f32_dpp v230, v118, v190 row_shl:1 row_mask:0xf bank_mask:0xf
	v_fmac_f32_dpp v231, v119, v191 row_shl:1 row_mask:0xf bank_mask:0xf
	v_fmac_f32_dpp v232, v120, v192 row_shl:1 row_mask:0xf bank_mask:0xf
	v_fmac_f32_dpp v233, v121, v193 row_shl:1 row_mask:0xf bank_mask:0xf
	v_fmac_f32_dpp v234, v114, v206 row_shl:1 row_mask:0xf bank_mask:0xf
	v_fmac_f32_dpp v235, v115, v207 row_shl:1 row_mask:0xf bank_mask:0xf
	v_fmac_f32_dpp v236, v116, v208 row_shl:1 row_mask:0xf bank_mask:0xf
	v_fmac_f32_dpp v237, v117, v209 row_shl:1 row_mask:0xf bank_mask:0xf
	v_fmac_f32_dpp v230, v126, v214 row_ror:1 row_mask:0xf bank_mask:0xf
	v_fmac_f32_dpp v231, v127, v215 row_ror:1 row_mask:0xf bank_mask:0xf
	v_fmac_f32_dpp v232, v128, v216 row_ror:1 row_mask:0xf bank_mask:0xf
	v_fmac_f32_dpp v233, v129, v217 row_ror:1 row_mask:0xf bank_mask:0xf
	v_fmac_f32_dpp v234, v122, v218 row_ror:1 row_mask:0xf bank_mask:0xf
	v_fmac_f32_dpp v235, v123, v219 row_ror:1 row_mask:0xf bank_mask:0xf
	v_fmac_f32_dpp v236, v124, v220 row_ror:1 row_mask:0xf bank_mask:0xf
	v_fmac_f32_dpp v237, v125, v221 row_ror:1 row_mask:0xf bank_mask:0xf
	v_fmac_f32_dpp v230, v110, v222 row_ror:15 row_mask:0xf bank_mask:0xf
	v_fmac_f32_dpp v231, v111, v223 row_ror:15 row_mask:0xf bank_mask:0xf
	v_fmac_f32_dpp v232, v112, v224 row_ror:15 row_mask:0xf bank_mask:0xf
	v_fmac_f32_dpp v233, v113, v225 row_ror:15 row_mask:0xf bank_mask:0xf
	v_fmac_f32_dpp v234, v102, v226 row_ror:15 row_mask:0xf bank_mask:0xf
	v_fmac_f32_dpp v235, v103, v227 row_ror:15 row_mask:0xf bank_mask:0xf
; __device__ __forceinline__ unsigned cvt_pk_bf16(float lo, float hi) { unsigned r; asm volatile("v_cvt_pk_bf16_f32 %0, %1, %2" : "=v"(r) : "v"(lo), "v"(hi)); return r; }
; __device__ __forceinline__ float sigmoid_f(float x) { return fast_rcp(1.0f + fast_exp2(-1.4426950409f * x)); }
;     __device__ __forceinline__ void operator()(f32x4 (&acc)[2][2][4][2], const Unit& u, int wr, int wc, int fr, int fq) const {
;     ...
;             for (int ai = 0; ai < 2; ++ai) {
;                 const int grp = u.pm * 4 + ai * 2 + wr;
; #pragma unroll
;                 for (int m = 0; m < 4; ++m) {
;                     f32x4 cv[2];
; #pragma unroll
;                     for (int bj = 0; bj < 2; ++bj) {
;                         const f32x4 cur = acc[ai][bj][m][n], lo = acc[ai][bj][m > 0 ? m - 1 : 0][n], hi = acc[ai][bj][m < 3 ? m + 1 : 3][n];
;                         f32x4 pv, nv;
; #pragma unroll
;                         for (int idx = 0; idx < 4; ++idx) {
;                             const float y = (fr == 15) ? lo[idx] : cur[idx], z = (fr == 0) ? hi[idx] : cur[idx];
;                             pv[idx] = __int_as_float(__builtin_amdgcn_update_dpp(0, __float_as_int(y), 0x121, 0xf, 0xf, false));
;                             nv[idx] = __int_as_float(__builtin_amdgcn_update_dpp(0, __float_as_int(z), 0x12f, 0xf, 0xf, false));
;                         }
;                         cv[bj] = kc[bj][0] * pv + kc[bj][1] * cur + kc[bj][2] * nv + bc[bj];
;                     }
;                     const int row = row0 + ai * HALF + m * 16;
;                     const bool edge = (m == 0 && fr == 0) || (m == 3 && fr == 15);
;                     if (!edge) { const f32x4 gt = cv[0], vl = cv[1];
;                         u32x2 w; w.x = cvt_pk_bf16(gt[0] * sigmoid_f(gt[0]) * vl[0], gt[1] * sigmoid_f(gt[1]) * vl[1]); w.y = cvt_pk_bf16(gt[2] * sigmoid_f(gt[2]) * vl[2], gt[3] * sigmoid_f(gt[3]) * vl[3]);
	v_fmac_f32_dpp v236, v104, v228 row_ror:15 row_mask:0xf bank_mask:0xf
	v_fmac_f32_dpp v237, v105, v229 row_ror:15 row_mask:0xf bank_mask:0xf
	v_pk_mul_f32 v[174:175], v[230:231], s[34:35]
	v_pk_mul_f32 v[176:177], v[232:233], s[34:35]
	v_exp_f32_e32 v174, v174
	v_exp_f32_e32 v175, v175
	v_exp_f32_e32 v176, v176
	v_exp_f32_e32 v177, v177
	v_pk_add_f32 v[174:175], v[174:175], s[36:37]
	v_pk_add_f32 v[176:177], v[176:177], s[36:37]
	v_rcp_f32_e32 v174, v174
	v_rcp_f32_e32 v175, v175
	v_rcp_f32_e32 v176, v176
	v_rcp_f32_e32 v177, v177
	v_pk_mul_f32 v[174:175], v[230:231], v[174:175]
	v_pk_mul_f32 v[176:177], v[232:233], v[176:177]
	v_pk_mul_f32 v[174:175], v[174:175], v[234:235]
	v_pk_mul_f32 v[176:177], v[176:177], v[236:237]
	v_cvt_pk_bf16_f32 v134, v174, v175
	v_cvt_pk_bf16_f32 v135, v176, v177
	v_pk_fma_f32 v[230:231], v[110:111], v[186:187], v[194:195]
	v_pk_fma_f32 v[232:233], v[112:113], v[188:189], v[196:197]
	v_pk_fma_f32 v[234:235], v[102:103], v[202:203], v[210:211]
	v_pk_fma_f32 v[236:237], v[104:105], v[204:205], v[212:213]
	v_fmac_f32_dpp v230, v110, v182 row_shr:1 row_mask:0xf bank_mask:0xf
	v_fmac_f32_dpp v231, v111, v183 row_shr:1 row_mask:0xf bank_mask:0xf
	v_fmac_f32_dpp v232, v112, v184 row_shr:1 row_mask:0xf bank_mask:0xf
	v_fmac_f32_dpp v233, v113, v185 row_shr:1 row_mask:0xf bank_mask:0xf
	v_fmac_f32_dpp v234, v102, v198 row_shr:1 row_mask:0xf bank_mask:0xf
	v_fmac_f32_dpp v235, v103, v199 row_shr:1 row_mask:0xf bank_mask:0xf
	v_fmac_f32_dpp v236, v104, v200 row_shr:1 row_mask:0xf bank_mask:0xf
	v_fmac_f32_dpp v237, v105, v201 row_shr:1 row_mask:0xf bank_mask:0xf
	v_fmac_f32_dpp v230, v110, v190 row_shl:1 row_mask:0xf bank_mask:0xf
	v_fmac_f32_dpp v231, v111, v191 row_shl:1 row_mask:0xf bank_mask:0xf
	v_fmac_f32_dpp v232, v112, v192 row_shl:1 row_mask:0xf bank_mask:0xf
	v_fmac_f32_dpp v233, v113, v193 row_shl:1 row_mask:0xf bank_mask:0xf
	v_fmac_f32_dpp v234, v102, v206 row_shl:1 row_mask:0xf bank_mask:0xf
	v_fmac_f32_dpp v235, v103, v207 row_shl:1 row_mask:0xf bank_mask:0xf
	v_fmac_f32_dpp v236, v104, v208 row_shl:1 row_mask:0xf bank_mask:0xf
	v_fmac_f32_dpp v237, v105, v209 row_shl:1 row_mask:0xf bank_mask:0xf
	v_fmac_f32_dpp v230, v118, v214 row_ror:1 row_mask:0xf bank_mask:0xf
	v_fmac_f32_dpp v231, v119, v215 row_ror:1 row_mask:0xf bank_mask:0xf
	v_fmac_f32_dpp v232, v120, v216 row_ror:1 row_mask:0xf bank_mask:0xf
	v_fmac_f32_dpp v233, v121, v217 row_ror:1 row_mask:0xf bank_mask:0xf
	v_fmac_f32_dpp v234, v114, v218 row_ror:1 row_mask:0xf bank_mask:0xf
	v_fmac_f32_dpp v235, v115, v219 row_ror:1 row_mask:0xf bank_mask:0xf
	v_fmac_f32_dpp v236, v116, v220 row_ror:1 row_mask:0xf bank_mask:0xf
	v_fmac_f32_dpp v237, v117, v221 row_ror:1 row_mask:0xf bank_mask:0xf
	v_fmac_f32_dpp v230, v106, v222 row_ror:15 row_mask:0xf bank_mask:0xf
	v_fmac_f32_dpp v231, v107, v223 row_ror:15 row_mask:0xf bank_mask:0xf
	v_fmac_f32_dpp v232, v108, v224 row_ror:15 row_mask:0xf bank_mask:0xf
	v_fmac_f32_dpp v233, v109, v225 row_ror:15 row_mask:0xf bank_mask:0xf
	v_fmac_f32_dpp v234, v98, v226 row_ror:15 row_mask:0xf bank_mask:0xf
	v_fmac_f32_dpp v235, v99, v227 row_ror:15 row_mask:0xf bank_mask:0xf
	v_fmac_f32_dpp v236, v100, v228 row_ror:15 row_mask:0xf bank_mask:0xf
	v_fmac_f32_dpp v237, v101, v229 row_ror:15 row_mask:0xf bank_mask:0xf
	v_pk_mul_f32 v[174:175], v[230:231], s[34:35]
	v_pk_mul_f32 v[176:177], v[232:233], s[34:35]
	v_exp_f32_e32 v174, v174
	v_exp_f32_e32 v175, v175
	v_exp_f32_e32 v176, v176
	v_exp_f32_e32 v177, v177
	v_pk_add_f32 v[174:175], v[174:175], s[36:37]
	v_pk_add_f32 v[176:177], v[176:177], s[36:37]
	v_rcp_f32_e32 v174, v174
	v_rcp_f32_e32 v175, v175
	v_rcp_f32_e32 v176, v176
	v_rcp_f32_e32 v177, v177
	v_pk_mul_f32 v[174:175], v[230:231], v[174:175]
	v_pk_mul_f32 v[176:177], v[232:233], v[176:177]
	v_pk_mul_f32 v[174:175], v[174:175], v[234:235]
	v_pk_mul_f32 v[176:177], v[176:177], v[236:237]
	v_cvt_pk_bf16_f32 v138, v174, v175
	v_cvt_pk_bf16_f32 v139, v176, v177
	v_pk_fma_f32 v[230:231], v[106:107], v[186:187], v[194:195]
	v_pk_fma_f32 v[232:233], v[108:109], v[188:189], v[196:197]
	v_pk_fma_f32 v[234:235], v[98:99], v[202:203], v[210:211]
	v_pk_fma_f32 v[236:237], v[100:101], v[204:205], v[212:213]
	v_fmac_f32_dpp v230, v106, v182 row_shr:1 row_mask:0xf bank_mask:0xf
	v_fmac_f32_dpp v231, v107, v183 row_shr:1 row_mask:0xf bank_mask:0xf
	v_fmac_f32_dpp v232, v108, v184 row_shr:1 row_mask:0xf bank_mask:0xf
	v_fmac_f32_dpp v233, v109, v185 row_shr:1 row_mask:0xf bank_mask:0xf
	v_fmac_f32_dpp v234, v98, v198 row_shr:1 row_mask:0xf bank_mask:0xf
	v_fmac_f32_dpp v235, v99, v199 row_shr:1 row_mask:0xf bank_mask:0xf
	v_fmac_f32_dpp v236, v100, v200 row_shr:1 row_mask:0xf bank_mask:0xf
	v_fmac_f32_dpp v237, v101, v201 row_shr:1 row_mask:0xf bank_mask:0xf
	v_fmac_f32_dpp v230, v106, v190 row_shl:1 row_mask:0xf bank_mask:0xf
	v_fmac_f32_dpp v231, v107, v191 row_shl:1 row_mask:0xf bank_mask:0xf
	v_fmac_f32_dpp v232, v108, v192 row_shl:1 row_mask:0xf bank_mask:0xf
	v_fmac_f32_dpp v233, v109, v193 row_shl:1 row_mask:0xf bank_mask:0xf
	v_fmac_f32_dpp v234, v98, v206 row_shl:1 row_mask:0xf bank_mask:0xf
	v_fmac_f32_dpp v235, v99, v207 row_shl:1 row_mask:0xf bank_mask:0xf
	v_fmac_f32_dpp v236, v100, v208 row_shl:1 row_mask:0xf bank_mask:0xf
	v_fmac_f32_dpp v237, v101, v209 row_shl:1 row_mask:0xf bank_mask:0xf
	v_fmac_f32_dpp v230, v110, v214 row_ror:1 row_mask:0xf bank_mask:0xf
	v_fmac_f32_dpp v231, v111, v215 row_ror:1 row_mask:0xf bank_mask:0xf
	v_fmac_f32_dpp v232, v112, v216 row_ror:1 row_mask:0xf bank_mask:0xf
	v_fmac_f32_dpp v233, v113, v217 row_ror:1 row_mask:0xf bank_mask:0xf
	v_fmac_f32_dpp v234, v102, v218 row_ror:1 row_mask:0xf bank_mask:0xf
; __device__ __forceinline__ unsigned cvt_pk_bf16(float lo, float hi) { unsigned r; asm volatile("v_cvt_pk_bf16_f32 %0, %1, %2" : "=v"(r) : "v"(lo), "v"(hi)); return r; }
; __device__ __forceinline__ float sigmoid_f(float x) { return fast_rcp(1.0f + fast_exp2(-1.4426950409f * x)); }
;     __device__ __forceinline__ void operator()(f32x4 (&acc)[2][2][4][2], const Unit& u, int wr, int wc, int fr, int fq) const {
;     ...
;             for (int bj = 0; bj < 2; ++bj) { bc[bj] = *(const f32x4*)(cb + bj * FF + j4);
; #pragma unroll
;                 for (int w = 0; w < 3; ++w) kc[bj][w] = *(const f32x4*)(ck + w * NUP + bj * FF + j4); }
; #pragma unroll
;             for (int ai = 0; ai < 2; ++ai) {
;                 const int grp = u.pm * 4 + ai * 2 + wr;
; #pragma unroll
;                 for (int m = 0; m < 4; ++m) {
;                     f32x4 cv[2];
; #pragma unroll
;                     for (int bj = 0; bj < 2; ++bj) {
;                         const f32x4 cur = acc[ai][bj][m][n], lo = acc[ai][bj][m > 0 ? m - 1 : 0][n], hi = acc[ai][bj][m < 3 ? m + 1 : 3][n];
;                         f32x4 pv, nv;
; #pragma unroll
;                         for (int idx = 0; idx < 4; ++idx) {
;                             const float y = (fr == 15) ? lo[idx] : cur[idx], z = (fr == 0) ? hi[idx] : cur[idx];
;                             pv[idx] = __int_as_float(__builtin_amdgcn_update_dpp(0, __float_as_int(y), 0x121, 0xf, 0xf, false));
;                             nv[idx] = __int_as_float(__builtin_amdgcn_update_dpp(0, __float_as_int(z), 0x12f, 0xf, 0xf, false));
;                         }
;                         cv[bj] = kc[bj][0] * pv + kc[bj][1] * cur + kc[bj][2] * nv + bc[bj];
;                     }
;                     const int row = row0 + ai * HALF + m * 16;
;                     const bool edge = (m == 0 && fr == 0) || (m == 3 && fr == 15);
;                     if (!edge) { const f32x4 gt = cv[0], vl = cv[1];
;                         u32x2 w; w.x = cvt_pk_bf16(gt[0] * sigmoid_f(gt[0]) * vl[0], gt[1] * sigmoid_f(gt[1]) * vl[1]); w.y = cvt_pk_bf16(gt[2] * sigmoid_f(gt[2]) * vl[2], gt[3] * sigmoid_f(gt[3]) * vl[3]);
	v_fmac_f32_dpp v235, v103, v219 row_ror:1 row_mask:0xf bank_mask:0xf
	v_fmac_f32_dpp v236, v104, v220 row_ror:1 row_mask:0xf bank_mask:0xf
	v_fmac_f32_dpp v237, v105, v221 row_ror:1 row_mask:0xf bank_mask:0xf
	v_pk_mul_f32 v[174:175], v[230:231], s[34:35]
	v_pk_mul_f32 v[176:177], v[232:233], s[34:35]
	v_exp_f32_e32 v174, v174
	v_exp_f32_e32 v175, v175
	v_exp_f32_e32 v176, v176
	v_exp_f32_e32 v177, v177
	v_pk_add_f32 v[174:175], v[174:175], s[36:37]
	v_pk_add_f32 v[176:177], v[176:177], s[36:37]
	v_rcp_f32_e32 v174, v174
	v_rcp_f32_e32 v175, v175
	v_rcp_f32_e32 v176, v176
	v_rcp_f32_e32 v177, v177
	v_pk_mul_f32 v[174:175], v[230:231], v[174:175]
	v_pk_mul_f32 v[176:177], v[232:233], v[176:177]
	v_pk_mul_f32 v[174:175], v[174:175], v[234:235]
	v_pk_mul_f32 v[176:177], v[176:177], v[236:237]
	v_cvt_pk_bf16_f32 v142, v174, v175
	v_cvt_pk_bf16_f32 v143, v176, v177
	v_add_u32_e32 v174, 0x5600, v242
	v_add_u32_e32 v175, 0xac00, v242
	v_add_u32_e32 v176, 0x10200, v242
	v_add_u32_e32 v177, 0x15800, v242
	v_add_u32_e32 v239, 0x1ae00, v242
	global_load_dwordx4 v[126:129], v242, s[18:19] offset:16
	global_load_dwordx4 v[118:121], v175, s[18:19] offset:16
	global_load_dwordx4 v[110:113], v177, s[18:19] offset:16
	global_load_dwordx4 v[106:109], v242, s[20:21] offset:16
	global_load_dwordx4 v[122:125], v174, s[18:19] offset:16
	global_load_dwordx4 v[114:117], v176, s[18:19] offset:16
	global_load_dwordx4 v[102:105], v239, s[18:19] offset:16
	global_load_dwordx4 v[98:101], v174, s[20:21] offset:16
	v_pk_fma_f32 v[230:231], v[94:95], v[186:187], v[194:195]
	v_pk_fma_f32 v[232:233], v[96:97], v[188:189], v[196:197]
	v_pk_fma_f32 v[234:235], v[86:87], v[202:203], v[210:211]
	v_pk_fma_f32 v[236:237], v[88:89], v[204:205], v[212:213]
	v_fmac_f32_dpp v230, v94, v182 row_shr:1 row_mask:0xf bank_mask:0xf
	v_fmac_f32_dpp v231, v95, v183 row_shr:1 row_mask:0xf bank_mask:0xf
	v_fmac_f32_dpp v232, v96, v184 row_shr:1 row_mask:0xf bank_mask:0xf
	v_fmac_f32_dpp v233, v97, v185 row_shr:1 row_mask:0xf bank_mask:0xf
	v_fmac_f32_dpp v234, v86, v198 row_shr:1 row_mask:0xf bank_mask:0xf
	v_fmac_f32_dpp v235, v87, v199 row_shr:1 row_mask:0xf bank_mask:0xf
	v_fmac_f32_dpp v236, v88, v200 row_shr:1 row_mask:0xf bank_mask:0xf
	v_fmac_f32_dpp v237, v89, v201 row_shr:1 row_mask:0xf bank_mask:0xf
	v_fmac_f32_dpp v230, v94, v190 row_shl:1 row_mask:0xf bank_mask:0xf
	v_fmac_f32_dpp v231, v95, v191 row_shl:1 row_mask:0xf bank_mask:0xf
	v_fmac_f32_dpp v232, v96, v192 row_shl:1 row_mask:0xf bank_mask:0xf
	v_fmac_f32_dpp v233, v97, v193 row_shl:1 row_mask:0xf bank_mask:0xf
	v_fmac_f32_dpp v234, v86, v206 row_shl:1 row_mask:0xf bank_mask:0xf
	v_fmac_f32_dpp v235, v87, v207 row_shl:1 row_mask:0xf bank_mask:0xf
	v_fmac_f32_dpp v236, v88, v208 row_shl:1 row_mask:0xf bank_mask:0xf
	v_fmac_f32_dpp v237, v89, v209 row_shl:1 row_mask:0xf bank_mask:0xf
	v_fmac_f32_dpp v230, v90, v222 row_ror:15 row_mask:0xf bank_mask:0xf
	v_fmac_f32_dpp v231, v91, v223 row_ror:15 row_mask:0xf bank_mask:0xf
	v_fmac_f32_dpp v232, v92, v224 row_ror:15 row_mask:0xf bank_mask:0xf
	v_fmac_f32_dpp v233, v93, v225 row_ror:15 row_mask:0xf bank_mask:0xf
	v_fmac_f32_dpp v234, v82, v226 row_ror:15 row_mask:0xf bank_mask:0xf
	v_fmac_f32_dpp v235, v83, v227 row_ror:15 row_mask:0xf bank_mask:0xf
	v_fmac_f32_dpp v236, v84, v228 row_ror:15 row_mask:0xf bank_mask:0xf
	v_fmac_f32_dpp v237, v85, v229 row_ror:15 row_mask:0xf bank_mask:0xf
	v_pk_mul_f32 v[174:175], v[230:231], s[34:35]
	v_pk_mul_f32 v[176:177], v[232:233], s[34:35]
	v_exp_f32_e32 v174, v174
	v_exp_f32_e32 v175, v175
	v_exp_f32_e32 v176, v176
	v_exp_f32_e32 v177, v177
	v_pk_add_f32 v[174:175], v[174:175], s[36:37]
	v_pk_add_f32 v[176:177], v[176:177], s[36:37]
	v_rcp_f32_e32 v174, v174
	v_rcp_f32_e32 v175, v175
	v_rcp_f32_e32 v176, v176
	v_rcp_f32_e32 v177, v177
	v_pk_mul_f32 v[174:175], v[230:231], v[174:175]
	v_pk_mul_f32 v[176:177], v[232:233], v[176:177]
	v_pk_mul_f32 v[174:175], v[174:175], v[234:235]
	v_pk_mul_f32 v[176:177], v[176:177], v[236:237]
	v_cvt_pk_bf16_f32 v178, v174, v175
	v_cvt_pk_bf16_f32 v179, v176, v177
	v_pk_fma_f32 v[230:231], v[90:91], v[186:187], v[194:195]
	v_pk_fma_f32 v[232:233], v[92:93], v[188:189], v[196:197]
	v_pk_fma_f32 v[234:235], v[82:83], v[202:203], v[210:211]
	v_pk_fma_f32 v[236:237], v[84:85], v[204:205], v[212:213]
	v_fmac_f32_dpp v230, v90, v182 row_shr:1 row_mask:0xf bank_mask:0xf
	v_fmac_f32_dpp v231, v91, v183 row_shr:1 row_mask:0xf bank_mask:0xf
	v_fmac_f32_dpp v232, v92, v184 row_shr:1 row_mask:0xf bank_mask:0xf
	v_fmac_f32_dpp v233, v93, v185 row_shr:1 row_mask:0xf bank_mask:0xf
	v_fmac_f32_dpp v234, v82, v198 row_shr:1 row_mask:0xf bank_mask:0xf
	v_fmac_f32_dpp v235, v83, v199 row_shr:1 row_mask:0xf bank_mask:0xf
	v_fmac_f32_dpp v236, v84, v200 row_shr:1 row_mask:0xf bank_mask:0xf
	v_fmac_f32_dpp v237, v85, v201 row_shr:1 row_mask:0xf bank_mask:0xf
	v_fmac_f32_dpp v230, v90, v190 row_shl:1 row_mask:0xf bank_mask:0xf
	v_fmac_f32_dpp v231, v91, v191 row_shl:1 row_mask:0xf bank_mask:0xf
	v_fmac_f32_dpp v232, v92, v192 row_shl:1 row_mask:0xf bank_mask:0xf
	v_fmac_f32_dpp v233, v93, v193 row_shl:1 row_mask:0xf bank_mask:0xf
	v_fmac_f32_dpp v234, v82, v206 row_shl:1 row_mask:0xf bank_mask:0xf
	v_fmac_f32_dpp v235, v83, v207 row_shl:1 row_mask:0xf bank_mask:0xf
	v_fmac_f32_dpp v236, v84, v208 row_shl:1 row_mask:0xf bank_mask:0xf
	v_fmac_f32_dpp v237, v85, v209 row_shl:1 row_mask:0xf bank_mask:0xf
	v_fmac_f32_dpp v230, v94, v214 row_ror:1 row_mask:0xf bank_mask:0xf
	v_fmac_f32_dpp v231, v95, v215 row_ror:1 row_mask:0xf bank_mask:0xf
	v_fmac_f32_dpp v232, v96, v216 row_ror:1 row_mask:0xf bank_mask:0xf
; __device__ __forceinline__ unsigned cvt_pk_bf16(float lo, float hi) { unsigned r; asm volatile("v_cvt_pk_bf16_f32 %0, %1, %2" : "=v"(r) : "v"(lo), "v"(hi)); return r; }
; __device__ __forceinline__ float sigmoid_f(float x) { return fast_rcp(1.0f + fast_exp2(-1.4426950409f * x)); }
;     __device__ __forceinline__ void operator()(f32x4 (&acc)[2][2][4][2], const Unit& u, int wr, int wc, int fr, int fq) const {
;     ...
;             for (int ai = 0; ai < 2; ++ai) {
;                 const int grp = u.pm * 4 + ai * 2 + wr;
; #pragma unroll
;                 for (int m = 0; m < 4; ++m) {
;                     f32x4 cv[2];
; #pragma unroll
;                     for (int bj = 0; bj < 2; ++bj) {
;                         const f32x4 cur = acc[ai][bj][m][n], lo = acc[ai][bj][m > 0 ? m - 1 : 0][n], hi = acc[ai][bj][m < 3 ? m + 1 : 3][n];
;                         f32x4 pv, nv;
; #pragma unroll
;                         for (int idx = 0; idx < 4; ++idx) {
;                             const float y = (fr == 15) ? lo[idx] : cur[idx], z = (fr == 0) ? hi[idx] : cur[idx];
;                             pv[idx] = __int_as_float(__builtin_amdgcn_update_dpp(0, __float_as_int(y), 0x121, 0xf, 0xf, false));
;                             nv[idx] = __int_as_float(__builtin_amdgcn_update_dpp(0, __float_as_int(z), 0x12f, 0xf, 0xf, false));
;                         }
;                         cv[bj] = kc[bj][0] * pv + kc[bj][1] * cur + kc[bj][2] * nv + bc[bj];
;                     }
;                     const int row = row0 + ai * HALF + m * 16;
;                     const bool edge = (m == 0 && fr == 0) || (m == 3 && fr == 15);
;                     if (!edge) { const f32x4 gt = cv[0], vl = cv[1];
;                         u32x2 w; w.x = cvt_pk_bf16(gt[0] * sigmoid_f(gt[0]) * vl[0], gt[1] * sigmoid_f(gt[1]) * vl[1]); w.y = cvt_pk_bf16(gt[2] * sigmoid_f(gt[2]) * vl[2], gt[3] * sigmoid_f(gt[3]) * vl[3]);
	v_fmac_f32_dpp v233, v97, v217 row_ror:1 row_mask:0xf bank_mask:0xf
	v_fmac_f32_dpp v234, v86, v218 row_ror:1 row_mask:0xf bank_mask:0xf
	v_fmac_f32_dpp v235, v87, v219 row_ror:1 row_mask:0xf bank_mask:0xf
	v_fmac_f32_dpp v236, v88, v220 row_ror:1 row_mask:0xf bank_mask:0xf
	v_fmac_f32_dpp v237, v89, v221 row_ror:1 row_mask:0xf bank_mask:0xf
	v_fmac_f32_dpp v230, v78, v222 row_ror:15 row_mask:0xf bank_mask:0xf
	v_fmac_f32_dpp v231, v79, v223 row_ror:15 row_mask:0xf bank_mask:0xf
	v_fmac_f32_dpp v232, v80, v224 row_ror:15 row_mask:0xf bank_mask:0xf
	v_fmac_f32_dpp v233, v81, v225 row_ror:15 row_mask:0xf bank_mask:0xf
	v_fmac_f32_dpp v234, v70, v226 row_ror:15 row_mask:0xf bank_mask:0xf
	v_fmac_f32_dpp v235, v71, v227 row_ror:15 row_mask:0xf bank_mask:0xf
	v_fmac_f32_dpp v236, v72, v228 row_ror:15 row_mask:0xf bank_mask:0xf
	v_fmac_f32_dpp v237, v73, v229 row_ror:15 row_mask:0xf bank_mask:0xf
	v_pk_mul_f32 v[174:175], v[230:231], s[34:35]
	v_pk_mul_f32 v[176:177], v[232:233], s[34:35]
	v_exp_f32_e32 v174, v174
	v_exp_f32_e32 v175, v175
	v_exp_f32_e32 v176, v176
	v_exp_f32_e32 v177, v177
	v_pk_add_f32 v[174:175], v[174:175], s[36:37]
	v_pk_add_f32 v[176:177], v[176:177], s[36:37]
	v_rcp_f32_e32 v174, v174
	v_rcp_f32_e32 v175, v175
	v_rcp_f32_e32 v176, v176
	v_rcp_f32_e32 v177, v177
	v_pk_mul_f32 v[174:175], v[230:231], v[174:175]
	v_pk_mul_f32 v[176:177], v[232:233], v[176:177]
	v_pk_mul_f32 v[174:175], v[174:175], v[234:235]
	v_pk_mul_f32 v[176:177], v[176:177], v[236:237]
	v_cvt_pk_bf16_f32 v94, v174, v175
	v_cvt_pk_bf16_f32 v95, v176, v177
	v_pk_fma_f32 v[230:231], v[78:79], v[186:187], v[194:195]
	v_pk_fma_f32 v[232:233], v[80:81], v[188:189], v[196:197]
	v_pk_fma_f32 v[234:235], v[70:71], v[202:203], v[210:211]
	v_pk_fma_f32 v[236:237], v[72:73], v[204:205], v[212:213]
	v_fmac_f32_dpp v230, v78, v182 row_shr:1 row_mask:0xf bank_mask:0xf
	v_fmac_f32_dpp v231, v79, v183 row_shr:1 row_mask:0xf bank_mask:0xf
	v_fmac_f32_dpp v232, v80, v184 row_shr:1 row_mask:0xf bank_mask:0xf
	v_fmac_f32_dpp v233, v81, v185 row_shr:1 row_mask:0xf bank_mask:0xf
	v_fmac_f32_dpp v234, v70, v198 row_shr:1 row_mask:0xf bank_mask:0xf
	v_fmac_f32_dpp v235, v71, v199 row_shr:1 row_mask:0xf bank_mask:0xf
	v_fmac_f32_dpp v236, v72, v200 row_shr:1 row_mask:0xf bank_mask:0xf
	v_fmac_f32_dpp v237, v73, v201 row_shr:1 row_mask:0xf bank_mask:0xf
	v_fmac_f32_dpp v230, v78, v190 row_shl:1 row_mask:0xf bank_mask:0xf
	v_fmac_f32_dpp v231, v79, v191 row_shl:1 row_mask:0xf bank_mask:0xf
	v_fmac_f32_dpp v232, v80, v192 row_shl:1 row_mask:0xf bank_mask:0xf
	v_fmac_f32_dpp v233, v81, v193 row_shl:1 row_mask:0xf bank_mask:0xf
	v_fmac_f32_dpp v234, v70, v206 row_shl:1 row_mask:0xf bank_mask:0xf
	v_fmac_f32_dpp v235, v71, v207 row_shl:1 row_mask:0xf bank_mask:0xf
	v_fmac_f32_dpp v236, v72, v208 row_shl:1 row_mask:0xf bank_mask:0xf
	v_fmac_f32_dpp v237, v73, v209 row_shl:1 row_mask:0xf bank_mask:0xf
	v_fmac_f32_dpp v230, v90, v214 row_ror:1 row_mask:0xf bank_mask:0xf
	v_fmac_f32_dpp v231, v91, v215 row_ror:1 row_mask:0xf bank_mask:0xf
	v_fmac_f32_dpp v232, v92, v216 row_ror:1 row_mask:0xf bank_mask:0xf
	v_fmac_f32_dpp v233, v93, v217 row_ror:1 row_mask:0xf bank_mask:0xf
	v_fmac_f32_dpp v234, v82, v218 row_ror:1 row_mask:0xf bank_mask:0xf
	v_fmac_f32_dpp v235, v83, v219 row_ror:1 row_mask:0xf bank_mask:0xf
	v_fmac_f32_dpp v236, v84, v220 row_ror:1 row_mask:0xf bank_mask:0xf
	v_fmac_f32_dpp v237, v85, v221 row_ror:1 row_mask:0xf bank_mask:0xf
	v_fmac_f32_dpp v230, v74, v222 row_ror:15 row_mask:0xf bank_mask:0xf
	v_fmac_f32_dpp v231, v75, v223 row_ror:15 row_mask:0xf bank_mask:0xf
	v_fmac_f32_dpp v232, v76, v224 row_ror:15 row_mask:0xf bank_mask:0xf
	v_fmac_f32_dpp v233, v77, v225 row_ror:15 row_mask:0xf bank_mask:0xf
	v_fmac_f32_dpp v234, v66, v226 row_ror:15 row_mask:0xf bank_mask:0xf
	v_fmac_f32_dpp v235, v67, v227 row_ror:15 row_mask:0xf bank_mask:0xf
	v_fmac_f32_dpp v236, v68, v228 row_ror:15 row_mask:0xf bank_mask:0xf
	v_fmac_f32_dpp v237, v69, v229 row_ror:15 row_mask:0xf bank_mask:0xf
	v_pk_mul_f32 v[174:175], v[230:231], s[34:35]
	v_pk_mul_f32 v[176:177], v[232:233], s[34:35]
	v_exp_f32_e32 v174, v174
	v_exp_f32_e32 v175, v175
	v_exp_f32_e32 v176, v176
	v_exp_f32_e32 v177, v177
	v_pk_add_f32 v[174:175], v[174:175], s[36:37]
	v_pk_add_f32 v[176:177], v[176:177], s[36:37]
	v_rcp_f32_e32 v174, v174
	v_rcp_f32_e32 v175, v175
	v_rcp_f32_e32 v176, v176
	v_rcp_f32_e32 v177, v177
	v_pk_mul_f32 v[174:175], v[230:231], v[174:175]
	v_pk_mul_f32 v[176:177], v[232:233], v[176:177]
	v_pk_mul_f32 v[174:175], v[174:175], v[234:235]
	v_pk_mul_f32 v[176:177], v[176:177], v[236:237]
	v_cvt_pk_bf16_f32 v90, v174, v175
	v_cvt_pk_bf16_f32 v91, v176, v177
	v_pk_fma_f32 v[230:231], v[74:75], v[186:187], v[194:195]
	v_pk_fma_f32 v[232:233], v[76:77], v[188:189], v[196:197]
	v_pk_fma_f32 v[234:235], v[66:67], v[202:203], v[210:211]
	v_pk_fma_f32 v[236:237], v[68:69], v[204:205], v[212:213]
	v_fmac_f32_dpp v230, v74, v182 row_shr:1 row_mask:0xf bank_mask:0xf
	v_fmac_f32_dpp v231, v75, v183 row_shr:1 row_mask:0xf bank_mask:0xf
	v_fmac_f32_dpp v232, v76, v184 row_shr:1 row_mask:0xf bank_mask:0xf
	v_fmac_f32_dpp v233, v77, v185 row_shr:1 row_mask:0xf bank_mask:0xf
	v_fmac_f32_dpp v234, v66, v198 row_shr:1 row_mask:0xf bank_mask:0xf
	v_fmac_f32_dpp v235, v67, v199 row_shr:1 row_mask:0xf bank_mask:0xf
	v_fmac_f32_dpp v236, v68, v200 row_shr:1 row_mask:0xf bank_mask:0xf
	v_fmac_f32_dpp v237, v69, v201 row_shr:1 row_mask:0xf bank_mask:0xf
	v_fmac_f32_dpp v230, v74, v190 row_shl:1 row_mask:0xf bank_mask:0xf
	v_fmac_f32_dpp v231, v75, v191 row_shl:1 row_mask:0xf bank_mask:0xf
; __device__ __forceinline__ unsigned cvt_pk_bf16(float lo, float hi) { unsigned r; asm volatile("v_cvt_pk_bf16_f32 %0, %1, %2" : "=v"(r) : "v"(lo), "v"(hi)); return r; }
; __device__ __forceinline__ float sigmoid_f(float x) { return fast_rcp(1.0f + fast_exp2(-1.4426950409f * x)); }
;     __device__ __forceinline__ void operator()(f32x4 (&acc)[2][2][4][2], const Unit& u, int wr, int wc, int fr, int fq) const {
;     ...
;             for (int ai = 0; ai < 2; ++ai) {
;                 const int grp = u.pm * 4 + ai * 2 + wr;
; #pragma unroll
;                 for (int m = 0; m < 4; ++m) {
;                     f32x4 cv[2];
; #pragma unroll
;                     for (int bj = 0; bj < 2; ++bj) {
;                         const f32x4 cur = acc[ai][bj][m][n], lo = acc[ai][bj][m > 0 ? m - 1 : 0][n], hi = acc[ai][bj][m < 3 ? m + 1 : 3][n];
;                         f32x4 pv, nv;
; #pragma unroll
;                         for (int idx = 0; idx < 4; ++idx) {
;                             const float y = (fr == 15) ? lo[idx] : cur[idx], z = (fr == 0) ? hi[idx] : cur[idx];
;                             pv[idx] = __int_as_float(__builtin_amdgcn_update_dpp(0, __float_as_int(y), 0x121, 0xf, 0xf, false));
;                             nv[idx] = __int_as_float(__builtin_amdgcn_update_dpp(0, __float_as_int(z), 0x12f, 0xf, 0xf, false));
;                         }
;                         cv[bj] = kc[bj][0] * pv + kc[bj][1] * cur + kc[bj][2] * nv + bc[bj];
;                     }
;                     const int row = row0 + ai * HALF + m * 16;
;                     const bool edge = (m == 0 && fr == 0) || (m == 3 && fr == 15);
;                     if (!edge) { const f32x4 gt = cv[0], vl = cv[1];
;                         u32x2 w; w.x = cvt_pk_bf16(gt[0] * sigmoid_f(gt[0]) * vl[0], gt[1] * sigmoid_f(gt[1]) * vl[1]); w.y = cvt_pk_bf16(gt[2] * sigmoid_f(gt[2]) * vl[2], gt[3] * sigmoid_f(gt[3]) * vl[3]);
;                         *(u32x2*)(ACT + (size_t)row * FF + j4) = w; }
	v_fmac_f32_dpp v232, v76, v192 row_shl:1 row_mask:0xf bank_mask:0xf
	v_fmac_f32_dpp v233, v77, v193 row_shl:1 row_mask:0xf bank_mask:0xf
	v_fmac_f32_dpp v234, v66, v206 row_shl:1 row_mask:0xf bank_mask:0xf
	v_fmac_f32_dpp v235, v67, v207 row_shl:1 row_mask:0xf bank_mask:0xf
	v_fmac_f32_dpp v236, v68, v208 row_shl:1 row_mask:0xf bank_mask:0xf
	v_fmac_f32_dpp v237, v69, v209 row_shl:1 row_mask:0xf bank_mask:0xf
	v_fmac_f32_dpp v230, v78, v214 row_ror:1 row_mask:0xf bank_mask:0xf
	v_fmac_f32_dpp v231, v79, v215 row_ror:1 row_mask:0xf bank_mask:0xf
	v_fmac_f32_dpp v232, v80, v216 row_ror:1 row_mask:0xf bank_mask:0xf
	v_fmac_f32_dpp v233, v81, v217 row_ror:1 row_mask:0xf bank_mask:0xf
	v_fmac_f32_dpp v234, v70, v218 row_ror:1 row_mask:0xf bank_mask:0xf
	v_fmac_f32_dpp v235, v71, v219 row_ror:1 row_mask:0xf bank_mask:0xf
	v_fmac_f32_dpp v236, v72, v220 row_ror:1 row_mask:0xf bank_mask:0xf
	v_fmac_f32_dpp v237, v73, v221 row_ror:1 row_mask:0xf bank_mask:0xf
	v_pk_mul_f32 v[174:175], v[230:231], s[34:35]
	v_pk_mul_f32 v[176:177], v[232:233], s[34:35]
	v_exp_f32_e32 v174, v174
	v_exp_f32_e32 v175, v175
	v_exp_f32_e32 v176, v176
	v_exp_f32_e32 v177, v177
	v_pk_add_f32 v[174:175], v[174:175], s[36:37]
	v_pk_add_f32 v[176:177], v[176:177], s[36:37]
	v_rcp_f32_e32 v174, v174
	v_rcp_f32_e32 v175, v175
	v_rcp_f32_e32 v176, v176
	v_rcp_f32_e32 v177, v177
	v_pk_mul_f32 v[174:175], v[230:231], v[174:175]
	v_pk_mul_f32 v[176:177], v[232:233], v[176:177]
	v_pk_mul_f32 v[174:175], v[174:175], v[234:235]
	v_pk_mul_f32 v[176:177], v[176:177], v[236:237]
	v_cvt_pk_bf16_f32 v78, v174, v175
	v_cvt_pk_bf16_f32 v79, v176, v177
	s_waitcnt vmcnt(0)
	v_cndmask_b32_e64 v214, 0, v126, s[42:43]
	v_cndmask_b32_e64 v215, 0, v127, s[42:43]
	v_cndmask_b32_e64 v216, 0, v128, s[42:43]
	v_cndmask_b32_e64 v217, 0, v129, s[42:43]
	v_cndmask_b32_e64 v218, 0, v122, s[42:43]
	v_cndmask_b32_e64 v219, 0, v123, s[42:43]
	v_cndmask_b32_e64 v220, 0, v124, s[42:43]
	v_cndmask_b32_e64 v221, 0, v125, s[42:43]
	v_cndmask_b32_e64 v222, 0, v110, s[38:39]
	v_cndmask_b32_e64 v223, 0, v111, s[38:39]
	v_cndmask_b32_e64 v224, 0, v112, s[38:39]
	v_cndmask_b32_e64 v225, 0, v113, s[38:39]
	v_cndmask_b32_e64 v226, 0, v102, s[38:39]
	v_cndmask_b32_e64 v227, 0, v103, s[38:39]
	v_cndmask_b32_e64 v228, 0, v104, s[38:39]
	v_cndmask_b32_e64 v229, 0, v105, s[38:39]
	v_pk_fma_f32 v[230:231], v[62:63], v[118:119], v[106:107]
	v_pk_fma_f32 v[232:233], v[64:65], v[120:121], v[108:109]
	v_pk_fma_f32 v[234:235], v[54:55], v[114:115], v[98:99]
	v_pk_fma_f32 v[236:237], v[56:57], v[116:117], v[100:101]
	v_fmac_f32_dpp v230, v62, v126 row_shr:1 row_mask:0xf bank_mask:0xf
	v_fmac_f32_dpp v231, v63, v127 row_shr:1 row_mask:0xf bank_mask:0xf
	v_fmac_f32_dpp v232, v64, v128 row_shr:1 row_mask:0xf bank_mask:0xf
	v_fmac_f32_dpp v233, v65, v129 row_shr:1 row_mask:0xf bank_mask:0xf
	v_fmac_f32_dpp v234, v54, v122 row_shr:1 row_mask:0xf bank_mask:0xf
	v_fmac_f32_dpp v235, v55, v123 row_shr:1 row_mask:0xf bank_mask:0xf
	v_fmac_f32_dpp v236, v56, v124 row_shr:1 row_mask:0xf bank_mask:0xf
	v_fmac_f32_dpp v237, v57, v125 row_shr:1 row_mask:0xf bank_mask:0xf
	v_fmac_f32_dpp v230, v62, v110 row_shl:1 row_mask:0xf bank_mask:0xf
	v_fmac_f32_dpp v231, v63, v111 row_shl:1 row_mask:0xf bank_mask:0xf
	v_fmac_f32_dpp v232, v64, v112 row_shl:1 row_mask:0xf bank_mask:0xf
	v_fmac_f32_dpp v233, v65, v113 row_shl:1 row_mask:0xf bank_mask:0xf
	v_fmac_f32_dpp v234, v54, v102 row_shl:1 row_mask:0xf bank_mask:0xf
	v_fmac_f32_dpp v235, v55, v103 row_shl:1 row_mask:0xf bank_mask:0xf
	v_fmac_f32_dpp v236, v56, v104 row_shl:1 row_mask:0xf bank_mask:0xf
	v_fmac_f32_dpp v237, v57, v105 row_shl:1 row_mask:0xf bank_mask:0xf
	v_fmac_f32_dpp v230, v58, v222 row_ror:15 row_mask:0xf bank_mask:0xf
	v_fmac_f32_dpp v231, v59, v223 row_ror:15 row_mask:0xf bank_mask:0xf
	v_fmac_f32_dpp v232, v60, v224 row_ror:15 row_mask:0xf bank_mask:0xf
	v_fmac_f32_dpp v233, v61, v225 row_ror:15 row_mask:0xf bank_mask:0xf
	v_fmac_f32_dpp v234, v50, v226 row_ror:15 row_mask:0xf bank_mask:0xf
	v_fmac_f32_dpp v235, v51, v227 row_ror:15 row_mask:0xf bank_mask:0xf
	v_fmac_f32_dpp v236, v52, v228 row_ror:15 row_mask:0xf bank_mask:0xf
	v_fmac_f32_dpp v237, v53, v229 row_ror:15 row_mask:0xf bank_mask:0xf
	v_pk_mul_f32 v[174:175], v[230:231], s[34:35]
	v_pk_mul_f32 v[176:177], v[232:233], s[34:35]
	v_exp_f32_e32 v174, v174
	v_exp_f32_e32 v175, v175
	v_exp_f32_e32 v176, v176
	v_exp_f32_e32 v177, v177
	v_pk_add_f32 v[174:175], v[174:175], s[36:37]
	v_pk_add_f32 v[176:177], v[176:177], s[36:37]
	v_rcp_f32_e32 v174, v174
	v_rcp_f32_e32 v175, v175
	v_rcp_f32_e32 v176, v176
	v_rcp_f32_e32 v177, v177
	v_pk_mul_f32 v[174:175], v[230:231], v[174:175]
	v_pk_mul_f32 v[176:177], v[232:233], v[176:177]
	v_pk_mul_f32 v[174:175], v[174:175], v[234:235]
	v_pk_mul_f32 v[176:177], v[176:177], v[236:237]
	v_cvt_pk_bf16_f32 v132, v174, v175
	v_cvt_pk_bf16_f32 v133, v176, v177
	s_and_saveexec_b64 s[16:17], s[44:45]
	global_store_dwordx4 v238, v[130:133], s[30:31]
	s_or_b64 exec, exec, s[16:17]
	v_pk_fma_f32 v[230:231], v[58:59], v[118:119], v[106:107]
	v_pk_fma_f32 v[232:233], v[60:61], v[120:121], v[108:109]
	v_pk_fma_f32 v[234:235], v[50:51], v[114:115], v[98:99]
	v_pk_fma_f32 v[236:237], v[52:53], v[116:117], v[100:101]
	v_fmac_f32_dpp v230, v58, v126 row_shr:1 row_mask:0xf bank_mask:0xf
	v_fmac_f32_dpp v231, v59, v127 row_shr:1 row_mask:0xf bank_mask:0xf
	v_fmac_f32_dpp v232, v60, v128 row_shr:1 row_mask:0xf bank_mask:0xf
	v_fmac_f32_dpp v233, v61, v129 row_shr:1 row_mask:0xf bank_mask:0xf
	v_fmac_f32_dpp v234, v50, v122 row_shr:1 row_mask:0xf bank_mask:0xf
	v_fmac_f32_dpp v235, v51, v123 row_shr:1 row_mask:0xf bank_mask:0xf
; __device__ __forceinline__ unsigned cvt_pk_bf16(float lo, float hi) { unsigned r; asm volatile("v_cvt_pk_bf16_f32 %0, %1, %2" : "=v"(r) : "v"(lo), "v"(hi)); return r; }
; __device__ __forceinline__ float sigmoid_f(float x) { return fast_rcp(1.0f + fast_exp2(-1.4426950409f * x)); }
;     __device__ __forceinline__ void operator()(f32x4 (&acc)[2][2][4][2], const Unit& u, int wr, int wc, int fr, int fq) const {
;     ...
;             for (int ai = 0; ai < 2; ++ai) {
;                 const int grp = u.pm * 4 + ai * 2 + wr;
; #pragma unroll
;                 for (int m = 0; m < 4; ++m) {
;                     f32x4 cv[2];
; #pragma unroll
;                     for (int bj = 0; bj < 2; ++bj) {
;                         const f32x4 cur = acc[ai][bj][m][n], lo = acc[ai][bj][m > 0 ? m - 1 : 0][n], hi = acc[ai][bj][m < 3 ? m + 1 : 3][n];
;                         f32x4 pv, nv;
; #pragma unroll
;                         for (int idx = 0; idx < 4; ++idx) {
;                             const float y = (fr == 15) ? lo[idx] : cur[idx], z = (fr == 0) ? hi[idx] : cur[idx];
;                             pv[idx] = __int_as_float(__builtin_amdgcn_update_dpp(0, __float_as_int(y), 0x121, 0xf, 0xf, false));
;                             nv[idx] = __int_as_float(__builtin_amdgcn_update_dpp(0, __float_as_int(z), 0x12f, 0xf, 0xf, false));
;                         }
;                         cv[bj] = kc[bj][0] * pv + kc[bj][1] * cur + kc[bj][2] * nv + bc[bj];
;                     }
;                     const int row = row0 + ai * HALF + m * 16;
;                     const bool edge = (m == 0 && fr == 0) || (m == 3 && fr == 15);
;                     if (!edge) { const f32x4 gt = cv[0], vl = cv[1];
;                         u32x2 w; w.x = cvt_pk_bf16(gt[0] * sigmoid_f(gt[0]) * vl[0], gt[1] * sigmoid_f(gt[1]) * vl[1]); w.y = cvt_pk_bf16(gt[2] * sigmoid_f(gt[2]) * vl[2], gt[3] * sigmoid_f(gt[3]) * vl[3]);
;                         *(u32x2*)(ACT + (size_t)row * FF + j4) = w; }
	v_fmac_f32_dpp v236, v52, v124 row_shr:1 row_mask:0xf bank_mask:0xf
	v_fmac_f32_dpp v237, v53, v125 row_shr:1 row_mask:0xf bank_mask:0xf
	v_fmac_f32_dpp v230, v58, v110 row_shl:1 row_mask:0xf bank_mask:0xf
	v_fmac_f32_dpp v231, v59, v111 row_shl:1 row_mask:0xf bank_mask:0xf
	v_fmac_f32_dpp v232, v60, v112 row_shl:1 row_mask:0xf bank_mask:0xf
	v_fmac_f32_dpp v233, v61, v113 row_shl:1 row_mask:0xf bank_mask:0xf
	v_fmac_f32_dpp v234, v50, v102 row_shl:1 row_mask:0xf bank_mask:0xf
	v_fmac_f32_dpp v235, v51, v103 row_shl:1 row_mask:0xf bank_mask:0xf
	v_fmac_f32_dpp v236, v52, v104 row_shl:1 row_mask:0xf bank_mask:0xf
	v_fmac_f32_dpp v237, v53, v105 row_shl:1 row_mask:0xf bank_mask:0xf
	v_fmac_f32_dpp v230, v62, v214 row_ror:1 row_mask:0xf bank_mask:0xf
	v_fmac_f32_dpp v231, v63, v215 row_ror:1 row_mask:0xf bank_mask:0xf
	v_fmac_f32_dpp v232, v64, v216 row_ror:1 row_mask:0xf bank_mask:0xf
	v_fmac_f32_dpp v233, v65, v217 row_ror:1 row_mask:0xf bank_mask:0xf
	v_fmac_f32_dpp v234, v54, v218 row_ror:1 row_mask:0xf bank_mask:0xf
	v_fmac_f32_dpp v235, v55, v219 row_ror:1 row_mask:0xf bank_mask:0xf
	v_fmac_f32_dpp v236, v56, v220 row_ror:1 row_mask:0xf bank_mask:0xf
	v_fmac_f32_dpp v237, v57, v221 row_ror:1 row_mask:0xf bank_mask:0xf
	v_fmac_f32_dpp v230, v46, v222 row_ror:15 row_mask:0xf bank_mask:0xf
	v_fmac_f32_dpp v231, v47, v223 row_ror:15 row_mask:0xf bank_mask:0xf
	v_fmac_f32_dpp v232, v48, v224 row_ror:15 row_mask:0xf bank_mask:0xf
	v_fmac_f32_dpp v233, v49, v225 row_ror:15 row_mask:0xf bank_mask:0xf
	v_fmac_f32_dpp v234, v38, v226 row_ror:15 row_mask:0xf bank_mask:0xf
	v_fmac_f32_dpp v235, v39, v227 row_ror:15 row_mask:0xf bank_mask:0xf
	v_fmac_f32_dpp v236, v40, v228 row_ror:15 row_mask:0xf bank_mask:0xf
	v_fmac_f32_dpp v237, v41, v229 row_ror:15 row_mask:0xf bank_mask:0xf
	v_pk_mul_f32 v[174:175], v[230:231], s[34:35]
	v_pk_mul_f32 v[176:177], v[232:233], s[34:35]
	v_exp_f32_e32 v174, v174
	v_exp_f32_e32 v175, v175
	v_exp_f32_e32 v176, v176
	v_exp_f32_e32 v177, v177
	v_pk_add_f32 v[174:175], v[174:175], s[36:37]
	v_pk_add_f32 v[176:177], v[176:177], s[36:37]
	v_rcp_f32_e32 v174, v174
	v_rcp_f32_e32 v175, v175
	v_rcp_f32_e32 v176, v176
	v_rcp_f32_e32 v177, v177
	v_pk_mul_f32 v[174:175], v[230:231], v[174:175]
	v_pk_mul_f32 v[176:177], v[232:233], v[176:177]
	v_pk_mul_f32 v[174:175], v[174:175], v[234:235]
	v_pk_mul_f32 v[176:177], v[176:177], v[236:237]
	v_cvt_pk_bf16_f32 v136, v174, v175
	v_cvt_pk_bf16_f32 v137, v176, v177
	v_add_u32_e32 v239, 0x2b000, v238
	global_store_dwordx4 v239, v[134:137], s[30:31]
	v_pk_fma_f32 v[230:231], v[46:47], v[118:119], v[106:107]
	v_pk_fma_f32 v[232:233], v[48:49], v[120:121], v[108:109]
	v_pk_fma_f32 v[234:235], v[38:39], v[114:115], v[98:99]
	v_pk_fma_f32 v[236:237], v[40:41], v[116:117], v[100:101]
	v_fmac_f32_dpp v230, v46, v126 row_shr:1 row_mask:0xf bank_mask:0xf
	v_fmac_f32_dpp v231, v47, v127 row_shr:1 row_mask:0xf bank_mask:0xf
	v_fmac_f32_dpp v232, v48, v128 row_shr:1 row_mask:0xf bank_mask:0xf
	v_fmac_f32_dpp v233, v49, v129 row_shr:1 row_mask:0xf bank_mask:0xf
	v_fmac_f32_dpp v234, v38, v122 row_shr:1 row_mask:0xf bank_mask:0xf
	v_fmac_f32_dpp v235, v39, v123 row_shr:1 row_mask:0xf bank_mask:0xf
	v_fmac_f32_dpp v236, v40, v124 row_shr:1 row_mask:0xf bank_mask:0xf
	v_fmac_f32_dpp v237, v41, v125 row_shr:1 row_mask:0xf bank_mask:0xf
	v_fmac_f32_dpp v230, v46, v110 row_shl:1 row_mask:0xf bank_mask:0xf
	v_fmac_f32_dpp v231, v47, v111 row_shl:1 row_mask:0xf bank_mask:0xf
	v_fmac_f32_dpp v232, v48, v112 row_shl:1 row_mask:0xf bank_mask:0xf
	v_fmac_f32_dpp v233, v49, v113 row_shl:1 row_mask:0xf bank_mask:0xf
	v_fmac_f32_dpp v234, v38, v102 row_shl:1 row_mask:0xf bank_mask:0xf
	v_fmac_f32_dpp v235, v39, v103 row_shl:1 row_mask:0xf bank_mask:0xf
	v_fmac_f32_dpp v236, v40, v104 row_shl:1 row_mask:0xf bank_mask:0xf
	v_fmac_f32_dpp v237, v41, v105 row_shl:1 row_mask:0xf bank_mask:0xf
	v_fmac_f32_dpp v230, v58, v214 row_ror:1 row_mask:0xf bank_mask:0xf
	v_fmac_f32_dpp v231, v59, v215 row_ror:1 row_mask:0xf bank_mask:0xf
	v_fmac_f32_dpp v232, v60, v216 row_ror:1 row_mask:0xf bank_mask:0xf
	v_fmac_f32_dpp v233, v61, v217 row_ror:1 row_mask:0xf bank_mask:0xf
	v_fmac_f32_dpp v234, v50, v218 row_ror:1 row_mask:0xf bank_mask:0xf
	v_fmac_f32_dpp v235, v51, v219 row_ror:1 row_mask:0xf bank_mask:0xf
	v_fmac_f32_dpp v236, v52, v220 row_ror:1 row_mask:0xf bank_mask:0xf
	v_fmac_f32_dpp v237, v53, v221 row_ror:1 row_mask:0xf bank_mask:0xf
	v_fmac_f32_dpp v230, v42, v222 row_ror:15 row_mask:0xf bank_mask:0xf
	v_fmac_f32_dpp v231, v43, v223 row_ror:15 row_mask:0xf bank_mask:0xf
	v_fmac_f32_dpp v232, v44, v224 row_ror:15 row_mask:0xf bank_mask:0xf
	v_fmac_f32_dpp v233, v45, v225 row_ror:15 row_mask:0xf bank_mask:0xf
	v_fmac_f32_dpp v234, v34, v226 row_ror:15 row_mask:0xf bank_mask:0xf
	v_fmac_f32_dpp v235, v35, v227 row_ror:15 row_mask:0xf bank_mask:0xf
	v_fmac_f32_dpp v236, v36, v228 row_ror:15 row_mask:0xf bank_mask:0xf
	v_fmac_f32_dpp v237, v37, v229 row_ror:15 row_mask:0xf bank_mask:0xf
	v_pk_mul_f32 v[174:175], v[230:231], s[34:35]
	v_pk_mul_f32 v[176:177], v[232:233], s[34:35]
	v_exp_f32_e32 v174, v174
	v_exp_f32_e32 v175, v175
	v_exp_f32_e32 v176, v176
	v_exp_f32_e32 v177, v177
	v_pk_add_f32 v[174:175], v[174:175], s[36:37]
	v_pk_add_f32 v[176:177], v[176:177], s[36:37]
	v_rcp_f32_e32 v174, v174
	v_rcp_f32_e32 v175, v175
	v_rcp_f32_e32 v176, v176
	v_rcp_f32_e32 v177, v177
	v_pk_mul_f32 v[174:175], v[230:231], v[174:175]
	v_pk_mul_f32 v[176:177], v[232:233], v[176:177]
	v_pk_mul_f32 v[174:175], v[174:175], v[234:235]
	v_pk_mul_f32 v[176:177], v[176:177], v[236:237]
	v_cvt_pk_bf16_f32 v140, v174, v175
; __device__ __forceinline__ unsigned cvt_pk_bf16(float lo, float hi) { unsigned r; asm volatile("v_cvt_pk_bf16_f32 %0, %1, %2" : "=v"(r) : "v"(lo), "v"(hi)); return r; }
; __device__ __forceinline__ float sigmoid_f(float x) { return fast_rcp(1.0f + fast_exp2(-1.4426950409f * x)); }
;     __device__ __forceinline__ void operator()(f32x4 (&acc)[2][2][4][2], const Unit& u, int wr, int wc, int fr, int fq) const {
;     ...
;             for (int ai = 0; ai < 2; ++ai) {
;                 const int grp = u.pm * 4 + ai * 2 + wr;
; #pragma unroll
;                 for (int m = 0; m < 4; ++m) {
;                     f32x4 cv[2];
; #pragma unroll
;                     for (int bj = 0; bj < 2; ++bj) {
;                         const f32x4 cur = acc[ai][bj][m][n], lo = acc[ai][bj][m > 0 ? m - 1 : 0][n], hi = acc[ai][bj][m < 3 ? m + 1 : 3][n];
;                         f32x4 pv, nv;
; #pragma unroll
;                         for (int idx = 0; idx < 4; ++idx) {
;                             const float y = (fr == 15) ? lo[idx] : cur[idx], z = (fr == 0) ? hi[idx] : cur[idx];
;                             pv[idx] = __int_as_float(__builtin_amdgcn_update_dpp(0, __float_as_int(y), 0x121, 0xf, 0xf, false));
;                             nv[idx] = __int_as_float(__builtin_amdgcn_update_dpp(0, __float_as_int(z), 0x12f, 0xf, 0xf, false));
;                         }
;                         cv[bj] = kc[bj][0] * pv + kc[bj][1] * cur + kc[bj][2] * nv + bc[bj];
;                     }
;                     const int row = row0 + ai * HALF + m * 16;
;                     const bool edge = (m == 0 && fr == 0) || (m == 3 && fr == 15);
;                     if (!edge) { const f32x4 gt = cv[0], vl = cv[1];
;                         u32x2 w; w.x = cvt_pk_bf16(gt[0] * sigmoid_f(gt[0]) * vl[0], gt[1] * sigmoid_f(gt[1]) * vl[1]); w.y = cvt_pk_bf16(gt[2] * sigmoid_f(gt[2]) * vl[2], gt[3] * sigmoid_f(gt[3]) * vl[3]);
;                         *(u32x2*)(ACT + (size_t)row * FF + j4) = w; }
	v_cvt_pk_bf16_f32 v141, v176, v177
	v_add_u32_e32 v239, 0x56000, v238
	global_store_dwordx4 v239, v[138:141], s[30:31]
	v_pk_fma_f32 v[230:231], v[42:43], v[118:119], v[106:107]
	v_pk_fma_f32 v[232:233], v[44:45], v[120:121], v[108:109]
	v_pk_fma_f32 v[234:235], v[34:35], v[114:115], v[98:99]
	v_pk_fma_f32 v[236:237], v[36:37], v[116:117], v[100:101]
	v_fmac_f32_dpp v230, v42, v126 row_shr:1 row_mask:0xf bank_mask:0xf
	v_fmac_f32_dpp v231, v43, v127 row_shr:1 row_mask:0xf bank_mask:0xf
	v_fmac_f32_dpp v232, v44, v128 row_shr:1 row_mask:0xf bank_mask:0xf
	v_fmac_f32_dpp v233, v45, v129 row_shr:1 row_mask:0xf bank_mask:0xf
	v_fmac_f32_dpp v234, v34, v122 row_shr:1 row_mask:0xf bank_mask:0xf
	v_fmac_f32_dpp v235, v35, v123 row_shr:1 row_mask:0xf bank_mask:0xf
	v_fmac_f32_dpp v236, v36, v124 row_shr:1 row_mask:0xf bank_mask:0xf
	v_fmac_f32_dpp v237, v37, v125 row_shr:1 row_mask:0xf bank_mask:0xf
	v_fmac_f32_dpp v230, v42, v110 row_shl:1 row_mask:0xf bank_mask:0xf
	v_fmac_f32_dpp v231, v43, v111 row_shl:1 row_mask:0xf bank_mask:0xf
	v_fmac_f32_dpp v232, v44, v112 row_shl:1 row_mask:0xf bank_mask:0xf
	v_fmac_f32_dpp v233, v45, v113 row_shl:1 row_mask:0xf bank_mask:0xf
	v_fmac_f32_dpp v234, v34, v102 row_shl:1 row_mask:0xf bank_mask:0xf
	v_fmac_f32_dpp v235, v35, v103 row_shl:1 row_mask:0xf bank_mask:0xf
	v_fmac_f32_dpp v236, v36, v104 row_shl:1 row_mask:0xf bank_mask:0xf
	v_fmac_f32_dpp v237, v37, v105 row_shl:1 row_mask:0xf bank_mask:0xf
	v_fmac_f32_dpp v230, v46, v214 row_ror:1 row_mask:0xf bank_mask:0xf
	v_fmac_f32_dpp v231, v47, v215 row_ror:1 row_mask:0xf bank_mask:0xf
	v_fmac_f32_dpp v232, v48, v216 row_ror:1 row_mask:0xf bank_mask:0xf
	v_fmac_f32_dpp v233, v49, v217 row_ror:1 row_mask:0xf bank_mask:0xf
	v_fmac_f32_dpp v234, v38, v218 row_ror:1 row_mask:0xf bank_mask:0xf
	v_fmac_f32_dpp v235, v39, v219 row_ror:1 row_mask:0xf bank_mask:0xf
	v_fmac_f32_dpp v236, v40, v220 row_ror:1 row_mask:0xf bank_mask:0xf
	v_fmac_f32_dpp v237, v41, v221 row_ror:1 row_mask:0xf bank_mask:0xf
	v_pk_mul_f32 v[174:175], v[230:231], s[34:35]
	v_pk_mul_f32 v[176:177], v[232:233], s[34:35]
	v_exp_f32_e32 v174, v174
	v_exp_f32_e32 v175, v175
	v_exp_f32_e32 v176, v176
	v_exp_f32_e32 v177, v177
	v_pk_add_f32 v[174:175], v[174:175], s[36:37]
	v_pk_add_f32 v[176:177], v[176:177], s[36:37]
	v_rcp_f32_e32 v174, v174
	v_rcp_f32_e32 v175, v175
	v_rcp_f32_e32 v176, v176
	v_rcp_f32_e32 v177, v177
	v_pk_mul_f32 v[174:175], v[230:231], v[174:175]
	v_pk_mul_f32 v[176:177], v[232:233], v[176:177]
	v_pk_mul_f32 v[174:175], v[174:175], v[234:235]
	v_pk_mul_f32 v[176:177], v[176:177], v[236:237]
	v_cvt_pk_bf16_f32 v144, v174, v175
	v_cvt_pk_bf16_f32 v145, v176, v177
	v_add_u32_e32 v239, 0x81000, v238
	s_and_saveexec_b64 s[16:17], s[40:41]
	global_store_dwordx4 v239, v[142:145], s[30:31]
	s_or_b64 exec, exec, s[16:17]
	v_pk_fma_f32 v[230:231], v[30:31], v[118:119], v[106:107]
	v_pk_fma_f32 v[232:233], v[32:33], v[120:121], v[108:109]
	v_pk_fma_f32 v[234:235], v[22:23], v[114:115], v[98:99]
	v_pk_fma_f32 v[236:237], v[24:25], v[116:117], v[100:101]
	v_fmac_f32_dpp v230, v30, v126 row_shr:1 row_mask:0xf bank_mask:0xf
	v_fmac_f32_dpp v231, v31, v127 row_shr:1 row_mask:0xf bank_mask:0xf
	v_fmac_f32_dpp v232, v32, v128 row_shr:1 row_mask:0xf bank_mask:0xf
	v_fmac_f32_dpp v233, v33, v129 row_shr:1 row_mask:0xf bank_mask:0xf
	v_fmac_f32_dpp v234, v22, v122 row_shr:1 row_mask:0xf bank_mask:0xf
	v_fmac_f32_dpp v235, v23, v123 row_shr:1 row_mask:0xf bank_mask:0xf
	v_fmac_f32_dpp v236, v24, v124 row_shr:1 row_mask:0xf bank_mask:0xf
	v_fmac_f32_dpp v237, v25, v125 row_shr:1 row_mask:0xf bank_mask:0xf
	v_fmac_f32_dpp v230, v30, v110 row_shl:1 row_mask:0xf bank_mask:0xf
	v_fmac_f32_dpp v231, v31, v111 row_shl:1 row_mask:0xf bank_mask:0xf
	v_fmac_f32_dpp v232, v32, v112 row_shl:1 row_mask:0xf bank_mask:0xf
	v_fmac_f32_dpp v233, v33, v113 row_shl:1 row_mask:0xf bank_mask:0xf
	v_fmac_f32_dpp v234, v22, v102 row_shl:1 row_mask:0xf bank_mask:0xf
	v_fmac_f32_dpp v235, v23, v103 row_shl:1 row_mask:0xf bank_mask:0xf
	v_fmac_f32_dpp v236, v24, v104 row_shl:1 row_mask:0xf bank_mask:0xf
	v_fmac_f32_dpp v237, v25, v105 row_shl:1 row_mask:0xf bank_mask:0xf
	v_fmac_f32_dpp v230, v26, v222 row_ror:15 row_mask:0xf bank_mask:0xf
	v_fmac_f32_dpp v231, v27, v223 row_ror:15 row_mask:0xf bank_mask:0xf
	v_fmac_f32_dpp v232, v28, v224 row_ror:15 row_mask:0xf bank_mask:0xf
	v_fmac_f32_dpp v233, v29, v225 row_ror:15 row_mask:0xf bank_mask:0xf
	v_fmac_f32_dpp v234, v18, v226 row_ror:15 row_mask:0xf bank_mask:0xf
	v_fmac_f32_dpp v235, v19, v227 row_ror:15 row_mask:0xf bank_mask:0xf
	v_fmac_f32_dpp v236, v20, v228 row_ror:15 row_mask:0xf bank_mask:0xf
	v_fmac_f32_dpp v237, v21, v229 row_ror:15 row_mask:0xf bank_mask:0xf
	v_pk_mul_f32 v[174:175], v[230:231], s[34:35]
	v_pk_mul_f32 v[176:177], v[232:233], s[34:35]
	v_exp_f32_e32 v174, v174
	v_exp_f32_e32 v175, v175
	v_exp_f32_e32 v176, v176
	v_exp_f32_e32 v177, v177
	v_pk_add_f32 v[174:175], v[174:175], s[36:37]
	v_pk_add_f32 v[176:177], v[176:177], s[36:37]
	v_rcp_f32_e32 v174, v174
	v_rcp_f32_e32 v175, v175
	v_rcp_f32_e32 v176, v176
	v_rcp_f32_e32 v177, v177
	v_pk_mul_f32 v[174:175], v[230:231], v[174:175]
	v_pk_mul_f32 v[176:177], v[232:233], v[176:177]
	v_pk_mul_f32 v[174:175], v[174:175], v[234:235]
	v_pk_mul_f32 v[176:177], v[176:177], v[236:237]
	v_cvt_pk_bf16_f32 v180, v174, v175
	v_cvt_pk_bf16_f32 v181, v176, v177
	v_add_u32_e32 v239, 0x158000, v238
	s_and_saveexec_b64 s[16:17], s[44:45]
	global_store_dwordx4 v239, v[178:181], s[30:31]
	s_or_b64 exec, exec, s[16:17]
	v_pk_fma_f32 v[230:231], v[26:27], v[118:119], v[106:107]
	v_pk_fma_f32 v[232:233], v[28:29], v[120:121], v[108:109]
; __device__ __forceinline__ unsigned cvt_pk_bf16(float lo, float hi) { unsigned r; asm volatile("v_cvt_pk_bf16_f32 %0, %1, %2" : "=v"(r) : "v"(lo), "v"(hi)); return r; }
; __device__ __forceinline__ float sigmoid_f(float x) { return fast_rcp(1.0f + fast_exp2(-1.4426950409f * x)); }
;     __device__ __forceinline__ void operator()(f32x4 (&acc)[2][2][4][2], const Unit& u, int wr, int wc, int fr, int fq) const {
;     ...
;             for (int ai = 0; ai < 2; ++ai) {
;                 const int grp = u.pm * 4 + ai * 2 + wr;
; #pragma unroll
;                 for (int m = 0; m < 4; ++m) {
;                     f32x4 cv[2];
; #pragma unroll
;                     for (int bj = 0; bj < 2; ++bj) {
;                         const f32x4 cur = acc[ai][bj][m][n], lo = acc[ai][bj][m > 0 ? m - 1 : 0][n], hi = acc[ai][bj][m < 3 ? m + 1 : 3][n];
;                         f32x4 pv, nv;
; #pragma unroll
;                         for (int idx = 0; idx < 4; ++idx) {
;                             const float y = (fr == 15) ? lo[idx] : cur[idx], z = (fr == 0) ? hi[idx] : cur[idx];
;                             pv[idx] = __int_as_float(__builtin_amdgcn_update_dpp(0, __float_as_int(y), 0x121, 0xf, 0xf, false));
;                             nv[idx] = __int_as_float(__builtin_amdgcn_update_dpp(0, __float_as_int(z), 0x12f, 0xf, 0xf, false));
;                         }
;                         cv[bj] = kc[bj][0] * pv + kc[bj][1] * cur + kc[bj][2] * nv + bc[bj];
;                     }
;                     const int row = row0 + ai * HALF + m * 16;
;                     const bool edge = (m == 0 && fr == 0) || (m == 3 && fr == 15);
;                     if (!edge) { const f32x4 gt = cv[0], vl = cv[1];
;                         u32x2 w; w.x = cvt_pk_bf16(gt[0] * sigmoid_f(gt[0]) * vl[0], gt[1] * sigmoid_f(gt[1]) * vl[1]); w.y = cvt_pk_bf16(gt[2] * sigmoid_f(gt[2]) * vl[2], gt[3] * sigmoid_f(gt[3]) * vl[3]);
;                         *(u32x2*)(ACT + (size_t)row * FF + j4) = w; }
	v_pk_fma_f32 v[234:235], v[18:19], v[114:115], v[98:99]
	v_pk_fma_f32 v[236:237], v[20:21], v[116:117], v[100:101]
	v_fmac_f32_dpp v230, v26, v126 row_shr:1 row_mask:0xf bank_mask:0xf
	v_fmac_f32_dpp v231, v27, v127 row_shr:1 row_mask:0xf bank_mask:0xf
	v_fmac_f32_dpp v232, v28, v128 row_shr:1 row_mask:0xf bank_mask:0xf
	v_fmac_f32_dpp v233, v29, v129 row_shr:1 row_mask:0xf bank_mask:0xf
	v_fmac_f32_dpp v234, v18, v122 row_shr:1 row_mask:0xf bank_mask:0xf
	v_fmac_f32_dpp v235, v19, v123 row_shr:1 row_mask:0xf bank_mask:0xf
	v_fmac_f32_dpp v236, v20, v124 row_shr:1 row_mask:0xf bank_mask:0xf
	v_fmac_f32_dpp v237, v21, v125 row_shr:1 row_mask:0xf bank_mask:0xf
	v_fmac_f32_dpp v230, v26, v110 row_shl:1 row_mask:0xf bank_mask:0xf
	v_fmac_f32_dpp v231, v27, v111 row_shl:1 row_mask:0xf bank_mask:0xf
	v_fmac_f32_dpp v232, v28, v112 row_shl:1 row_mask:0xf bank_mask:0xf
	v_fmac_f32_dpp v233, v29, v113 row_shl:1 row_mask:0xf bank_mask:0xf
	v_fmac_f32_dpp v234, v18, v102 row_shl:1 row_mask:0xf bank_mask:0xf
	v_fmac_f32_dpp v235, v19, v103 row_shl:1 row_mask:0xf bank_mask:0xf
	v_fmac_f32_dpp v236, v20, v104 row_shl:1 row_mask:0xf bank_mask:0xf
	v_fmac_f32_dpp v237, v21, v105 row_shl:1 row_mask:0xf bank_mask:0xf
	v_fmac_f32_dpp v230, v30, v214 row_ror:1 row_mask:0xf bank_mask:0xf
	v_fmac_f32_dpp v231, v31, v215 row_ror:1 row_mask:0xf bank_mask:0xf
	v_fmac_f32_dpp v232, v32, v216 row_ror:1 row_mask:0xf bank_mask:0xf
	v_fmac_f32_dpp v233, v33, v217 row_ror:1 row_mask:0xf bank_mask:0xf
	v_fmac_f32_dpp v234, v22, v218 row_ror:1 row_mask:0xf bank_mask:0xf
	v_fmac_f32_dpp v235, v23, v219 row_ror:1 row_mask:0xf bank_mask:0xf
	v_fmac_f32_dpp v236, v24, v220 row_ror:1 row_mask:0xf bank_mask:0xf
	v_fmac_f32_dpp v237, v25, v221 row_ror:1 row_mask:0xf bank_mask:0xf
	v_fmac_f32_dpp v230, v14, v222 row_ror:15 row_mask:0xf bank_mask:0xf
	v_fmac_f32_dpp v231, v15, v223 row_ror:15 row_mask:0xf bank_mask:0xf
	v_fmac_f32_dpp v232, v16, v224 row_ror:15 row_mask:0xf bank_mask:0xf
	v_fmac_f32_dpp v233, v17, v225 row_ror:15 row_mask:0xf bank_mask:0xf
	v_fmac_f32_dpp v234, v6, v226 row_ror:15 row_mask:0xf bank_mask:0xf
	v_fmac_f32_dpp v235, v7, v227 row_ror:15 row_mask:0xf bank_mask:0xf
	v_fmac_f32_dpp v236, v8, v228 row_ror:15 row_mask:0xf bank_mask:0xf
	v_fmac_f32_dpp v237, v9, v229 row_ror:15 row_mask:0xf bank_mask:0xf
	v_pk_mul_f32 v[174:175], v[230:231], s[34:35]
	v_pk_mul_f32 v[176:177], v[232:233], s[34:35]
	v_exp_f32_e32 v174, v174
	v_exp_f32_e32 v175, v175
	v_exp_f32_e32 v176, v176
	v_exp_f32_e32 v177, v177
	v_pk_add_f32 v[174:175], v[174:175], s[36:37]
	v_pk_add_f32 v[176:177], v[176:177], s[36:37]
	v_rcp_f32_e32 v174, v174
	v_rcp_f32_e32 v175, v175
	v_rcp_f32_e32 v176, v176
	v_rcp_f32_e32 v177, v177
	v_pk_mul_f32 v[174:175], v[230:231], v[174:175]
	v_pk_mul_f32 v[176:177], v[232:233], v[176:177]
	v_pk_mul_f32 v[174:175], v[174:175], v[234:235]
	v_pk_mul_f32 v[176:177], v[176:177], v[236:237]
	v_cvt_pk_bf16_f32 v96, v174, v175
	v_cvt_pk_bf16_f32 v97, v176, v177
	v_add_u32_e32 v239, 0x183000, v238
	global_store_dwordx4 v239, v[94:97], s[30:31]
	v_pk_fma_f32 v[230:231], v[14:15], v[118:119], v[106:107]
	v_pk_fma_f32 v[232:233], v[16:17], v[120:121], v[108:109]
	v_pk_fma_f32 v[234:235], v[6:7], v[114:115], v[98:99]
	v_pk_fma_f32 v[236:237], v[8:9], v[116:117], v[100:101]
	v_fmac_f32_dpp v230, v14, v126 row_shr:1 row_mask:0xf bank_mask:0xf
	v_fmac_f32_dpp v231, v15, v127 row_shr:1 row_mask:0xf bank_mask:0xf
	v_fmac_f32_dpp v232, v16, v128 row_shr:1 row_mask:0xf bank_mask:0xf
	v_fmac_f32_dpp v233, v17, v129 row_shr:1 row_mask:0xf bank_mask:0xf
	v_fmac_f32_dpp v234, v6, v122 row_shr:1 row_mask:0xf bank_mask:0xf
	v_fmac_f32_dpp v235, v7, v123 row_shr:1 row_mask:0xf bank_mask:0xf
	v_fmac_f32_dpp v236, v8, v124 row_shr:1 row_mask:0xf bank_mask:0xf
	v_fmac_f32_dpp v237, v9, v125 row_shr:1 row_mask:0xf bank_mask:0xf
	v_fmac_f32_dpp v230, v14, v110 row_shl:1 row_mask:0xf bank_mask:0xf
	v_fmac_f32_dpp v231, v15, v111 row_shl:1 row_mask:0xf bank_mask:0xf
	v_fmac_f32_dpp v232, v16, v112 row_shl:1 row_mask:0xf bank_mask:0xf
	v_fmac_f32_dpp v233, v17, v113 row_shl:1 row_mask:0xf bank_mask:0xf
	v_fmac_f32_dpp v234, v6, v102 row_shl:1 row_mask:0xf bank_mask:0xf
	v_fmac_f32_dpp v235, v7, v103 row_shl:1 row_mask:0xf bank_mask:0xf
	v_fmac_f32_dpp v236, v8, v104 row_shl:1 row_mask:0xf bank_mask:0xf
	v_fmac_f32_dpp v237, v9, v105 row_shl:1 row_mask:0xf bank_mask:0xf
	v_fmac_f32_dpp v230, v26, v214 row_ror:1 row_mask:0xf bank_mask:0xf
	v_fmac_f32_dpp v231, v27, v215 row_ror:1 row_mask:0xf bank_mask:0xf
; __device__ __forceinline__ unsigned cvt_pk_bf16(float lo, float hi) { unsigned r; asm volatile("v_cvt_pk_bf16_f32 %0, %1, %2" : "=v"(r) : "v"(lo), "v"(hi)); return r; }
; __device__ __forceinline__ float sigmoid_f(float x) { return fast_rcp(1.0f + fast_exp2(-1.4426950409f * x)); }
; #define PG8_BAR __builtin_amdgcn_s_barrier()
; template <class Epi, class SchedT, bool ALIGN_EPI, bool SP2>
; __device__ __forceinline__ void gemm_phase(LAS unsigned char* lds, const int ldk, const int nt, const SchedT& S, const Epi& E) {
;     ...
;         cur = nxt; cA = nA; cB = nB; ++ui;
;         if constexpr (ALIGN_EPI) { if (wr == 1) PG8_BAR; }
;     __device__ __forceinline__ void operator()(f32x4 (&acc)[2][2][4][2], const Unit& u, int wr, int wc, int fr, int fq) const {
;     ...
;             for (int ai = 0; ai < 2; ++ai) {
;                 const int grp = u.pm * 4 + ai * 2 + wr;
; #pragma unroll
;                 for (int m = 0; m < 4; ++m) {
;                     f32x4 cv[2];
; #pragma unroll
;                     for (int bj = 0; bj < 2; ++bj) {
;                         const f32x4 cur = acc[ai][bj][m][n], lo = acc[ai][bj][m > 0 ? m - 1 : 0][n], hi = acc[ai][bj][m < 3 ? m + 1 : 3][n];
;                         f32x4 pv, nv;
; #pragma unroll
;                         for (int idx = 0; idx < 4; ++idx) {
;                             const float y = (fr == 15) ? lo[idx] : cur[idx], z = (fr == 0) ? hi[idx] : cur[idx];
;                             pv[idx] = __int_as_float(__builtin_amdgcn_update_dpp(0, __float_as_int(y), 0x121, 0xf, 0xf, false));
;                             nv[idx] = __int_as_float(__builtin_amdgcn_update_dpp(0, __float_as_int(z), 0x12f, 0xf, 0xf, false));
;                         }
;                         cv[bj] = kc[bj][0] * pv + kc[bj][1] * cur + kc[bj][2] * nv + bc[bj];
;                     }
;                     const int row = row0 + ai * HALF + m * 16;
;                     const bool edge = (m == 0 && fr == 0) || (m == 3 && fr == 15);
;                     if (!edge) { const f32x4 gt = cv[0], vl = cv[1];
;                         u32x2 w; w.x = cvt_pk_bf16(gt[0] * sigmoid_f(gt[0]) * vl[0], gt[1] * sigmoid_f(gt[1]) * vl[1]); w.y = cvt_pk_bf16(gt[2] * sigmoid_f(gt[2]) * vl[2], gt[3] * sigmoid_f(gt[3]) * vl[3]);
;                         *(u32x2*)(ACT + (size_t)row * FF + j4) = w; }
	v_fmac_f32_dpp v232, v28, v216 row_ror:1 row_mask:0xf bank_mask:0xf
	v_fmac_f32_dpp v233, v29, v217 row_ror:1 row_mask:0xf bank_mask:0xf
	v_fmac_f32_dpp v234, v18, v218 row_ror:1 row_mask:0xf bank_mask:0xf
	v_fmac_f32_dpp v235, v19, v219 row_ror:1 row_mask:0xf bank_mask:0xf
	v_fmac_f32_dpp v236, v20, v220 row_ror:1 row_mask:0xf bank_mask:0xf
	v_fmac_f32_dpp v237, v21, v221 row_ror:1 row_mask:0xf bank_mask:0xf
	v_fmac_f32_dpp v230, v10, v222 row_ror:15 row_mask:0xf bank_mask:0xf
	v_fmac_f32_dpp v231, v11, v223 row_ror:15 row_mask:0xf bank_mask:0xf
	v_fmac_f32_dpp v232, v12, v224 row_ror:15 row_mask:0xf bank_mask:0xf
	v_fmac_f32_dpp v233, v13, v225 row_ror:15 row_mask:0xf bank_mask:0xf
	v_fmac_f32_dpp v234, v2, v226 row_ror:15 row_mask:0xf bank_mask:0xf
	v_fmac_f32_dpp v235, v3, v227 row_ror:15 row_mask:0xf bank_mask:0xf
	v_fmac_f32_dpp v236, v4, v228 row_ror:15 row_mask:0xf bank_mask:0xf
	v_fmac_f32_dpp v237, v5, v229 row_ror:15 row_mask:0xf bank_mask:0xf
	v_pk_mul_f32 v[174:175], v[230:231], s[34:35]
	v_pk_mul_f32 v[176:177], v[232:233], s[34:35]
	v_exp_f32_e32 v174, v174
	v_exp_f32_e32 v175, v175
	v_exp_f32_e32 v176, v176
	v_exp_f32_e32 v177, v177
	v_pk_add_f32 v[174:175], v[174:175], s[36:37]
	v_pk_add_f32 v[176:177], v[176:177], s[36:37]
	v_rcp_f32_e32 v174, v174
	v_rcp_f32_e32 v175, v175
	v_rcp_f32_e32 v176, v176
	v_rcp_f32_e32 v177, v177
	v_pk_mul_f32 v[174:175], v[230:231], v[174:175]
	v_pk_mul_f32 v[176:177], v[232:233], v[176:177]
	v_pk_mul_f32 v[174:175], v[174:175], v[234:235]
	v_pk_mul_f32 v[176:177], v[176:177], v[236:237]
	v_cvt_pk_bf16_f32 v92, v174, v175
	v_cvt_pk_bf16_f32 v93, v176, v177
	v_add_u32_e32 v239, 0x1ae000, v238
	global_store_dwordx4 v239, v[90:93], s[30:31]
	v_pk_fma_f32 v[230:231], v[10:11], v[118:119], v[106:107]
	v_pk_fma_f32 v[232:233], v[12:13], v[120:121], v[108:109]
	v_pk_fma_f32 v[234:235], v[2:3], v[114:115], v[98:99]
	v_pk_fma_f32 v[236:237], v[4:5], v[116:117], v[100:101]
	v_fmac_f32_dpp v230, v10, v126 row_shr:1 row_mask:0xf bank_mask:0xf
	v_fmac_f32_dpp v231, v11, v127 row_shr:1 row_mask:0xf bank_mask:0xf
	v_fmac_f32_dpp v232, v12, v128 row_shr:1 row_mask:0xf bank_mask:0xf
	v_fmac_f32_dpp v233, v13, v129 row_shr:1 row_mask:0xf bank_mask:0xf
	v_fmac_f32_dpp v234, v2, v122 row_shr:1 row_mask:0xf bank_mask:0xf
	v_fmac_f32_dpp v235, v3, v123 row_shr:1 row_mask:0xf bank_mask:0xf
	v_fmac_f32_dpp v236, v4, v124 row_shr:1 row_mask:0xf bank_mask:0xf
	v_fmac_f32_dpp v237, v5, v125 row_shr:1 row_mask:0xf bank_mask:0xf
	v_fmac_f32_dpp v230, v10, v110 row_shl:1 row_mask:0xf bank_mask:0xf
	v_fmac_f32_dpp v231, v11, v111 row_shl:1 row_mask:0xf bank_mask:0xf
	v_fmac_f32_dpp v232, v12, v112 row_shl:1 row_mask:0xf bank_mask:0xf
	v_fmac_f32_dpp v233, v13, v113 row_shl:1 row_mask:0xf bank_mask:0xf
	v_fmac_f32_dpp v234, v2, v102 row_shl:1 row_mask:0xf bank_mask:0xf
	v_fmac_f32_dpp v235, v3, v103 row_shl:1 row_mask:0xf bank_mask:0xf
	v_fmac_f32_dpp v236, v4, v104 row_shl:1 row_mask:0xf bank_mask:0xf
	v_fmac_f32_dpp v237, v5, v105 row_shl:1 row_mask:0xf bank_mask:0xf
	v_fmac_f32_dpp v230, v14, v214 row_ror:1 row_mask:0xf bank_mask:0xf
	v_fmac_f32_dpp v231, v15, v215 row_ror:1 row_mask:0xf bank_mask:0xf
	v_fmac_f32_dpp v232, v16, v216 row_ror:1 row_mask:0xf bank_mask:0xf
	v_fmac_f32_dpp v233, v17, v217 row_ror:1 row_mask:0xf bank_mask:0xf
	v_fmac_f32_dpp v234, v6, v218 row_ror:1 row_mask:0xf bank_mask:0xf
	v_fmac_f32_dpp v235, v7, v219 row_ror:1 row_mask:0xf bank_mask:0xf
	v_fmac_f32_dpp v236, v8, v220 row_ror:1 row_mask:0xf bank_mask:0xf
	v_fmac_f32_dpp v237, v9, v221 row_ror:1 row_mask:0xf bank_mask:0xf
	v_pk_mul_f32 v[174:175], v[230:231], s[34:35]
	v_pk_mul_f32 v[176:177], v[232:233], s[34:35]
	v_exp_f32_e32 v174, v174
	v_exp_f32_e32 v175, v175
	v_exp_f32_e32 v176, v176
	v_exp_f32_e32 v177, v177
	v_pk_add_f32 v[174:175], v[174:175], s[36:37]
	v_pk_add_f32 v[176:177], v[176:177], s[36:37]
	v_rcp_f32_e32 v174, v174
	v_rcp_f32_e32 v175, v175
	v_rcp_f32_e32 v176, v176
	v_rcp_f32_e32 v177, v177
	v_pk_mul_f32 v[174:175], v[230:231], v[174:175]
	v_pk_mul_f32 v[176:177], v[232:233], v[176:177]
	v_pk_mul_f32 v[174:175], v[174:175], v[234:235]
	v_pk_mul_f32 v[176:177], v[176:177], v[236:237]
	v_cvt_pk_bf16_f32 v80, v174, v175
	v_cvt_pk_bf16_f32 v81, v176, v177
	v_add_u32_e32 v239, 0x1d9000, v238
	s_and_saveexec_b64 s[16:17], s[40:41]
	global_store_dwordx4 v239, v[78:81], s[30:31]
	s_or_b64 exec, exec, s[16:17]
	s_movk_i32 s94, 0x1000
	s_movk_i32 s95, 0x3000
	s_and_b64 vcc, exec, s[50:51]
	s_mov_b64 s[12:13], -1
	s_cbranch_vccnz .LBB0_746

; #define PG8_STAGE(bufoff, gbase, voff) do { _Pragma("unroll") for (int _i = 0; _i < 2; ++_i) \
;         __builtin_amdgcn_global_load_lds((const __attribute__((address_space(1))) unsigned*)((const char*)(gbase) + (voff)[_i]), (LAS unsigned*)(lds + (bufoff) + ldsw + _i * 8192), 16, 0, 0); } while (0)
; #define PG8_LDA(dst, b, h) do { _Pragma("unroll") for (int m = 0; m < 4; ++m) _Pragma("unroll") for (int k = 0; k < 2; ++k) dst[m][k] = *(const LAS bf16x8*)(lds + PG8_SA(b, h) + aoff + m * 2048 + k * 1024); } while (0)
; #define PG8_LDB(dst, b, h) do { _Pragma("unroll") for (int n = 0; n < 2; ++n) _Pragma("unroll") for (int k = 0; k < 2; ++k) dst[n][k] = *(const LAS bf16x8*)(lds + PG8_SB(b, h) + boff + n * 2048 + k * 1024); } while (0)
; #define PG8_MMA(ai, bj, At, Bt) do { __builtin_amdgcn_s_setprio(1); _Pragma("unroll") for (int m = 0; m < 4; ++m) _Pragma("unroll") for (int n = 0; n < 2; ++n) _Pragma("unroll") for (int k = 0; k < 2; ++k) \
;         acc[ai][bj][m][n] = __builtin_amdgcn_mfma_f32_16x16x32_bf16(Bt[n][k], At[m][k], acc[ai][bj][m][n], 0, 0, 0); __builtin_amdgcn_s_setprio(0); } while (0)
; #define PG8_WAIT_V(n) asm volatile("s_waitcnt vmcnt(" #n ")" ::: "memory")
; #define PG8_WAIT_L(n) asm volatile("s_waitcnt lgkmcnt(" #n ")" ::: "memory")
; #define PG8_BAR __builtin_amdgcn_s_barrier()
; template <class Epi, class SchedT, bool ALIGN_EPI, bool SP2>
; __device__ __forceinline__ void gemm_phase(LAS unsigned char* lds, const int ldk, const int nt, const SchedT& S, const Epi& E) {
;     ...
;             const bool last = (t == nt - 2);
;             const char* a1 = cA + (size_t)(t + 1) * kstep;
;             const char* a2 = last ? nA : cA + (size_t)(t + 2) * kstep; const char* b2 = last ? nB : cB + (size_t)(t + 2) * kstep;
;             const char* a3 = a2 + kstep; const char* b3 = b2 + kstep;
;             if constexpr (SP2) {
;             PG8_LDB(B0, 0, 0); PG8_LDB(B1, 0, 1); PG8_SCHED; PG8_LDA(At, 0, 0); PG8_STAGE(PG8_SA(1, 1), a1 + hstep, voffA);
;             PG8_WAIT_V(8); PG8_WAIT_L(0); PG8_BAR; PG8_MMA(0, 0, At, B0); PG8_MMA(0, 1, At, B1); PG8_BAR; PG8_SCHED;
;             PG8_LDA(At, 0, 1); PG8_STAGE(PG8_SB(0, 0), b2, voffB); PG8_STAGE(PG8_SB(0, 1), b2 + hstepB, voffB); PG8_STAGE(PG8_SA(0, 0), a2, voffA);
;             PG8_WAIT_V(8); PG8_WAIT_L(0); PG8_BAR; PG8_MMA(1, 0, At, B0); PG8_MMA(1, 1, At, B1); PG8_BAR; PG8_SCHED;
.LBB0_948:
	s_add_u32 s16, s12, 0x100
	s_addc_u32 s17, s13, 0
	s_add_i32 s64, 0, 0x10000
	s_cmpk_eq_i32 s83, 0x52
	s_cselect_b32 s47, s1, s17
	s_cselect_b32 s46, s0, s16
	v_add_u32_e32 v144, s64, v147
	s_cselect_b32 s45, s43, s82
	s_cselect_b32 s44, s42, s81
	s_add_i32 s65, 0, 0x14000
	ds_read_b128 v[140:143], v144
	ds_read_b128 v[150:153], v144 offset:1024
	ds_read_b128 v[154:157], v144 offset:2048
	ds_read_b128 v[158:161], v144 offset:3072
	v_add_u32_e32 v144, s65, v147
	ds_read_b128 v[174:177], v144
	ds_read_b128 v[178:181], v144 offset:1024
	ds_read_b128 v[182:185], v144 offset:2048
	ds_read_b128 v[186:189], v144 offset:3072
	v_lshl_add_u64 v[144:145], s[12:13], 0, v[136:137]
	s_add_i32 m0, s53, 0xc000
	ds_read_b128 v[190:193], v149
	ds_read_b128 v[194:197], v149 offset:1024
	ds_read_b128 v[198:201], v149 offset:2048
	ds_read_b128 v[202:205], v149 offset:3072
	ds_read_b128 v[206:209], v149 offset:4096
	ds_read_b128 v[210:213], v149 offset:5120
	ds_read_b128 v[214:217], v149 offset:6144
	ds_read_b128 v[218:221], v149 offset:7168
	global_load_lds_dwordx4 v[144:145], off
	v_lshl_add_u64 v[144:145], s[12:13], 0, v[138:139]
	s_add_i32 m0, s53, 0xe000
	s_nop 0
	global_load_lds_dwordx4 v[144:145], off
	s_waitcnt vmcnt(8)
	s_waitcnt lgkmcnt(0)
	s_barrier
	s_waitcnt lgkmcnt(0)
	v_mfma_f32_16x16x32_bf16 v[126:129], v[140:143], v[190:193], v[126:129]
	v_mfma_f32_16x16x32_bf16 v[122:125], v[154:157], v[190:193], v[122:125]
	v_mfma_f32_16x16x32_bf16 v[110:113], v[140:143], v[198:201], v[110:113]
	v_mfma_f32_16x16x32_bf16 v[106:109], v[154:157], v[198:201], v[106:109]
	v_mfma_f32_16x16x32_bf16 v[94:97], v[140:143], v[206:209], v[94:97]
	v_mfma_f32_16x16x32_bf16 v[90:93], v[154:157], v[206:209], v[90:93]
	v_mfma_f32_16x16x32_bf16 v[78:81], v[140:143], v[214:217], v[78:81]
	v_mfma_f32_16x16x32_bf16 v[74:77], v[154:157], v[214:217], v[74:77]
	v_mfma_f32_16x16x32_bf16 v[126:129], v[150:153], v[194:197], v[126:129]
	v_mfma_f32_16x16x32_bf16 v[122:125], v[158:161], v[194:197], v[122:125]
	v_mfma_f32_16x16x32_bf16 v[110:113], v[150:153], v[202:205], v[110:113]
	v_mfma_f32_16x16x32_bf16 v[106:109], v[158:161], v[202:205], v[106:109]
	v_mfma_f32_16x16x32_bf16 v[94:97], v[150:153], v[210:213], v[94:97]
	v_mfma_f32_16x16x32_bf16 v[90:93], v[158:161], v[210:213], v[90:93]
	v_mfma_f32_16x16x32_bf16 v[78:81], v[150:153], v[218:221], v[78:81]
	v_mfma_f32_16x16x32_bf16 v[74:77], v[158:161], v[218:221], v[74:77]
	v_mfma_f32_16x16x32_bf16 v[118:121], v[174:177], v[190:193], v[118:121]
	v_mfma_f32_16x16x32_bf16 v[114:117], v[182:185], v[190:193], v[114:117]
	v_mfma_f32_16x16x32_bf16 v[102:105], v[174:177], v[198:201], v[102:105]
	v_mfma_f32_16x16x32_bf16 v[98:101], v[182:185], v[198:201], v[98:101]
	v_mfma_f32_16x16x32_bf16 v[86:89], v[174:177], v[206:209], v[86:89]
	v_mfma_f32_16x16x32_bf16 v[82:85], v[182:185], v[206:209], v[82:85]
	v_mfma_f32_16x16x32_bf16 v[70:73], v[174:177], v[214:217], v[70:73]
	v_mfma_f32_16x16x32_bf16 v[66:69], v[182:185], v[214:217], v[66:69]
	v_mfma_f32_16x16x32_bf16 v[118:121], v[178:181], v[194:197], v[118:121]
	v_mfma_f32_16x16x32_bf16 v[114:117], v[186:189], v[194:197], v[114:117]
	v_mfma_f32_16x16x32_bf16 v[102:105], v[178:181], v[202:205], v[102:105]
	v_mfma_f32_16x16x32_bf16 v[98:101], v[186:189], v[202:205], v[98:101]
	v_mfma_f32_16x16x32_bf16 v[86:89], v[178:181], v[210:213], v[86:89]
	v_mfma_f32_16x16x32_bf16 v[82:85], v[186:189], v[210:213], v[82:85]
	v_mfma_f32_16x16x32_bf16 v[70:73], v[178:181], v[218:221], v[70:73]
	v_mfma_f32_16x16x32_bf16 v[66:69], v[186:189], v[218:221], v[66:69]
	s_barrier
	s_add_i32 s12, s64, s52
	v_lshl_add_u64 v[144:145], s[44:45], 0, v[0:1]
	s_mov_b32 m0, s12
	ds_read_b128 v[190:193], v149 offset:16384
	ds_read_b128 v[194:197], v149 offset:17408
	ds_read_b128 v[198:201], v149 offset:18432
	ds_read_b128 v[202:205], v149 offset:19456
	ds_read_b128 v[206:209], v149 offset:20480
	ds_read_b128 v[210:213], v149 offset:21504
	ds_read_b128 v[214:217], v149 offset:22528
	ds_read_b128 v[218:221], v149 offset:23552
	global_load_lds_dwordx4 v[144:145], off
	s_add_i32 m0, s12, 0x2000
	s_add_u32 s12, s44, 0x56000
	v_lshl_add_u64 v[222:223], s[44:45], 0, v[134:135]
	s_addc_u32 s13, s45, 0
	s_add_i32 s64, s65, s52
	global_load_lds_dwordx4 v[222:223], off
	v_lshl_add_u64 v[224:225], s[12:13], 0, v[0:1]
	s_mov_b32 m0, s64
	v_lshl_add_u64 v[226:227], s[46:47], 0, v[132:133]
	global_load_lds_dwordx4 v[224:225], off
	v_lshl_add_u64 v[224:225], s[12:13], 0, v[134:135]
	s_add_i32 m0, s64, 0x2000
	s_nop 0
	global_load_lds_dwordx4 v[224:225], off
	v_lshl_add_u64 v[224:225], s[46:47], 0, v[130:131]
	s_mov_b32 m0, s53
	s_nop 0
	global_load_lds_dwordx4 v[224:225], off
	s_mov_b32 m0, s54
	s_nop 0
	global_load_lds_dwordx4 v[226:227], off
	s_waitcnt vmcnt(8)
	s_waitcnt lgkmcnt(0)
	s_barrier
; #define PG8_STAGE(bufoff, gbase, voff) do { _Pragma("unroll") for (int _i = 0; _i < 2; ++_i) \
;         __builtin_amdgcn_global_load_lds((const __attribute__((address_space(1))) unsigned*)((const char*)(gbase) + (voff)[_i]), (LAS unsigned*)(lds + (bufoff) + ldsw + _i * 8192), 16, 0, 0); } while (0)
; #define PG8_LDA(dst, b, h) do { _Pragma("unroll") for (int m = 0; m < 4; ++m) _Pragma("unroll") for (int k = 0; k < 2; ++k) dst[m][k] = *(const LAS bf16x8*)(lds + PG8_SA(b, h) + aoff + m * 2048 + k * 1024); } while (0)
; #define PG8_LDB(dst, b, h) do { _Pragma("unroll") for (int n = 0; n < 2; ++n) _Pragma("unroll") for (int k = 0; k < 2; ++k) dst[n][k] = *(const LAS bf16x8*)(lds + PG8_SB(b, h) + boff + n * 2048 + k * 1024); } while (0)
; #define PG8_MMA(ai, bj, At, Bt) do { __builtin_amdgcn_s_setprio(1); _Pragma("unroll") for (int m = 0; m < 4; ++m) _Pragma("unroll") for (int n = 0; n < 2; ++n) _Pragma("unroll") for (int k = 0; k < 2; ++k) \
;         acc[ai][bj][m][n] = __builtin_amdgcn_mfma_f32_16x16x32_bf16(Bt[n][k], At[m][k], acc[ai][bj][m][n], 0, 0, 0); __builtin_amdgcn_s_setprio(0); } while (0)
; #define PG8_WAIT_V(n) asm volatile("s_waitcnt vmcnt(" #n ")" ::: "memory")
; #define PG8_WAIT_L(n) asm volatile("s_waitcnt lgkmcnt(" #n ")" ::: "memory")
; #define PG8_BAR __builtin_amdgcn_s_barrier()
; #define PG8_SCHED __builtin_amdgcn_sched_barrier(0)
; template <class Epi, class SchedT, bool ALIGN_EPI, bool SP2>
; __device__ __forceinline__ void gemm_phase(LAS unsigned char* lds, const int ldk, const int nt, const SchedT& S, const Epi& E) {
;     ...
;             PG8_WAIT_V(8); PG8_WAIT_L(0); PG8_BAR; PG8_MMA(1, 0, At, B0); PG8_MMA(1, 1, At, B1); PG8_BAR; PG8_SCHED;
;             PG8_LDB(B0, 1, 0); PG8_LDB(B1, 1, 1); PG8_SCHED; PG8_LDA(At, 1, 0); PG8_STAGE(PG8_SA(0, 1), a2 + hstep, voffA);
;             PG8_WAIT_V(8); PG8_WAIT_L(0); PG8_BAR; PG8_MMA(0, 0, At, B0); PG8_MMA(0, 1, At, B1); PG8_BAR; PG8_SCHED;
	s_waitcnt lgkmcnt(0)
	v_mfma_f32_16x16x32_bf16 v[62:65], v[140:143], v[190:193], v[62:65]
	v_mfma_f32_16x16x32_bf16 v[58:61], v[154:157], v[190:193], v[58:61]
	v_mfma_f32_16x16x32_bf16 v[46:49], v[140:143], v[198:201], v[46:49]
	v_mfma_f32_16x16x32_bf16 v[42:45], v[154:157], v[198:201], v[42:45]
	v_mfma_f32_16x16x32_bf16 v[30:33], v[140:143], v[206:209], v[30:33]
	v_mfma_f32_16x16x32_bf16 v[26:29], v[154:157], v[206:209], v[26:29]
	v_mfma_f32_16x16x32_bf16 v[14:17], v[140:143], v[214:217], v[14:17]
	v_mfma_f32_16x16x32_bf16 v[10:13], v[154:157], v[214:217], v[10:13]
	v_mfma_f32_16x16x32_bf16 v[62:65], v[150:153], v[194:197], v[62:65]
	v_mfma_f32_16x16x32_bf16 v[58:61], v[158:161], v[194:197], v[58:61]
	v_mfma_f32_16x16x32_bf16 v[46:49], v[150:153], v[202:205], v[46:49]
	v_mfma_f32_16x16x32_bf16 v[42:45], v[158:161], v[202:205], v[42:45]
	v_mfma_f32_16x16x32_bf16 v[30:33], v[150:153], v[210:213], v[30:33]
	v_mfma_f32_16x16x32_bf16 v[26:29], v[158:161], v[210:213], v[26:29]
	v_mfma_f32_16x16x32_bf16 v[14:17], v[150:153], v[218:221], v[14:17]
	v_mfma_f32_16x16x32_bf16 v[10:13], v[158:161], v[218:221], v[10:13]
	v_mfma_f32_16x16x32_bf16 v[54:57], v[174:177], v[190:193], v[54:57]
	v_mfma_f32_16x16x32_bf16 v[50:53], v[182:185], v[190:193], v[50:53]
	v_mfma_f32_16x16x32_bf16 v[38:41], v[174:177], v[198:201], v[38:41]
	v_mfma_f32_16x16x32_bf16 v[34:37], v[182:185], v[198:201], v[34:37]
	v_mfma_f32_16x16x32_bf16 v[22:25], v[174:177], v[206:209], v[22:25]
	v_mfma_f32_16x16x32_bf16 v[18:21], v[182:185], v[206:209], v[18:21]
	v_mfma_f32_16x16x32_bf16 v[6:9], v[174:177], v[214:217], v[6:9]
	v_mfma_f32_16x16x32_bf16 v[2:5], v[182:185], v[214:217], v[2:5]
	v_mfma_f32_16x16x32_bf16 v[54:57], v[178:181], v[194:197], v[54:57]
	v_mfma_f32_16x16x32_bf16 v[50:53], v[186:189], v[194:197], v[50:53]
	v_mfma_f32_16x16x32_bf16 v[38:41], v[178:181], v[202:205], v[38:41]
	v_mfma_f32_16x16x32_bf16 v[34:37], v[186:189], v[202:205], v[34:37]
	v_mfma_f32_16x16x32_bf16 v[22:25], v[178:181], v[210:213], v[22:25]
	v_mfma_f32_16x16x32_bf16 v[18:21], v[186:189], v[210:213], v[18:21]
	v_mfma_f32_16x16x32_bf16 v[6:9], v[178:181], v[218:221], v[6:9]
	v_mfma_f32_16x16x32_bf16 v[2:5], v[186:189], v[218:221], v[2:5]
	s_barrier
	s_add_i32 s64, 0, 0x18000
	s_add_i32 s65, 0, 0x1c000
	v_add_u32_e32 v158, s64, v147
	v_add_u32_e32 v186, s65, v147
	ds_read_b128 v[140:143], v158
	ds_read_b128 v[150:153], v158 offset:1024
	ds_read_b128 v[154:157], v158 offset:2048
	ds_read_b128 v[158:161], v158 offset:3072
	ds_read_b128 v[174:177], v186
	ds_read_b128 v[178:181], v186 offset:1024
	ds_read_b128 v[182:185], v186 offset:2048
	ds_read_b128 v[186:189], v186 offset:3072
	s_add_u32 s12, s46, 0x158000
	s_addc_u32 s13, s47, 0
	s_mov_b32 m0, s55
	v_lshl_add_u64 v[228:229], s[12:13], 0, v[130:131]
	ds_read_b128 v[190:193], v149 offset:32768
	ds_read_b128 v[194:197], v149 offset:33792
	ds_read_b128 v[198:201], v149 offset:34816
	ds_read_b128 v[202:205], v149 offset:35840
	ds_read_b128 v[206:209], v149 offset:36864
	ds_read_b128 v[210:213], v149 offset:37888
	ds_read_b128 v[214:217], v149 offset:38912
	ds_read_b128 v[218:221], v149 offset:39936
	global_load_lds_dwordx4 v[228:229], off
	v_lshl_add_u64 v[228:229], s[12:13], 0, v[132:133]
	s_mov_b32 m0, s56
	s_nop 0
	global_load_lds_dwordx4 v[228:229], off
	s_waitcnt vmcnt(8)
	s_waitcnt lgkmcnt(0)
	s_barrier
	s_waitcnt lgkmcnt(0)
	v_mfma_f32_16x16x32_bf16 v[126:129], v[140:143], v[190:193], v[126:129]
	v_mfma_f32_16x16x32_bf16 v[122:125], v[154:157], v[190:193], v[122:125]
	v_mfma_f32_16x16x32_bf16 v[110:113], v[140:143], v[198:201], v[110:113]
	v_mfma_f32_16x16x32_bf16 v[106:109], v[154:157], v[198:201], v[106:109]
	v_mfma_f32_16x16x32_bf16 v[94:97], v[140:143], v[206:209], v[94:97]
	v_mfma_f32_16x16x32_bf16 v[90:93], v[154:157], v[206:209], v[90:93]
	v_mfma_f32_16x16x32_bf16 v[78:81], v[140:143], v[214:217], v[78:81]
	v_mfma_f32_16x16x32_bf16 v[74:77], v[154:157], v[214:217], v[74:77]
	v_mfma_f32_16x16x32_bf16 v[126:129], v[150:153], v[194:197], v[126:129]
	v_mfma_f32_16x16x32_bf16 v[122:125], v[158:161], v[194:197], v[122:125]
	v_mfma_f32_16x16x32_bf16 v[110:113], v[150:153], v[202:205], v[110:113]
	v_mfma_f32_16x16x32_bf16 v[106:109], v[158:161], v[202:205], v[106:109]
	v_mfma_f32_16x16x32_bf16 v[94:97], v[150:153], v[210:213], v[94:97]
	v_mfma_f32_16x16x32_bf16 v[90:93], v[158:161], v[210:213], v[90:93]
	v_mfma_f32_16x16x32_bf16 v[78:81], v[150:153], v[218:221], v[78:81]
	v_mfma_f32_16x16x32_bf16 v[74:77], v[158:161], v[218:221], v[74:77]
	v_mfma_f32_16x16x32_bf16 v[118:121], v[174:177], v[190:193], v[118:121]
	v_mfma_f32_16x16x32_bf16 v[114:117], v[182:185], v[190:193], v[114:117]
	v_mfma_f32_16x16x32_bf16 v[102:105], v[174:177], v[198:201], v[102:105]
	v_mfma_f32_16x16x32_bf16 v[98:101], v[182:185], v[198:201], v[98:101]
	v_mfma_f32_16x16x32_bf16 v[86:89], v[174:177], v[206:209], v[86:89]
	v_mfma_f32_16x16x32_bf16 v[82:85], v[182:185], v[206:209], v[82:85]
	v_mfma_f32_16x16x32_bf16 v[70:73], v[174:177], v[214:217], v[70:73]
	v_mfma_f32_16x16x32_bf16 v[66:69], v[182:185], v[214:217], v[66:69]
	v_mfma_f32_16x16x32_bf16 v[118:121], v[178:181], v[194:197], v[118:121]
	v_mfma_f32_16x16x32_bf16 v[114:117], v[186:189], v[194:197], v[114:117]
	v_mfma_f32_16x16x32_bf16 v[102:105], v[178:181], v[202:205], v[102:105]
	v_mfma_f32_16x16x32_bf16 v[98:101], v[186:189], v[202:205], v[98:101]
	v_mfma_f32_16x16x32_bf16 v[86:89], v[178:181], v[210:213], v[86:89]
	v_mfma_f32_16x16x32_bf16 v[82:85], v[186:189], v[210:213], v[82:85]
	v_mfma_f32_16x16x32_bf16 v[70:73], v[178:181], v[218:221], v[70:73]
	v_mfma_f32_16x16x32_bf16 v[66:69], v[186:189], v[218:221], v[66:69]
	s_barrier
; #define PG8_STAGE(bufoff, gbase, voff) do { _Pragma("unroll") for (int _i = 0; _i < 2; ++_i) \
;         __builtin_amdgcn_global_load_lds((const __attribute__((address_space(1))) unsigned*)((const char*)(gbase) + (voff)[_i]), (LAS unsigned*)(lds + (bufoff) + ldsw + _i * 8192), 16, 0, 0); } while (0)
; #define PG8_LDA(dst, b, h) do { _Pragma("unroll") for (int m = 0; m < 4; ++m) _Pragma("unroll") for (int k = 0; k < 2; ++k) dst[m][k] = *(const LAS bf16x8*)(lds + PG8_SA(b, h) + aoff + m * 2048 + k * 1024); } while (0)
; #define PG8_MMA(ai, bj, At, Bt) do { __builtin_amdgcn_s_setprio(1); _Pragma("unroll") for (int m = 0; m < 4; ++m) _Pragma("unroll") for (int n = 0; n < 2; ++n) _Pragma("unroll") for (int k = 0; k < 2; ++k) \
;         acc[ai][bj][m][n] = __builtin_amdgcn_mfma_f32_16x16x32_bf16(Bt[n][k], At[m][k], acc[ai][bj][m][n], 0, 0, 0); __builtin_amdgcn_s_setprio(0); } while (0)
; #define PG8_WAIT_V(n) asm volatile("s_waitcnt vmcnt(" #n ")" ::: "memory")
; #define PG8_WAIT_L(n) asm volatile("s_waitcnt lgkmcnt(" #n ")" ::: "memory")
; #define PG8_BAR __builtin_amdgcn_s_barrier()
; #define PG8_SCHED __builtin_amdgcn_sched_barrier(0)
; template <class Epi, class SchedT, bool ALIGN_EPI, bool SP2>
; __device__ __forceinline__ void gemm_phase(LAS unsigned char* lds, const int ldk, const int nt, const SchedT& S, const Epi& E) {
;     ...
;             PG8_LDA(At, 1, 1); PG8_STAGE(PG8_SB(1, 0), b3, voffB); PG8_STAGE(PG8_SB(1, 1), b3 + hstepB, voffB); PG8_STAGE(PG8_SA(1, 0), a3, voffA);
;             PG8_WAIT_V(8); PG8_WAIT_L(0); PG8_BAR; PG8_MMA(1, 0, At, B0); PG8_MMA(1, 1, At, B1); PG8_BAR; PG8_SCHED;
;     __device__ __forceinline__ void operator()(f32x4 (&acc)[2][2][4][2], const Unit& u, int wr, int wc, int fr, int fq) const {
;     ...
;                 const int row = row0 + ai * HALF + m * 16; float sq = 0.f;
; #pragma unroll
;                 for (int bj = 0; bj < 2; ++bj) {
;                     const size_t off = (size_t)row * D + col0 + bj * 32;
;                     const u32x4 xw = *(const u32x4*)(xin + off);
	s_add_i32 s12, s64, s52
	v_lshl_add_u64 v[144:145], v[144:145], 0, s[24:25]
	s_mov_b32 m0, s12
	ds_read_b128 v[190:193], v149 offset:49152
	ds_read_b128 v[194:197], v149 offset:50176
	ds_read_b128 v[198:201], v149 offset:51200
	ds_read_b128 v[202:205], v149 offset:52224
	ds_read_b128 v[206:209], v149 offset:53248
	ds_read_b128 v[210:213], v149 offset:54272
	ds_read_b128 v[214:217], v149 offset:55296
	ds_read_b128 v[218:221], v149 offset:56320
	global_load_lds_dwordx4 v[144:145], off
	s_add_i32 m0, s12, 0x2000
	s_add_u32 s12, s44, 0x56080
	v_lshl_add_u64 v[144:145], v[222:223], 0, s[24:25]
	s_addc_u32 s13, s45, 0
	s_add_i32 s44, s65, s52
	global_load_lds_dwordx4 v[144:145], off
	v_lshl_add_u64 v[144:145], s[12:13], 0, v[0:1]
	s_mov_b32 m0, s44
	s_nop 0
	global_load_lds_dwordx4 v[144:145], off
	v_lshl_add_u64 v[144:145], s[12:13], 0, v[134:135]
	s_add_i32 m0, s44, 0x2000
	s_nop 0
	global_load_lds_dwordx4 v[144:145], off
	v_lshl_add_u64 v[144:145], v[224:225], 0, s[24:25]
	s_mov_b32 m0, s58
	s_nop 0
	global_load_lds_dwordx4 v[144:145], off
	v_lshl_add_u64 v[144:145], v[226:227], 0, s[24:25]
	s_mov_b32 m0, s59
	s_nop 0
	global_load_lds_dwordx4 v[144:145], off
	s_waitcnt vmcnt(8)
	s_waitcnt lgkmcnt(0)
	s_barrier
	s_waitcnt lgkmcnt(0)
	v_mfma_f32_16x16x32_bf16 v[62:65], v[140:143], v[190:193], v[62:65]
	v_mfma_f32_16x16x32_bf16 v[58:61], v[154:157], v[190:193], v[58:61]
	v_mfma_f32_16x16x32_bf16 v[46:49], v[140:143], v[198:201], v[46:49]
	v_mfma_f32_16x16x32_bf16 v[42:45], v[154:157], v[198:201], v[42:45]
	v_mfma_f32_16x16x32_bf16 v[30:33], v[140:143], v[206:209], v[30:33]
	v_mfma_f32_16x16x32_bf16 v[26:29], v[154:157], v[206:209], v[26:29]
	v_mfma_f32_16x16x32_bf16 v[14:17], v[140:143], v[214:217], v[14:17]
	v_mfma_f32_16x16x32_bf16 v[10:13], v[154:157], v[214:217], v[10:13]
	v_mfma_f32_16x16x32_bf16 v[62:65], v[150:153], v[194:197], v[62:65]
	v_mfma_f32_16x16x32_bf16 v[58:61], v[158:161], v[194:197], v[58:61]
	v_mfma_f32_16x16x32_bf16 v[46:49], v[150:153], v[202:205], v[46:49]
	v_mfma_f32_16x16x32_bf16 v[42:45], v[158:161], v[202:205], v[42:45]
	v_mfma_f32_16x16x32_bf16 v[30:33], v[150:153], v[210:213], v[30:33]
	v_mfma_f32_16x16x32_bf16 v[26:29], v[158:161], v[210:213], v[26:29]
	v_mfma_f32_16x16x32_bf16 v[14:17], v[150:153], v[218:221], v[14:17]
	v_mfma_f32_16x16x32_bf16 v[10:13], v[158:161], v[218:221], v[10:13]
	v_mfma_f32_16x16x32_bf16 v[54:57], v[174:177], v[190:193], v[54:57]
	v_mfma_f32_16x16x32_bf16 v[50:53], v[182:185], v[190:193], v[50:53]
	v_mfma_f32_16x16x32_bf16 v[38:41], v[174:177], v[198:201], v[38:41]
	v_mfma_f32_16x16x32_bf16 v[34:37], v[182:185], v[198:201], v[34:37]
	v_mfma_f32_16x16x32_bf16 v[22:25], v[174:177], v[206:209], v[22:25]
	v_mfma_f32_16x16x32_bf16 v[18:21], v[182:185], v[206:209], v[18:21]
	v_mfma_f32_16x16x32_bf16 v[6:9], v[174:177], v[214:217], v[6:9]
	v_mfma_f32_16x16x32_bf16 v[2:5], v[182:185], v[214:217], v[2:5]
	v_mfma_f32_16x16x32_bf16 v[54:57], v[178:181], v[194:197], v[54:57]
	v_mfma_f32_16x16x32_bf16 v[50:53], v[186:189], v[194:197], v[50:53]
	v_mfma_f32_16x16x32_bf16 v[38:41], v[178:181], v[202:205], v[38:41]
	v_mfma_f32_16x16x32_bf16 v[34:37], v[186:189], v[202:205], v[34:37]
	v_mfma_f32_16x16x32_bf16 v[22:25], v[178:181], v[210:213], v[22:25]
	v_mfma_f32_16x16x32_bf16 v[18:21], v[186:189], v[210:213], v[18:21]
	v_mfma_f32_16x16x32_bf16 v[6:9], v[178:181], v[218:221], v[6:9]
	v_mfma_f32_16x16x32_bf16 v[2:5], v[186:189], v[218:221], v[2:5]
	s_barrier
	s_add_i32 s83, s83, 2
	s_add_u32 s81, s81, 0x100
	s_addc_u32 s82, s82, 0
	s_cmpk_gt_u32 s83, 0x53
	s_mov_b64 s[12:13], s[16:17]
	s_cbranch_scc0 .LBB0_948
	s_setprio 2
	v_lshl_add_u32 v142, s63, 8, v146
	v_lshl_or_b32 v140, s22, 8, v148
	v_lshlrev_b32_e32 v141, 12, v142
	v_lshl_add_u32 v150, v140, 1, v141
	v_add_u32_e32 v151, 0x10000, v150
	v_add_u32_e32 v152, 0x20000, v150
	v_add_u32_e32 v153, 0x30000, v150
	v_add_u32_e32 v154, 0x80000, v150
	v_add_u32_e32 v155, 0x90000, v150
	v_add_u32_e32 v156, 0xa0000, v150
	v_add_u32_e32 v157, 0xb0000, v150
	global_load_dwordx4 v[174:177], v150, s[20:21]
	global_load_dwordx4 v[178:181], v150, s[20:21] offset:64
	global_load_dwordx4 v[182:185], v151, s[20:21]
	global_load_dwordx4 v[186:189], v151, s[20:21] offset:64
	global_load_dwordx4 v[190:193], v152, s[20:21]
	global_load_dwordx4 v[194:197], v152, s[20:21] offset:64
	global_load_dwordx4 v[198:201], v153, s[20:21]
	global_load_dwordx4 v[202:205], v153, s[20:21] offset:64
	global_load_dwordx4 v[206:209], v154, s[20:21]
	global_load_dwordx4 v[210:213], v154, s[20:21] offset:64
	global_load_dwordx4 v[214:217], v155, s[20:21]
	global_load_dwordx4 v[218:221], v155, s[20:21] offset:64
	global_load_dwordx4 v[222:225], v156, s[20:21]
	global_load_dwordx4 v[226:229], v156, s[20:21] offset:64
	global_load_dwordx4 v[230:233], v157, s[20:21]
	global_load_dwordx4 v[234:237], v157, s[20:21] offset:64
	s_lshl_b32 s44, s22, 4
	s_lshl_b32 s45, s57, 2
	s_add_i32 s44, s44, s45
	v_lshl_add_u32 v158, v142, 7, s44
	v_add_u32_e32 v159, 0x1000, v158
	v_add_u32_e32 v160, 0x4000, v158
	v_add_u32_e32 v161, 0x5000, v158
	v_xor_b32_e32 v239, 16, v241
	v_xor_b32_e32 v252, 32, v241
	v_lshlrev_b32_e32 v239, 2, v239
	v_lshlrev_b32_e32 v252, 2, v252
	s_and_b64 vcc, exec, s[40:41]
	s_cbranch_vccnz .Lg0bar_p7
	s_setprio 1
	s_branch .LBB0_951
.Lg0bar_p7:
	s_barrier
; __device__ __forceinline__ float bf_lo(unsigned w) { return __uint_as_float(w << 16); }
; __device__ __forceinline__ float bf_hi(unsigned w) { return __uint_as_float(w & 0xffff0000u); }
; __device__ __forceinline__ u32x4 pack8(f32x4 a, f32x4 b) { u32x4 w; w.x = cvt_pk_bf16(a[0], a[1]); w.y = cvt_pk_bf16(a[2], a[3]); w.z = cvt_pk_bf16(b[0], b[1]); w.w = cvt_pk_bf16(b[2], b[3]); return w; }
;     __device__ __forceinline__ void operator()(f32x4 (&acc)[2][2][4][2], const Unit& u, int wr, int wc, int fr, int fq) const {
;     ...
;                 const int row = row0 + ai * HALF + m * 16; float sq = 0.f;
; #pragma unroll
;                 for (int bj = 0; bj < 2; ++bj) {
;                     const size_t off = (size_t)row * D + col0 + bj * 32;
;                     const u32x4 xw = *(const u32x4*)(xin + off);
;                     const f32x4 v0 = acc[ai][bj][m][0] + (f32x4){bf_lo(xw.x), bf_hi(xw.x), bf_lo(xw.y), bf_hi(xw.y)}, v1 = acc[ai][bj][m][1] + (f32x4){bf_lo(xw.z), bf_hi(xw.z), bf_lo(xw.w), bf_hi(xw.w)};
;                     *(u32x4*)(xb + off) = pack8(v0, v1);
;                     sq += (v0[0] * v0[0] + v0[1] * v0[1]) + (v0[2] * v0[2] + v0[3] * v0[3]) + (v1[0] * v1[0] + v1[1] * v1[1]) + (v1[2] * v1[2] + v1[3] * v1[3]);
;                 }
.LBB0_951:
	s_waitcnt vmcnt(15)
	v_lshlrev_b32_e32 v246, 16, v174
	v_and_b32_e32 v247, 0xffff0000, v174
	v_lshlrev_b32_e32 v248, 16, v175
	v_and_b32_e32 v249, 0xffff0000, v175
	v_pk_add_f32 v[126:127], v[126:127], v[246:247]
	v_pk_add_f32 v[128:129], v[128:129], v[248:249]
	v_lshlrev_b32_e32 v246, 16, v176
	v_and_b32_e32 v247, 0xffff0000, v176
	v_lshlrev_b32_e32 v248, 16, v177
	v_and_b32_e32 v249, 0xffff0000, v177
	v_pk_add_f32 v[122:123], v[122:123], v[246:247]
	v_pk_add_f32 v[124:125], v[124:125], v[248:249]
	v_cvt_pk_bf16_f32 v174, v126, v127
	v_cvt_pk_bf16_f32 v175, v128, v129
	v_cvt_pk_bf16_f32 v176, v122, v123
	v_cvt_pk_bf16_f32 v177, v124, v125
	global_store_dwordx4 v150, v[174:177], s[30:31]
	v_pk_mul_f32 v[250:251], v[126:127], v[126:127]
	v_pk_fma_f32 v[250:251], v[128:129], v[128:129], v[250:251]
	v_pk_fma_f32 v[250:251], v[122:123], v[122:123], v[250:251]
	v_pk_fma_f32 v[250:251], v[124:125], v[124:125], v[250:251]
	s_waitcnt vmcnt(15)
	v_lshlrev_b32_e32 v246, 16, v178
	v_and_b32_e32 v247, 0xffff0000, v178
	v_lshlrev_b32_e32 v248, 16, v179
	v_and_b32_e32 v249, 0xffff0000, v179
	v_pk_add_f32 v[118:119], v[118:119], v[246:247]
	v_pk_add_f32 v[120:121], v[120:121], v[248:249]
	v_lshlrev_b32_e32 v246, 16, v180
	v_and_b32_e32 v247, 0xffff0000, v180
	v_lshlrev_b32_e32 v248, 16, v181
	v_and_b32_e32 v249, 0xffff0000, v181
	v_pk_add_f32 v[114:115], v[114:115], v[246:247]
	v_pk_add_f32 v[116:117], v[116:117], v[248:249]
	v_cvt_pk_bf16_f32 v178, v118, v119
	v_cvt_pk_bf16_f32 v179, v120, v121
	v_cvt_pk_bf16_f32 v180, v114, v115
	v_cvt_pk_bf16_f32 v181, v116, v117
	global_store_dwordx4 v150, v[178:181], s[30:31] offset:64
	v_pk_fma_f32 v[250:251], v[118:119], v[118:119], v[250:251]
	v_pk_fma_f32 v[250:251], v[120:121], v[120:121], v[250:251]
	v_pk_fma_f32 v[250:251], v[114:115], v[114:115], v[250:251]
	v_pk_fma_f32 v[250:251], v[116:117], v[116:117], v[250:251]
	v_add_f32_e32 v140, v250, v251
	s_waitcnt vmcnt(15)
	v_lshlrev_b32_e32 v246, 16, v182
	v_and_b32_e32 v247, 0xffff0000, v182
	v_lshlrev_b32_e32 v248, 16, v183
	v_and_b32_e32 v249, 0xffff0000, v183
	v_pk_add_f32 v[110:111], v[110:111], v[246:247]
	v_pk_add_f32 v[112:113], v[112:113], v[248:249]
	v_lshlrev_b32_e32 v246, 16, v184
	v_and_b32_e32 v247, 0xffff0000, v184
	v_lshlrev_b32_e32 v248, 16, v185
	v_and_b32_e32 v249, 0xffff0000, v185
	v_pk_add_f32 v[106:107], v[106:107], v[246:247]
	v_pk_add_f32 v[108:109], v[108:109], v[248:249]
	v_cvt_pk_bf16_f32 v182, v110, v111
	v_cvt_pk_bf16_f32 v183, v112, v113
	v_cvt_pk_bf16_f32 v184, v106, v107
	v_cvt_pk_bf16_f32 v185, v108, v109
	global_store_dwordx4 v151, v[182:185], s[30:31]
	v_pk_mul_f32 v[250:251], v[110:111], v[110:111]
	v_pk_fma_f32 v[250:251], v[112:113], v[112:113], v[250:251]
	v_pk_fma_f32 v[250:251], v[106:107], v[106:107], v[250:251]
	v_pk_fma_f32 v[250:251], v[108:109], v[108:109], v[250:251]
	s_waitcnt vmcnt(15)
	v_lshlrev_b32_e32 v246, 16, v186
	v_and_b32_e32 v247, 0xffff0000, v186
	v_lshlrev_b32_e32 v248, 16, v187
	v_and_b32_e32 v249, 0xffff0000, v187
	v_pk_add_f32 v[102:103], v[102:103], v[246:247]
	v_pk_add_f32 v[104:105], v[104:105], v[248:249]
	v_lshlrev_b32_e32 v246, 16, v188
	v_and_b32_e32 v247, 0xffff0000, v188
	v_lshlrev_b32_e32 v248, 16, v189
	v_and_b32_e32 v249, 0xffff0000, v189
	v_pk_add_f32 v[98:99], v[98:99], v[246:247]
	v_pk_add_f32 v[100:101], v[100:101], v[248:249]
	v_cvt_pk_bf16_f32 v186, v102, v103
	v_cvt_pk_bf16_f32 v187, v104, v105
	v_cvt_pk_bf16_f32 v188, v98, v99
	v_cvt_pk_bf16_f32 v189, v100, v101
	global_store_dwordx4 v151, v[186:189], s[30:31] offset:64
	v_pk_fma_f32 v[250:251], v[102:103], v[102:103], v[250:251]
	v_pk_fma_f32 v[250:251], v[104:105], v[104:105], v[250:251]
	v_pk_fma_f32 v[250:251], v[98:99], v[98:99], v[250:251]
	v_pk_fma_f32 v[250:251], v[100:101], v[100:101], v[250:251]
	v_add_f32_e32 v141, v250, v251
	s_waitcnt vmcnt(15)
	v_lshlrev_b32_e32 v246, 16, v190
	v_and_b32_e32 v247, 0xffff0000, v190
	v_lshlrev_b32_e32 v248, 16, v191
	v_and_b32_e32 v249, 0xffff0000, v191
	v_pk_add_f32 v[94:95], v[94:95], v[246:247]
	v_pk_add_f32 v[96:97], v[96:97], v[248:249]
	v_lshlrev_b32_e32 v246, 16, v192
	v_and_b32_e32 v247, 0xffff0000, v192
	v_lshlrev_b32_e32 v248, 16, v193
	v_and_b32_e32 v249, 0xffff0000, v193
	v_pk_add_f32 v[90:91], v[90:91], v[246:247]
	v_pk_add_f32 v[92:93], v[92:93], v[248:249]
	v_cvt_pk_bf16_f32 v190, v94, v95
	v_cvt_pk_bf16_f32 v191, v96, v97
	v_cvt_pk_bf16_f32 v192, v90, v91
	v_cvt_pk_bf16_f32 v193, v92, v93
	global_store_dwordx4 v152, v[190:193], s[30:31]
	v_pk_mul_f32 v[250:251], v[94:95], v[94:95]
	v_pk_fma_f32 v[250:251], v[96:97], v[96:97], v[250:251]
	v_pk_fma_f32 v[250:251], v[90:91], v[90:91], v[250:251]
	v_pk_fma_f32 v[250:251], v[92:93], v[92:93], v[250:251]
	s_waitcnt vmcnt(15)
	v_lshlrev_b32_e32 v246, 16, v194
	v_and_b32_e32 v247, 0xffff0000, v194
	v_lshlrev_b32_e32 v248, 16, v195
	v_and_b32_e32 v249, 0xffff0000, v195
	v_pk_add_f32 v[86:87], v[86:87], v[246:247]
	v_pk_add_f32 v[88:89], v[88:89], v[248:249]
	v_lshlrev_b32_e32 v246, 16, v196
	v_and_b32_e32 v247, 0xffff0000, v196
	v_lshlrev_b32_e32 v248, 16, v197
	v_and_b32_e32 v249, 0xffff0000, v197
	v_pk_add_f32 v[82:83], v[82:83], v[246:247]
	v_pk_add_f32 v[84:85], v[84:85], v[248:249]
	v_cvt_pk_bf16_f32 v194, v86, v87
	v_cvt_pk_bf16_f32 v195, v88, v89
	v_cvt_pk_bf16_f32 v196, v82, v83
	v_cvt_pk_bf16_f32 v197, v84, v85
	global_store_dwordx4 v152, v[194:197], s[30:31] offset:64
	v_pk_fma_f32 v[250:251], v[86:87], v[86:87], v[250:251]
	v_pk_fma_f32 v[250:251], v[88:89], v[88:89], v[250:251]
	v_pk_fma_f32 v[250:251], v[82:83], v[82:83], v[250:251]
	v_pk_fma_f32 v[250:251], v[84:85], v[84:85], v[250:251]
	v_add_f32_e32 v142, v250, v251
	s_waitcnt vmcnt(15)
; __device__ __forceinline__ float bf_lo(unsigned w) { return __uint_as_float(w << 16); }
; __device__ __forceinline__ float bf_hi(unsigned w) { return __uint_as_float(w & 0xffff0000u); }
; __device__ __forceinline__ u32x4 pack8(f32x4 a, f32x4 b) { u32x4 w; w.x = cvt_pk_bf16(a[0], a[1]); w.y = cvt_pk_bf16(a[2], a[3]); w.z = cvt_pk_bf16(b[0], b[1]); w.w = cvt_pk_bf16(b[2], b[3]); return w; }
;     __device__ __forceinline__ void operator()(f32x4 (&acc)[2][2][4][2], const Unit& u, int wr, int wc, int fr, int fq) const {
;     ...
;                 const int row = row0 + ai * HALF + m * 16; float sq = 0.f;
; #pragma unroll
;                 for (int bj = 0; bj < 2; ++bj) {
;                     const size_t off = (size_t)row * D + col0 + bj * 32;
;                     const u32x4 xw = *(const u32x4*)(xin + off);
;                     const f32x4 v0 = acc[ai][bj][m][0] + (f32x4){bf_lo(xw.x), bf_hi(xw.x), bf_lo(xw.y), bf_hi(xw.y)}, v1 = acc[ai][bj][m][1] + (f32x4){bf_lo(xw.z), bf_hi(xw.z), bf_lo(xw.w), bf_hi(xw.w)};
;                     *(u32x4*)(xb + off) = pack8(v0, v1);
;                     sq += (v0[0] * v0[0] + v0[1] * v0[1]) + (v0[2] * v0[2] + v0[3] * v0[3]) + (v1[0] * v1[0] + v1[1] * v1[1]) + (v1[2] * v1[2] + v1[3] * v1[3]);
;                 }
	v_lshlrev_b32_e32 v246, 16, v198
	v_and_b32_e32 v247, 0xffff0000, v198
	v_lshlrev_b32_e32 v248, 16, v199
	v_and_b32_e32 v249, 0xffff0000, v199
	v_pk_add_f32 v[78:79], v[78:79], v[246:247]
	v_pk_add_f32 v[80:81], v[80:81], v[248:249]
	v_lshlrev_b32_e32 v246, 16, v200
	v_and_b32_e32 v247, 0xffff0000, v200
	v_lshlrev_b32_e32 v248, 16, v201
	v_and_b32_e32 v249, 0xffff0000, v201
	v_pk_add_f32 v[74:75], v[74:75], v[246:247]
	v_pk_add_f32 v[76:77], v[76:77], v[248:249]
	v_cvt_pk_bf16_f32 v198, v78, v79
	v_cvt_pk_bf16_f32 v199, v80, v81
	v_cvt_pk_bf16_f32 v200, v74, v75
	v_cvt_pk_bf16_f32 v201, v76, v77
	global_store_dwordx4 v153, v[198:201], s[30:31]
	v_pk_mul_f32 v[250:251], v[78:79], v[78:79]
	v_pk_fma_f32 v[250:251], v[80:81], v[80:81], v[250:251]
	v_pk_fma_f32 v[250:251], v[74:75], v[74:75], v[250:251]
	v_pk_fma_f32 v[250:251], v[76:77], v[76:77], v[250:251]
	s_waitcnt vmcnt(15)
	v_lshlrev_b32_e32 v246, 16, v202
	v_and_b32_e32 v247, 0xffff0000, v202
	v_lshlrev_b32_e32 v248, 16, v203
	v_and_b32_e32 v249, 0xffff0000, v203
	v_pk_add_f32 v[70:71], v[70:71], v[246:247]
	v_pk_add_f32 v[72:73], v[72:73], v[248:249]
	v_lshlrev_b32_e32 v246, 16, v204
	v_and_b32_e32 v247, 0xffff0000, v204
	v_lshlrev_b32_e32 v248, 16, v205
	v_and_b32_e32 v249, 0xffff0000, v205
	v_pk_add_f32 v[66:67], v[66:67], v[246:247]
	v_pk_add_f32 v[68:69], v[68:69], v[248:249]
	v_cvt_pk_bf16_f32 v202, v70, v71
	v_cvt_pk_bf16_f32 v203, v72, v73
	v_cvt_pk_bf16_f32 v204, v66, v67
	v_cvt_pk_bf16_f32 v205, v68, v69
	global_store_dwordx4 v153, v[202:205], s[30:31] offset:64
	v_pk_fma_f32 v[250:251], v[70:71], v[70:71], v[250:251]
	v_pk_fma_f32 v[250:251], v[72:73], v[72:73], v[250:251]
	v_pk_fma_f32 v[250:251], v[66:67], v[66:67], v[250:251]
	v_pk_fma_f32 v[250:251], v[68:69], v[68:69], v[250:251]
	v_add_f32_e32 v143, v250, v251
	s_waitcnt vmcnt(15)
	v_lshlrev_b32_e32 v246, 16, v206
	v_and_b32_e32 v247, 0xffff0000, v206
	v_lshlrev_b32_e32 v248, 16, v207
	v_and_b32_e32 v249, 0xffff0000, v207
	v_pk_add_f32 v[62:63], v[62:63], v[246:247]
	v_pk_add_f32 v[64:65], v[64:65], v[248:249]
	v_lshlrev_b32_e32 v246, 16, v208
	v_and_b32_e32 v247, 0xffff0000, v208
	v_lshlrev_b32_e32 v248, 16, v209
	v_and_b32_e32 v249, 0xffff0000, v209
	v_pk_add_f32 v[58:59], v[58:59], v[246:247]
	v_pk_add_f32 v[60:61], v[60:61], v[248:249]
	v_cvt_pk_bf16_f32 v206, v62, v63
	v_cvt_pk_bf16_f32 v207, v64, v65
	v_cvt_pk_bf16_f32 v208, v58, v59
	v_cvt_pk_bf16_f32 v209, v60, v61
	global_store_dwordx4 v154, v[206:209], s[30:31]
	v_pk_mul_f32 v[250:251], v[62:63], v[62:63]
	v_pk_fma_f32 v[250:251], v[64:65], v[64:65], v[250:251]
	v_pk_fma_f32 v[250:251], v[58:59], v[58:59], v[250:251]
	v_pk_fma_f32 v[250:251], v[60:61], v[60:61], v[250:251]
	s_waitcnt vmcnt(15)
	v_lshlrev_b32_e32 v246, 16, v210
	v_and_b32_e32 v247, 0xffff0000, v210
	v_lshlrev_b32_e32 v248, 16, v211
	v_and_b32_e32 v249, 0xffff0000, v211
	v_pk_add_f32 v[54:55], v[54:55], v[246:247]
	v_pk_add_f32 v[56:57], v[56:57], v[248:249]
	v_lshlrev_b32_e32 v246, 16, v212
	v_and_b32_e32 v247, 0xffff0000, v212
	v_lshlrev_b32_e32 v248, 16, v213
	v_and_b32_e32 v249, 0xffff0000, v213
	v_pk_add_f32 v[50:51], v[50:51], v[246:247]
	v_pk_add_f32 v[52:53], v[52:53], v[248:249]
	v_cvt_pk_bf16_f32 v210, v54, v55
	v_cvt_pk_bf16_f32 v211, v56, v57
	v_cvt_pk_bf16_f32 v212, v50, v51
	v_cvt_pk_bf16_f32 v213, v52, v53
	global_store_dwordx4 v154, v[210:213], s[30:31] offset:64
	v_pk_fma_f32 v[250:251], v[54:55], v[54:55], v[250:251]
	v_pk_fma_f32 v[250:251], v[56:57], v[56:57], v[250:251]
	v_pk_fma_f32 v[250:251], v[50:51], v[50:51], v[250:251]
	v_pk_fma_f32 v[250:251], v[52:53], v[52:53], v[250:251]
	v_add_f32_e32 v144, v250, v251
	s_waitcnt vmcnt(15)
	v_lshlrev_b32_e32 v246, 16, v214
	v_and_b32_e32 v247, 0xffff0000, v214
	v_lshlrev_b32_e32 v248, 16, v215
	v_and_b32_e32 v249, 0xffff0000, v215
	v_pk_add_f32 v[46:47], v[46:47], v[246:247]
	v_pk_add_f32 v[48:49], v[48:49], v[248:249]
	v_lshlrev_b32_e32 v246, 16, v216
	v_and_b32_e32 v247, 0xffff0000, v216
	v_lshlrev_b32_e32 v248, 16, v217
	v_and_b32_e32 v249, 0xffff0000, v217
	v_pk_add_f32 v[42:43], v[42:43], v[246:247]
	v_pk_add_f32 v[44:45], v[44:45], v[248:249]
	v_cvt_pk_bf16_f32 v214, v46, v47
	v_cvt_pk_bf16_f32 v215, v48, v49
	v_cvt_pk_bf16_f32 v216, v42, v43
	v_cvt_pk_bf16_f32 v217, v44, v45
	global_store_dwordx4 v155, v[214:217], s[30:31]
	v_pk_mul_f32 v[250:251], v[46:47], v[46:47]
	v_pk_fma_f32 v[250:251], v[48:49], v[48:49], v[250:251]
	v_pk_fma_f32 v[250:251], v[42:43], v[42:43], v[250:251]
	v_pk_fma_f32 v[250:251], v[44:45], v[44:45], v[250:251]
	s_waitcnt vmcnt(15)
	v_lshlrev_b32_e32 v246, 16, v218
	v_and_b32_e32 v247, 0xffff0000, v218
	v_lshlrev_b32_e32 v248, 16, v219
	v_and_b32_e32 v249, 0xffff0000, v219
	v_pk_add_f32 v[38:39], v[38:39], v[246:247]
	v_pk_add_f32 v[40:41], v[40:41], v[248:249]
	v_lshlrev_b32_e32 v246, 16, v220
	v_and_b32_e32 v247, 0xffff0000, v220
	v_lshlrev_b32_e32 v248, 16, v221
	v_and_b32_e32 v249, 0xffff0000, v221
	v_pk_add_f32 v[34:35], v[34:35], v[246:247]
	v_pk_add_f32 v[36:37], v[36:37], v[248:249]
	v_cvt_pk_bf16_f32 v218, v38, v39
	v_cvt_pk_bf16_f32 v219, v40, v41
	v_cvt_pk_bf16_f32 v220, v34, v35
	v_cvt_pk_bf16_f32 v221, v36, v37
	global_store_dwordx4 v155, v[218:221], s[30:31] offset:64
	v_pk_fma_f32 v[250:251], v[38:39], v[38:39], v[250:251]
	v_pk_fma_f32 v[250:251], v[40:41], v[40:41], v[250:251]
	v_pk_fma_f32 v[250:251], v[34:35], v[34:35], v[250:251]
	v_pk_fma_f32 v[250:251], v[36:37], v[36:37], v[250:251]
	v_add_f32_e32 v145, v250, v251
	s_waitcnt vmcnt(15)
; __device__ __forceinline__ float bf_lo(unsigned w) { return __uint_as_float(w << 16); }
; __device__ __forceinline__ float bf_hi(unsigned w) { return __uint_as_float(w & 0xffff0000u); }
; __device__ __forceinline__ u32x4 pack8(f32x4 a, f32x4 b) { u32x4 w; w.x = cvt_pk_bf16(a[0], a[1]); w.y = cvt_pk_bf16(a[2], a[3]); w.z = cvt_pk_bf16(b[0], b[1]); w.w = cvt_pk_bf16(b[2], b[3]); return w; }
;     __device__ __forceinline__ void operator()(f32x4 (&acc)[2][2][4][2], const Unit& u, int wr, int wc, int fr, int fq) const {
;     ...
;                     const f32x4 v0 = acc[ai][bj][m][0] + (f32x4){bf_lo(xw.x), bf_hi(xw.x), bf_lo(xw.y), bf_hi(xw.y)}, v1 = acc[ai][bj][m][1] + (f32x4){bf_lo(xw.z), bf_hi(xw.z), bf_lo(xw.w), bf_hi(xw.w)};
;                     *(u32x4*)(xb + off) = pack8(v0, v1);
;                     sq += (v0[0] * v0[0] + v0[1] * v0[1]) + (v0[2] * v0[2] + v0[3] * v0[3]) + (v1[0] * v1[0] + v1[1] * v1[1]) + (v1[2] * v1[2] + v1[3] * v1[3]);
;                 }
;                 sq += __shfl_xor(sq, 16); sq += __shfl_xor(sq, 32);
;                 if (fq == 0) ss[(size_t)row * 32 + u.pn * 4 + wc] = sq;
	v_lshlrev_b32_e32 v246, 16, v222
	v_and_b32_e32 v247, 0xffff0000, v222
	v_lshlrev_b32_e32 v248, 16, v223
	v_and_b32_e32 v249, 0xffff0000, v223
	v_pk_add_f32 v[30:31], v[30:31], v[246:247]
	v_pk_add_f32 v[32:33], v[32:33], v[248:249]
	v_lshlrev_b32_e32 v246, 16, v224
	v_and_b32_e32 v247, 0xffff0000, v224
	v_lshlrev_b32_e32 v248, 16, v225
	v_and_b32_e32 v249, 0xffff0000, v225
	v_pk_add_f32 v[26:27], v[26:27], v[246:247]
	v_pk_add_f32 v[28:29], v[28:29], v[248:249]
	v_cvt_pk_bf16_f32 v222, v30, v31
	v_cvt_pk_bf16_f32 v223, v32, v33
	v_cvt_pk_bf16_f32 v224, v26, v27
	v_cvt_pk_bf16_f32 v225, v28, v29
	global_store_dwordx4 v156, v[222:225], s[30:31]
	v_pk_mul_f32 v[250:251], v[30:31], v[30:31]
	v_pk_fma_f32 v[250:251], v[32:33], v[32:33], v[250:251]
	v_pk_fma_f32 v[250:251], v[26:27], v[26:27], v[250:251]
	v_pk_fma_f32 v[250:251], v[28:29], v[28:29], v[250:251]
	s_waitcnt vmcnt(15)
	v_lshlrev_b32_e32 v246, 16, v226
	v_and_b32_e32 v247, 0xffff0000, v226
	v_lshlrev_b32_e32 v248, 16, v227
	v_and_b32_e32 v249, 0xffff0000, v227
	v_pk_add_f32 v[22:23], v[22:23], v[246:247]
	v_pk_add_f32 v[24:25], v[24:25], v[248:249]
	v_lshlrev_b32_e32 v246, 16, v228
	v_and_b32_e32 v247, 0xffff0000, v228
	v_lshlrev_b32_e32 v248, 16, v229
	v_and_b32_e32 v249, 0xffff0000, v229
	v_pk_add_f32 v[18:19], v[18:19], v[246:247]
	v_pk_add_f32 v[20:21], v[20:21], v[248:249]
	v_cvt_pk_bf16_f32 v226, v22, v23
	v_cvt_pk_bf16_f32 v227, v24, v25
	v_cvt_pk_bf16_f32 v228, v18, v19
	v_cvt_pk_bf16_f32 v229, v20, v21
	global_store_dwordx4 v156, v[226:229], s[30:31] offset:64
	v_pk_fma_f32 v[250:251], v[22:23], v[22:23], v[250:251]
	v_pk_fma_f32 v[250:251], v[24:25], v[24:25], v[250:251]
	v_pk_fma_f32 v[250:251], v[18:19], v[18:19], v[250:251]
	v_pk_fma_f32 v[250:251], v[20:21], v[20:21], v[250:251]
	v_add_f32_e32 v162, v250, v251
	s_waitcnt vmcnt(15)
	v_lshlrev_b32_e32 v246, 16, v230
	v_and_b32_e32 v247, 0xffff0000, v230
	v_lshlrev_b32_e32 v248, 16, v231
	v_and_b32_e32 v249, 0xffff0000, v231
	v_pk_add_f32 v[14:15], v[14:15], v[246:247]
	v_pk_add_f32 v[16:17], v[16:17], v[248:249]
	v_lshlrev_b32_e32 v246, 16, v232
	v_and_b32_e32 v247, 0xffff0000, v232
	v_lshlrev_b32_e32 v248, 16, v233
	v_and_b32_e32 v249, 0xffff0000, v233
	v_pk_add_f32 v[10:11], v[10:11], v[246:247]
	v_pk_add_f32 v[12:13], v[12:13], v[248:249]
	v_cvt_pk_bf16_f32 v230, v14, v15
	v_cvt_pk_bf16_f32 v231, v16, v17
	v_cvt_pk_bf16_f32 v232, v10, v11
	v_cvt_pk_bf16_f32 v233, v12, v13
	global_store_dwordx4 v157, v[230:233], s[30:31]
	v_pk_mul_f32 v[250:251], v[14:15], v[14:15]
	v_pk_fma_f32 v[250:251], v[16:17], v[16:17], v[250:251]
	v_pk_fma_f32 v[250:251], v[10:11], v[10:11], v[250:251]
	v_pk_fma_f32 v[250:251], v[12:13], v[12:13], v[250:251]
	s_waitcnt vmcnt(15)
	v_lshlrev_b32_e32 v246, 16, v234
	v_and_b32_e32 v247, 0xffff0000, v234
	v_lshlrev_b32_e32 v248, 16, v235
	v_and_b32_e32 v249, 0xffff0000, v235
	v_pk_add_f32 v[6:7], v[6:7], v[246:247]
	v_pk_add_f32 v[8:9], v[8:9], v[248:249]
	v_lshlrev_b32_e32 v246, 16, v236
	v_and_b32_e32 v247, 0xffff0000, v236
	v_lshlrev_b32_e32 v248, 16, v237
	v_and_b32_e32 v249, 0xffff0000, v237
	v_pk_add_f32 v[2:3], v[2:3], v[246:247]
	v_pk_add_f32 v[4:5], v[4:5], v[248:249]
	v_cvt_pk_bf16_f32 v234, v6, v7
	v_cvt_pk_bf16_f32 v235, v8, v9
	v_cvt_pk_bf16_f32 v236, v2, v3
	v_cvt_pk_bf16_f32 v237, v4, v5
	global_store_dwordx4 v157, v[234:237], s[30:31] offset:64
	v_pk_fma_f32 v[250:251], v[6:7], v[6:7], v[250:251]
	v_pk_fma_f32 v[250:251], v[8:9], v[8:9], v[250:251]
	v_pk_fma_f32 v[250:251], v[2:3], v[2:3], v[250:251]
	v_pk_fma_f32 v[250:251], v[4:5], v[4:5], v[250:251]
	v_add_f32_e32 v238, v250, v251
	ds_bpermute_b32 v174, v239, v140
	ds_bpermute_b32 v175, v239, v141
	ds_bpermute_b32 v176, v239, v142
	ds_bpermute_b32 v177, v239, v143
	ds_bpermute_b32 v178, v239, v144
	ds_bpermute_b32 v179, v239, v145
	ds_bpermute_b32 v180, v239, v162
	ds_bpermute_b32 v181, v239, v238
	s_waitcnt lgkmcnt(0)
	v_add_f32_e32 v140, v140, v174
	v_add_f32_e32 v141, v141, v175
	v_add_f32_e32 v142, v142, v176
	v_add_f32_e32 v143, v143, v177
	v_add_f32_e32 v144, v144, v178
	v_add_f32_e32 v145, v145, v179
	v_add_f32_e32 v162, v162, v180
	v_add_f32_e32 v238, v238, v181
	ds_bpermute_b32 v174, v252, v140
	ds_bpermute_b32 v175, v252, v141
	ds_bpermute_b32 v176, v252, v142
	ds_bpermute_b32 v177, v252, v143
	ds_bpermute_b32 v178, v252, v144
	ds_bpermute_b32 v179, v252, v145
	ds_bpermute_b32 v180, v252, v162
	ds_bpermute_b32 v181, v252, v238
	s_waitcnt lgkmcnt(0)
	v_add_f32_e32 v140, v140, v174
	v_add_f32_e32 v141, v141, v175
	v_add_f32_e32 v142, v142, v176
	v_add_f32_e32 v143, v143, v177
	v_add_f32_e32 v144, v144, v178
	v_add_f32_e32 v145, v145, v179
	v_add_f32_e32 v162, v162, v180
	v_add_f32_e32 v238, v238, v181
	s_and_saveexec_b64 s[12:13], s[36:37]
	global_store_dword v158, v140, s[34:35]
	global_store_dword v158, v141, s[34:35] offset:2048
	global_store_dword v159, v142, s[34:35]
	global_store_dword v159, v143, s[34:35] offset:2048
	global_store_dword v160, v144, s[34:35]
	global_store_dword v160, v145, s[34:35] offset:2048
	global_store_dword v161, v162, s[34:35]
	global_store_dword v161, v238, s[34:35] offset:2048
	s_mov_b32 s65, 0x10000
	s_or_b64 exec, exec, s[12:13]
	s_and_b64 vcc, exec, s[38:39]
	s_mov_b64 s[12:13], -1
	s_cbranch_vccnz .LBB0_942
	s_setprio 0
	s_andn2_b64 vcc, exec, s[18:19]
	s_cbranch_vccnz .LBB0_941
	s_barrier
	s_setprio 1
	s_branch .LBB0_941
